# GEMM K-loops: per-segment s_setprio flips removed, one static s_setprio 1 for waves 4-7 (strategy: static priority raise)
# baseline (speedup 1.0000x reference)
.LBB0_227:
	s_ashr_i32 s43, s42, 31
	s_lshl_b64 s[44:45], s[42:43], 19
	s_add_u32 s44, s3, s44
	s_addc_u32 s45, s22, s45
	s_and_b64 s[46:47], s[36:37], exec
	s_cselect_b32 s43, s45, s71
	s_cselect_b32 s80, s44, s70
	s_ashr_i32 s41, s40, 31
	s_lshl_b64 s[46:47], s[40:41], 19
	s_add_u32 s46, s58, s46
	s_addc_u32 s47, s59, s47
	s_and_b64 s[72:73], s[36:37], exec
	s_cselect_b32 s41, s47, s69
	s_cselect_b32 s81, s46, s68
	s_add_u32 s82, s68, 0x100
	s_addc_u32 s83, s69, 0
	s_add_u32 s68, s70, 0x40080
	v_mov_b32_e32 v0, 0
	s_addc_u32 s69, s71, 0
	s_mov_b32 s86, -2
	v_mov_b32_e32 v1, v0
	v_mov_b32_e32 v2, v0
	v_mov_b32_e32 v3, v0
	v_mov_b32_e32 v4, v0
	v_mov_b32_e32 v5, v0
	v_mov_b32_e32 v6, v0
	v_mov_b32_e32 v7, v0
	v_mov_b32_e32 v16, v0
	v_mov_b32_e32 v17, v0
	v_mov_b32_e32 v18, v0
	v_mov_b32_e32 v19, v0
	v_mov_b32_e32 v20, v0
	v_mov_b32_e32 v21, v0
	v_mov_b32_e32 v22, v0
	v_mov_b32_e32 v23, v0
	v_mov_b32_e32 v32, v0
	v_mov_b32_e32 v33, v0
	v_mov_b32_e32 v34, v0
	v_mov_b32_e32 v35, v0
	v_mov_b32_e32 v36, v0
	v_mov_b32_e32 v37, v0
	v_mov_b32_e32 v38, v0
	v_mov_b32_e32 v39, v0
	v_mov_b32_e32 v48, v0
	v_mov_b32_e32 v49, v0
	v_mov_b32_e32 v50, v0
	v_mov_b32_e32 v51, v0
	v_mov_b32_e32 v52, v0
	v_mov_b32_e32 v53, v0
	v_mov_b32_e32 v54, v0
	v_mov_b32_e32 v55, v0
	v_mov_b32_e32 v8, v0
	v_mov_b32_e32 v9, v0
	v_mov_b32_e32 v10, v0
	v_mov_b32_e32 v11, v0
	v_mov_b32_e32 v12, v0
	v_mov_b32_e32 v13, v0
	v_mov_b32_e32 v14, v0
	v_mov_b32_e32 v15, v0
	v_mov_b32_e32 v24, v0
	v_mov_b32_e32 v25, v0
	v_mov_b32_e32 v26, v0
	v_mov_b32_e32 v27, v0
	v_mov_b32_e32 v28, v0
	v_mov_b32_e32 v29, v0
	v_mov_b32_e32 v30, v0
	v_mov_b32_e32 v31, v0
	v_mov_b32_e32 v40, v0
	v_mov_b32_e32 v41, v0
	v_mov_b32_e32 v42, v0
	v_mov_b32_e32 v43, v0
	v_mov_b32_e32 v44, v0
	v_mov_b32_e32 v45, v0
	v_mov_b32_e32 v46, v0
	v_mov_b32_e32 v47, v0
	v_mov_b32_e32 v56, v0
	v_mov_b32_e32 v57, v0
	v_mov_b32_e32 v58, v0
	v_mov_b32_e32 v59, v0
	v_mov_b32_e32 v60, v0
	v_mov_b32_e32 v61, v0
	v_mov_b32_e32 v62, v0
	v_mov_b32_e32 v63, v0
	v_mov_b32_e32 v64, v0
	v_mov_b32_e32 v65, v0
	v_mov_b32_e32 v66, v0
	v_mov_b32_e32 v67, v0
	v_mov_b32_e32 v68, v0
	v_mov_b32_e32 v69, v0
	v_mov_b32_e32 v70, v0
	v_mov_b32_e32 v71, v0
	v_mov_b32_e32 v80, v0
	v_mov_b32_e32 v81, v0
	v_mov_b32_e32 v82, v0
	v_mov_b32_e32 v83, v0
	v_mov_b32_e32 v84, v0
	v_mov_b32_e32 v85, v0
	v_mov_b32_e32 v86, v0
	v_mov_b32_e32 v87, v0
	v_mov_b32_e32 v96, v0
	v_mov_b32_e32 v97, v0
	v_mov_b32_e32 v98, v0
	v_mov_b32_e32 v99, v0
	v_mov_b32_e32 v100, v0
	v_mov_b32_e32 v101, v0
	v_mov_b32_e32 v102, v0
	v_mov_b32_e32 v103, v0
	v_mov_b32_e32 v112, v0
	v_mov_b32_e32 v113, v0
	v_mov_b32_e32 v114, v0
	v_mov_b32_e32 v115, v0
	v_mov_b32_e32 v116, v0
	v_mov_b32_e32 v117, v0
	v_mov_b32_e32 v118, v0
	v_mov_b32_e32 v119, v0
	v_mov_b32_e32 v72, v0
	v_mov_b32_e32 v73, v0
	v_mov_b32_e32 v74, v0
	v_mov_b32_e32 v75, v0
	v_mov_b32_e32 v76, v0
	v_mov_b32_e32 v77, v0
	v_mov_b32_e32 v78, v0
	v_mov_b32_e32 v79, v0
	v_mov_b32_e32 v88, v0
	v_mov_b32_e32 v89, v0
	v_mov_b32_e32 v90, v0
	v_mov_b32_e32 v91, v0
	v_mov_b32_e32 v92, v0
	v_mov_b32_e32 v93, v0
	v_mov_b32_e32 v94, v0
	v_mov_b32_e32 v95, v0
	v_mov_b32_e32 v104, v0
	v_mov_b32_e32 v105, v0
	v_mov_b32_e32 v106, v0
	v_mov_b32_e32 v107, v0
	v_mov_b32_e32 v108, v0
	v_mov_b32_e32 v109, v0
	v_mov_b32_e32 v110, v0
	v_mov_b32_e32 v111, v0
	v_mov_b32_e32 v120, v0
	v_mov_b32_e32 v121, v0
	v_mov_b32_e32 v122, v0
	v_mov_b32_e32 v123, v0
	v_mov_b32_e32 v124, v0
	v_mov_b32_e32 v125, v0
	v_mov_b32_e32 v126, v0
	v_mov_b32_e32 v127, v0
	v_readfirstlane_b32 s70, v226
	s_nop 3
	s_bitcmp1_b32 s70, 8
	s_cbranch_scc0 .Lpr_228
	s_setprio 1
.Lpr_228:
.LBB0_228:
	s_add_u32 s70, s68, 0xfffc0080
	s_addc_u32 s71, s69, -1
	s_add_i32 s87, 0, 0x10000
	s_cmp_eq_u32 s86, 12
	s_cselect_b32 s73, s43, s71
	s_cselect_b32 s72, s80, s70
	v_add_u32_e32 v138, s87, v141
	s_cselect_b32 s71, s41, s83
	s_cselect_b32 s70, s81, s82
	s_add_i32 s96, 0, 0x14000
	ds_read_b128 v[144:147], v138
	ds_read_b128 v[148:151], v138 offset:1024
	ds_read_b128 v[152:155], v138 offset:2048
	ds_read_b128 v[156:159], v138 offset:3072
	v_add_u32_e32 v138, s96, v141
	ds_read_b128 v[160:163], v138
	ds_read_b128 v[164:167], v138 offset:1024
	ds_read_b128 v[168:171], v138 offset:2048
	ds_read_b128 v[172:175], v138 offset:3072
	v_lshl_add_u64 v[138:139], s[68:69], 0, v[136:137]
	s_add_i32 m0, s61, 0xc000
	ds_read_b128 v[190:193], v143
	ds_read_b128 v[194:197], v143 offset:1024
	ds_read_b128 v[198:201], v143 offset:2048
	ds_read_b128 v[202:205], v143 offset:3072
	ds_read_b128 v[206:209], v143 offset:4096
	ds_read_b128 v[210:213], v143 offset:5120
	ds_read_b128 v[214:217], v143 offset:6144
	ds_read_b128 v[218:221], v143 offset:7168
	global_load_lds_dwordx4 v[138:139], off
	v_lshl_add_u64 v[138:139], s[68:69], 0, v[134:135]
	s_add_i32 m0, s61, 0xe000
	s_nop 0
	global_load_lds_dwordx4 v[138:139], off
	s_waitcnt vmcnt(8)
	s_waitcnt lgkmcnt(0)
	s_barrier
	s_waitcnt lgkmcnt(0)
	v_mfma_f32_16x16x32_bf16 v[124:127], v[144:147], v[190:193], v[124:127]
	v_mfma_f32_16x16x32_bf16 v[120:123], v[152:155], v[190:193], v[120:123]
	v_mfma_f32_16x16x32_bf16 v[108:111], v[144:147], v[198:201], v[108:111]
	v_mfma_f32_16x16x32_bf16 v[104:107], v[152:155], v[198:201], v[104:107]
	v_mfma_f32_16x16x32_bf16 v[92:95], v[144:147], v[206:209], v[92:95]
	v_mfma_f32_16x16x32_bf16 v[88:91], v[152:155], v[206:209], v[88:91]
	v_mfma_f32_16x16x32_bf16 v[76:79], v[144:147], v[214:217], v[76:79]
	v_mfma_f32_16x16x32_bf16 v[72:75], v[152:155], v[214:217], v[72:75]
	v_mfma_f32_16x16x32_bf16 v[124:127], v[148:151], v[194:197], v[124:127]
	v_mfma_f32_16x16x32_bf16 v[120:123], v[156:159], v[194:197], v[120:123]
	v_mfma_f32_16x16x32_bf16 v[108:111], v[148:151], v[202:205], v[108:111]
	v_mfma_f32_16x16x32_bf16 v[104:107], v[156:159], v[202:205], v[104:107]
	v_mfma_f32_16x16x32_bf16 v[92:95], v[148:151], v[210:213], v[92:95]
	v_mfma_f32_16x16x32_bf16 v[88:91], v[156:159], v[210:213], v[88:91]
	v_mfma_f32_16x16x32_bf16 v[76:79], v[148:151], v[218:221], v[76:79]
	v_mfma_f32_16x16x32_bf16 v[72:75], v[156:159], v[218:221], v[72:75]
	v_mfma_f32_16x16x32_bf16 v[116:119], v[160:163], v[190:193], v[116:119]
	v_mfma_f32_16x16x32_bf16 v[112:115], v[168:171], v[190:193], v[112:115]
	v_mfma_f32_16x16x32_bf16 v[100:103], v[160:163], v[198:201], v[100:103]
	v_mfma_f32_16x16x32_bf16 v[96:99], v[168:171], v[198:201], v[96:99]
	v_mfma_f32_16x16x32_bf16 v[84:87], v[160:163], v[206:209], v[84:87]
	v_mfma_f32_16x16x32_bf16 v[80:83], v[168:171], v[206:209], v[80:83]
	v_mfma_f32_16x16x32_bf16 v[68:71], v[160:163], v[214:217], v[68:71]
	v_mfma_f32_16x16x32_bf16 v[64:67], v[168:171], v[214:217], v[64:67]
	v_mfma_f32_16x16x32_bf16 v[116:119], v[164:167], v[194:197], v[116:119]
	v_mfma_f32_16x16x32_bf16 v[112:115], v[172:175], v[194:197], v[112:115]
	v_mfma_f32_16x16x32_bf16 v[100:103], v[164:167], v[202:205], v[100:103]
	v_mfma_f32_16x16x32_bf16 v[96:99], v[172:175], v[202:205], v[96:99]
	v_mfma_f32_16x16x32_bf16 v[84:87], v[164:167], v[210:213], v[84:87]
	v_mfma_f32_16x16x32_bf16 v[80:83], v[172:175], v[210:213], v[80:83]
	v_mfma_f32_16x16x32_bf16 v[68:71], v[164:167], v[218:221], v[68:71]
	v_mfma_f32_16x16x32_bf16 v[64:67], v[172:175], v[218:221], v[64:67]
	s_barrier
	s_add_i32 s87, s87, s60
	v_lshl_add_u64 v[138:139], s[70:71], 0, v[176:177]
	s_mov_b32 m0, s87
	ds_read_b128 v[190:193], v143 offset:16384
	ds_read_b128 v[194:197], v143 offset:17408
	ds_read_b128 v[198:201], v143 offset:18432
	ds_read_b128 v[202:205], v143 offset:19456
	ds_read_b128 v[206:209], v143 offset:20480
	ds_read_b128 v[210:213], v143 offset:21504
	ds_read_b128 v[214:217], v143 offset:22528
	ds_read_b128 v[218:221], v143 offset:23552
	global_load_lds_dwordx4 v[138:139], off
	s_add_i32 m0, s87, 0x2000
	s_add_u32 s90, s70, 0x40000
	v_lshl_add_u64 v[222:223], s[70:71], 0, v[128:129]
	s_addc_u32 s91, s71, 0
	s_add_i32 s87, s96, s60
	global_load_lds_dwordx4 v[222:223], off
	v_lshl_add_u64 v[224:225], s[90:91], 0, v[176:177]
	s_mov_b32 m0, s87
	v_lshl_add_u64 v[234:235], s[72:73], 0, v[130:131]
	global_load_lds_dwordx4 v[224:225], off
	v_lshl_add_u64 v[224:225], s[90:91], 0, v[128:129]
	s_add_i32 m0, s87, 0x2000
	s_nop 0
	global_load_lds_dwordx4 v[224:225], off
	v_lshl_add_u64 v[224:225], s[72:73], 0, v[132:133]
	s_mov_b32 m0, s61
	s_nop 0
	global_load_lds_dwordx4 v[224:225], off
	s_mov_b32 m0, s62
	s_nop 0
	global_load_lds_dwordx4 v[234:235], off
	s_waitcnt vmcnt(8)
	s_waitcnt lgkmcnt(0)
	s_barrier
	s_waitcnt lgkmcnt(0)
	v_mfma_f32_16x16x32_bf16 v[60:63], v[144:147], v[190:193], v[60:63]
	v_mfma_f32_16x16x32_bf16 v[56:59], v[152:155], v[190:193], v[56:59]
	v_mfma_f32_16x16x32_bf16 v[44:47], v[144:147], v[198:201], v[44:47]
	v_mfma_f32_16x16x32_bf16 v[40:43], v[152:155], v[198:201], v[40:43]
	v_mfma_f32_16x16x32_bf16 v[28:31], v[144:147], v[206:209], v[28:31]
	v_mfma_f32_16x16x32_bf16 v[24:27], v[152:155], v[206:209], v[24:27]
	v_mfma_f32_16x16x32_bf16 v[12:15], v[144:147], v[214:217], v[12:15]
	v_mfma_f32_16x16x32_bf16 v[8:11], v[152:155], v[214:217], v[8:11]
	v_mfma_f32_16x16x32_bf16 v[60:63], v[148:151], v[194:197], v[60:63]
	v_mfma_f32_16x16x32_bf16 v[56:59], v[156:159], v[194:197], v[56:59]
	v_mfma_f32_16x16x32_bf16 v[44:47], v[148:151], v[202:205], v[44:47]
	v_mfma_f32_16x16x32_bf16 v[40:43], v[156:159], v[202:205], v[40:43]
	v_mfma_f32_16x16x32_bf16 v[28:31], v[148:151], v[210:213], v[28:31]
	v_mfma_f32_16x16x32_bf16 v[24:27], v[156:159], v[210:213], v[24:27]
	v_mfma_f32_16x16x32_bf16 v[12:15], v[148:151], v[218:221], v[12:15]
	v_mfma_f32_16x16x32_bf16 v[8:11], v[156:159], v[218:221], v[8:11]
	v_mfma_f32_16x16x32_bf16 v[52:55], v[160:163], v[190:193], v[52:55]
	v_mfma_f32_16x16x32_bf16 v[48:51], v[168:171], v[190:193], v[48:51]
	v_mfma_f32_16x16x32_bf16 v[36:39], v[160:163], v[198:201], v[36:39]
	v_mfma_f32_16x16x32_bf16 v[32:35], v[168:171], v[198:201], v[32:35]
	v_mfma_f32_16x16x32_bf16 v[20:23], v[160:163], v[206:209], v[20:23]
	v_mfma_f32_16x16x32_bf16 v[16:19], v[168:171], v[206:209], v[16:19]
	v_mfma_f32_16x16x32_bf16 v[4:7], v[160:163], v[214:217], v[4:7]
	v_mfma_f32_16x16x32_bf16 v[0:3], v[168:171], v[214:217], v[0:3]
	v_mfma_f32_16x16x32_bf16 v[52:55], v[164:167], v[194:197], v[52:55]
	v_mfma_f32_16x16x32_bf16 v[48:51], v[172:175], v[194:197], v[48:51]
	v_mfma_f32_16x16x32_bf16 v[36:39], v[164:167], v[202:205], v[36:39]
	v_mfma_f32_16x16x32_bf16 v[32:35], v[172:175], v[202:205], v[32:35]
	v_mfma_f32_16x16x32_bf16 v[20:23], v[164:167], v[210:213], v[20:23]
	v_mfma_f32_16x16x32_bf16 v[16:19], v[172:175], v[210:213], v[16:19]
	v_mfma_f32_16x16x32_bf16 v[4:7], v[164:167], v[218:221], v[4:7]
	v_mfma_f32_16x16x32_bf16 v[0:3], v[172:175], v[218:221], v[0:3]
	s_barrier
	s_add_i32 s87, 0, 0x18000
	s_add_i32 s90, 0, 0x1c000
	v_add_u32_e32 v156, s87, v141
	v_add_u32_e32 v172, s90, v141
	ds_read_b128 v[144:147], v156
	ds_read_b128 v[148:151], v156 offset:1024
	ds_read_b128 v[152:155], v156 offset:2048
	ds_read_b128 v[156:159], v156 offset:3072
	ds_read_b128 v[160:163], v172
	ds_read_b128 v[164:167], v172 offset:1024
	ds_read_b128 v[168:171], v172 offset:2048
	ds_read_b128 v[172:175], v172 offset:3072
	s_add_u32 s72, s72, 0x40000
	s_addc_u32 s73, s73, 0
	s_mov_b32 m0, s63
	v_lshl_add_u64 v[236:237], s[72:73], 0, v[132:133]
	ds_read_b128 v[190:193], v143 offset:32768
	ds_read_b128 v[194:197], v143 offset:33792
	ds_read_b128 v[198:201], v143 offset:34816
	ds_read_b128 v[202:205], v143 offset:35840
	ds_read_b128 v[206:209], v143 offset:36864
	ds_read_b128 v[210:213], v143 offset:37888
	ds_read_b128 v[214:217], v143 offset:38912
	ds_read_b128 v[218:221], v143 offset:39936
	global_load_lds_dwordx4 v[236:237], off
	v_lshl_add_u64 v[236:237], s[72:73], 0, v[130:131]
	s_mov_b32 m0, s74
	s_nop 0
	global_load_lds_dwordx4 v[236:237], off
	s_waitcnt vmcnt(8)
	s_waitcnt lgkmcnt(0)
	s_barrier
	s_waitcnt lgkmcnt(0)
	v_mfma_f32_16x16x32_bf16 v[124:127], v[144:147], v[190:193], v[124:127]
	v_mfma_f32_16x16x32_bf16 v[120:123], v[152:155], v[190:193], v[120:123]
	v_mfma_f32_16x16x32_bf16 v[108:111], v[144:147], v[198:201], v[108:111]
	v_mfma_f32_16x16x32_bf16 v[104:107], v[152:155], v[198:201], v[104:107]
	v_mfma_f32_16x16x32_bf16 v[92:95], v[144:147], v[206:209], v[92:95]
	v_mfma_f32_16x16x32_bf16 v[88:91], v[152:155], v[206:209], v[88:91]
	v_mfma_f32_16x16x32_bf16 v[76:79], v[144:147], v[214:217], v[76:79]
	v_mfma_f32_16x16x32_bf16 v[72:75], v[152:155], v[214:217], v[72:75]
	v_mfma_f32_16x16x32_bf16 v[124:127], v[148:151], v[194:197], v[124:127]
	v_mfma_f32_16x16x32_bf16 v[120:123], v[156:159], v[194:197], v[120:123]
	v_mfma_f32_16x16x32_bf16 v[108:111], v[148:151], v[202:205], v[108:111]
	v_mfma_f32_16x16x32_bf16 v[104:107], v[156:159], v[202:205], v[104:107]
	v_mfma_f32_16x16x32_bf16 v[92:95], v[148:151], v[210:213], v[92:95]
	v_mfma_f32_16x16x32_bf16 v[88:91], v[156:159], v[210:213], v[88:91]
	v_mfma_f32_16x16x32_bf16 v[76:79], v[148:151], v[218:221], v[76:79]
	v_mfma_f32_16x16x32_bf16 v[72:75], v[156:159], v[218:221], v[72:75]
	v_mfma_f32_16x16x32_bf16 v[116:119], v[160:163], v[190:193], v[116:119]
	v_mfma_f32_16x16x32_bf16 v[112:115], v[168:171], v[190:193], v[112:115]
	v_mfma_f32_16x16x32_bf16 v[100:103], v[160:163], v[198:201], v[100:103]
	v_mfma_f32_16x16x32_bf16 v[96:99], v[168:171], v[198:201], v[96:99]
	v_mfma_f32_16x16x32_bf16 v[84:87], v[160:163], v[206:209], v[84:87]
	v_mfma_f32_16x16x32_bf16 v[80:83], v[168:171], v[206:209], v[80:83]
	v_mfma_f32_16x16x32_bf16 v[68:71], v[160:163], v[214:217], v[68:71]
	v_mfma_f32_16x16x32_bf16 v[64:67], v[168:171], v[214:217], v[64:67]
	v_mfma_f32_16x16x32_bf16 v[116:119], v[164:167], v[194:197], v[116:119]
	v_mfma_f32_16x16x32_bf16 v[112:115], v[172:175], v[194:197], v[112:115]
	v_mfma_f32_16x16x32_bf16 v[100:103], v[164:167], v[202:205], v[100:103]
	v_mfma_f32_16x16x32_bf16 v[96:99], v[172:175], v[202:205], v[96:99]
	v_mfma_f32_16x16x32_bf16 v[84:87], v[164:167], v[210:213], v[84:87]
	v_mfma_f32_16x16x32_bf16 v[80:83], v[172:175], v[210:213], v[80:83]
	v_mfma_f32_16x16x32_bf16 v[68:71], v[164:167], v[218:221], v[68:71]
	v_mfma_f32_16x16x32_bf16 v[64:67], v[172:175], v[218:221], v[64:67]
	s_barrier
	s_add_i32 s72, s87, s60
	v_lshl_add_u64 v[138:139], v[138:139], 0, s[24:25]
	s_mov_b32 m0, s72
	ds_read_b128 v[190:193], v143 offset:49152
	ds_read_b128 v[194:197], v143 offset:50176
	ds_read_b128 v[198:201], v143 offset:51200
	ds_read_b128 v[202:205], v143 offset:52224
	ds_read_b128 v[206:209], v143 offset:53248
	ds_read_b128 v[210:213], v143 offset:54272
	ds_read_b128 v[214:217], v143 offset:55296
	ds_read_b128 v[218:221], v143 offset:56320
	global_load_lds_dwordx4 v[138:139], off
	s_add_i32 m0, s72, 0x2000
	s_add_u32 s70, s70, 0x40080
	v_lshl_add_u64 v[138:139], v[222:223], 0, s[24:25]
	s_addc_u32 s71, s71, 0
	s_add_i32 s72, s90, s60
	global_load_lds_dwordx4 v[138:139], off
	v_lshl_add_u64 v[138:139], s[70:71], 0, v[176:177]
	s_mov_b32 m0, s72
	s_nop 0
	global_load_lds_dwordx4 v[138:139], off
	v_lshl_add_u64 v[138:139], s[70:71], 0, v[128:129]
	s_add_i32 m0, s72, 0x2000
	s_nop 0
	global_load_lds_dwordx4 v[138:139], off
	v_lshl_add_u64 v[138:139], v[224:225], 0, s[24:25]
	s_mov_b32 m0, s75
	s_nop 0
	global_load_lds_dwordx4 v[138:139], off
	v_lshl_add_u64 v[138:139], v[234:235], 0, s[24:25]
	s_mov_b32 m0, s76
	s_nop 0
	global_load_lds_dwordx4 v[138:139], off
	s_waitcnt vmcnt(8)
	s_waitcnt lgkmcnt(0)
	s_barrier
	s_waitcnt lgkmcnt(0)
	v_mfma_f32_16x16x32_bf16 v[60:63], v[144:147], v[190:193], v[60:63]
	v_mfma_f32_16x16x32_bf16 v[56:59], v[152:155], v[190:193], v[56:59]
	v_mfma_f32_16x16x32_bf16 v[44:47], v[144:147], v[198:201], v[44:47]
	v_mfma_f32_16x16x32_bf16 v[40:43], v[152:155], v[198:201], v[40:43]
	v_mfma_f32_16x16x32_bf16 v[28:31], v[144:147], v[206:209], v[28:31]
	v_mfma_f32_16x16x32_bf16 v[24:27], v[152:155], v[206:209], v[24:27]
	v_mfma_f32_16x16x32_bf16 v[12:15], v[144:147], v[214:217], v[12:15]
	v_mfma_f32_16x16x32_bf16 v[8:11], v[152:155], v[214:217], v[8:11]
	v_mfma_f32_16x16x32_bf16 v[60:63], v[148:151], v[194:197], v[60:63]
	v_mfma_f32_16x16x32_bf16 v[56:59], v[156:159], v[194:197], v[56:59]
	v_mfma_f32_16x16x32_bf16 v[44:47], v[148:151], v[202:205], v[44:47]
	v_mfma_f32_16x16x32_bf16 v[40:43], v[156:159], v[202:205], v[40:43]
	v_mfma_f32_16x16x32_bf16 v[28:31], v[148:151], v[210:213], v[28:31]
	v_mfma_f32_16x16x32_bf16 v[24:27], v[156:159], v[210:213], v[24:27]
	v_mfma_f32_16x16x32_bf16 v[12:15], v[148:151], v[218:221], v[12:15]
	v_mfma_f32_16x16x32_bf16 v[8:11], v[156:159], v[218:221], v[8:11]
	v_mfma_f32_16x16x32_bf16 v[52:55], v[160:163], v[190:193], v[52:55]
	v_mfma_f32_16x16x32_bf16 v[48:51], v[168:171], v[190:193], v[48:51]
	v_mfma_f32_16x16x32_bf16 v[36:39], v[160:163], v[198:201], v[36:39]
	v_mfma_f32_16x16x32_bf16 v[32:35], v[168:171], v[198:201], v[32:35]
	v_mfma_f32_16x16x32_bf16 v[20:23], v[160:163], v[206:209], v[20:23]
	v_mfma_f32_16x16x32_bf16 v[16:19], v[168:171], v[206:209], v[16:19]
	v_mfma_f32_16x16x32_bf16 v[4:7], v[160:163], v[214:217], v[4:7]
	v_mfma_f32_16x16x32_bf16 v[0:3], v[168:171], v[214:217], v[0:3]
	v_mfma_f32_16x16x32_bf16 v[52:55], v[164:167], v[194:197], v[52:55]
	v_mfma_f32_16x16x32_bf16 v[48:51], v[172:175], v[194:197], v[48:51]
	v_mfma_f32_16x16x32_bf16 v[36:39], v[164:167], v[202:205], v[36:39]
	v_mfma_f32_16x16x32_bf16 v[32:35], v[172:175], v[202:205], v[32:35]
	v_mfma_f32_16x16x32_bf16 v[20:23], v[164:167], v[210:213], v[20:23]
	v_mfma_f32_16x16x32_bf16 v[16:19], v[172:175], v[210:213], v[16:19]
	v_mfma_f32_16x16x32_bf16 v[4:7], v[164:167], v[218:221], v[4:7]
	v_mfma_f32_16x16x32_bf16 v[0:3], v[172:175], v[218:221], v[0:3]
	s_barrier
	s_add_i32 s86, s86, 2
	s_add_u32 s82, s82, 0x100
	s_addc_u32 s83, s83, 0
	s_add_u32 s68, s68, 0x100
	s_addc_u32 s69, s69, 0
	s_cmp_gt_u32 s86, 13
	s_cbranch_scc0 .LBB0_228
	s_setprio 0
	s_and_b64 vcc, exec, s[38:39]
	s_cbranch_vccz .LBB0_231
	s_barrier

.LBB0_296:
	s_add_u32 s82, s44, 0x100
	v_mov_b32_e32 v0, 0
	s_addc_u32 s83, s45, 0
	s_mov_b32 s86, -2
	v_mov_b32_e32 v1, v0
	v_mov_b32_e32 v2, v0
	v_mov_b32_e32 v3, v0
	v_mov_b32_e32 v4, v0
	v_mov_b32_e32 v5, v0
	v_mov_b32_e32 v6, v0
	v_mov_b32_e32 v7, v0
	v_mov_b32_e32 v12, v0
	v_mov_b32_e32 v13, v0
	v_mov_b32_e32 v14, v0
	v_mov_b32_e32 v15, v0
	v_mov_b32_e32 v20, v0
	v_mov_b32_e32 v21, v0
	v_mov_b32_e32 v22, v0
	v_mov_b32_e32 v23, v0
	v_mov_b32_e32 v28, v0
	v_mov_b32_e32 v29, v0
	v_mov_b32_e32 v30, v0
	v_mov_b32_e32 v31, v0
	v_mov_b32_e32 v36, v0
	v_mov_b32_e32 v37, v0
	v_mov_b32_e32 v38, v0
	v_mov_b32_e32 v39, v0
	v_mov_b32_e32 v44, v0
	v_mov_b32_e32 v45, v0
	v_mov_b32_e32 v46, v0
	v_mov_b32_e32 v47, v0
	v_mov_b32_e32 v52, v0
	v_mov_b32_e32 v53, v0
	v_mov_b32_e32 v54, v0
	v_mov_b32_e32 v55, v0
	v_mov_b32_e32 v8, v0
	v_mov_b32_e32 v9, v0
	v_mov_b32_e32 v10, v0
	v_mov_b32_e32 v11, v0
	v_mov_b32_e32 v16, v0
	v_mov_b32_e32 v17, v0
	v_mov_b32_e32 v18, v0
	v_mov_b32_e32 v19, v0
	v_mov_b32_e32 v24, v0
	v_mov_b32_e32 v25, v0
	v_mov_b32_e32 v26, v0
	v_mov_b32_e32 v27, v0
	v_mov_b32_e32 v32, v0
	v_mov_b32_e32 v33, v0
	v_mov_b32_e32 v34, v0
	v_mov_b32_e32 v35, v0
	v_mov_b32_e32 v40, v0
	v_mov_b32_e32 v41, v0
	v_mov_b32_e32 v42, v0
	v_mov_b32_e32 v43, v0
	v_mov_b32_e32 v48, v0
	v_mov_b32_e32 v49, v0
	v_mov_b32_e32 v50, v0
	v_mov_b32_e32 v51, v0
	v_mov_b32_e32 v56, v0
	v_mov_b32_e32 v57, v0
	v_mov_b32_e32 v58, v0
	v_mov_b32_e32 v59, v0
	v_mov_b32_e32 v60, v0
	v_mov_b32_e32 v61, v0
	v_mov_b32_e32 v62, v0
	v_mov_b32_e32 v63, v0
	v_mov_b32_e32 v64, v0
	v_mov_b32_e32 v65, v0
	v_mov_b32_e32 v66, v0
	v_mov_b32_e32 v67, v0
	v_mov_b32_e32 v68, v0
	v_mov_b32_e32 v69, v0
	v_mov_b32_e32 v70, v0
	v_mov_b32_e32 v71, v0
	v_mov_b32_e32 v76, v0
	v_mov_b32_e32 v77, v0
	v_mov_b32_e32 v78, v0
	v_mov_b32_e32 v79, v0
	v_mov_b32_e32 v84, v0
	v_mov_b32_e32 v85, v0
	v_mov_b32_e32 v86, v0
	v_mov_b32_e32 v87, v0
	v_mov_b32_e32 v92, v0
	v_mov_b32_e32 v93, v0
	v_mov_b32_e32 v94, v0
	v_mov_b32_e32 v95, v0
	v_mov_b32_e32 v100, v0
	v_mov_b32_e32 v101, v0
	v_mov_b32_e32 v102, v0
	v_mov_b32_e32 v103, v0
	v_mov_b32_e32 v112, v0
	v_mov_b32_e32 v113, v0
	v_mov_b32_e32 v114, v0
	v_mov_b32_e32 v115, v0
	v_mov_b32_e32 v116, v0
	v_mov_b32_e32 v117, v0
	v_mov_b32_e32 v118, v0
	v_mov_b32_e32 v119, v0
	v_mov_b32_e32 v72, v0
	v_mov_b32_e32 v73, v0
	v_mov_b32_e32 v74, v0
	v_mov_b32_e32 v75, v0
	v_mov_b32_e32 v80, v0
	v_mov_b32_e32 v81, v0
	v_mov_b32_e32 v82, v0
	v_mov_b32_e32 v83, v0
	v_mov_b32_e32 v88, v0
	v_mov_b32_e32 v89, v0
	v_mov_b32_e32 v90, v0
	v_mov_b32_e32 v91, v0
	v_mov_b32_e32 v96, v0
	v_mov_b32_e32 v97, v0
	v_mov_b32_e32 v98, v0
	v_mov_b32_e32 v99, v0
	v_mov_b32_e32 v104, v0
	v_mov_b32_e32 v105, v0
	v_mov_b32_e32 v106, v0
	v_mov_b32_e32 v107, v0
	v_mov_b32_e32 v108, v0
	v_mov_b32_e32 v109, v0
	v_mov_b32_e32 v110, v0
	v_mov_b32_e32 v111, v0
	v_mov_b32_e32 v120, v0
	v_mov_b32_e32 v121, v0
	v_mov_b32_e32 v122, v0
	v_mov_b32_e32 v123, v0
	v_mov_b32_e32 v124, v0
	v_mov_b32_e32 v125, v0
	v_mov_b32_e32 v126, v0
	v_mov_b32_e32 v127, v0
	v_readfirstlane_b32 s44, v226
	s_nop 3
	s_bitcmp1_b32 s44, 8
	s_cbranch_scc0 .Lpr_297
	s_setprio 1
.Lpr_297:
.LBB0_297:
	s_add_u32 s44, s42, 0x100
	s_addc_u32 s45, s43, 0
	s_add_i32 s87, 0, 0x10000
	s_cmp_eq_u32 s86, 40
	s_cselect_b32 s69, s1, s45
	s_cselect_b32 s68, s0, s44
	s_cselect_b32 s47, s39, s83
	s_cselect_b32 s46, s38, s82
	s_add_i32 s90, 0, 0x14000
	v_add_u32_e32 v140, s87, v204
	v_add_u32_e32 v166, s90, v204
	ds_read_b128 v[128:131], v140
	ds_read_b128 v[132:135], v140 offset:1024
	ds_read_b128 v[136:139], v140 offset:2048
	ds_read_b128 v[140:143], v140 offset:3072
	ds_read_b128 v[144:147], v166
	ds_read_b128 v[148:151], v166 offset:1024
	ds_read_b128 v[162:165], v166 offset:2048
	ds_read_b128 v[166:169], v166 offset:3072
	v_lshl_add_u64 v[174:175], s[42:43], 0, v[160:161]
	s_add_i32 m0, s22, 0xc000
	ds_read_b128 v[170:173], v205
	ds_read_b128 v[190:193], v205 offset:1024
	ds_read_b128 v[194:197], v205 offset:2048
	ds_read_b128 v[198:201], v205 offset:3072
	ds_read_b128 v[206:209], v205 offset:4096
	ds_read_b128 v[210:213], v205 offset:5120
	ds_read_b128 v[214:217], v205 offset:6144
	ds_read_b128 v[218:221], v205 offset:7168
	global_load_lds_dwordx4 v[174:175], off
	v_lshl_add_u64 v[174:175], s[42:43], 0, v[158:159]
	s_add_i32 m0, s22, 0xe000
	s_nop 0
	global_load_lds_dwordx4 v[174:175], off
	s_waitcnt vmcnt(8)
	s_waitcnt lgkmcnt(0)
	s_barrier
	s_waitcnt lgkmcnt(0)
	v_mfma_f32_16x16x32_bf16 v[124:127], v[128:131], v[170:173], v[124:127]
	v_mfma_f32_16x16x32_bf16 v[120:123], v[136:139], v[170:173], v[120:123]
	v_mfma_f32_16x16x32_bf16 v[108:111], v[128:131], v[194:197], v[108:111]
	v_mfma_f32_16x16x32_bf16 v[104:107], v[136:139], v[194:197], v[104:107]
	v_mfma_f32_16x16x32_bf16 v[96:99], v[128:131], v[206:209], v[96:99]
	v_mfma_f32_16x16x32_bf16 v[88:91], v[136:139], v[206:209], v[88:91]
	v_mfma_f32_16x16x32_bf16 v[80:83], v[128:131], v[214:217], v[80:83]
	v_mfma_f32_16x16x32_bf16 v[72:75], v[136:139], v[214:217], v[72:75]
	v_mfma_f32_16x16x32_bf16 v[124:127], v[132:135], v[190:193], v[124:127]
	v_mfma_f32_16x16x32_bf16 v[120:123], v[140:143], v[190:193], v[120:123]
	v_mfma_f32_16x16x32_bf16 v[108:111], v[132:135], v[198:201], v[108:111]
	v_mfma_f32_16x16x32_bf16 v[104:107], v[140:143], v[198:201], v[104:107]
	v_mfma_f32_16x16x32_bf16 v[96:99], v[132:135], v[210:213], v[96:99]
	v_mfma_f32_16x16x32_bf16 v[88:91], v[140:143], v[210:213], v[88:91]
	v_mfma_f32_16x16x32_bf16 v[80:83], v[132:135], v[218:221], v[80:83]
	v_mfma_f32_16x16x32_bf16 v[72:75], v[140:143], v[218:221], v[72:75]
	v_mfma_f32_16x16x32_bf16 v[116:119], v[144:147], v[170:173], v[116:119]
	v_mfma_f32_16x16x32_bf16 v[112:115], v[162:165], v[170:173], v[112:115]
	v_mfma_f32_16x16x32_bf16 v[100:103], v[144:147], v[194:197], v[100:103]
	v_mfma_f32_16x16x32_bf16 v[92:95], v[162:165], v[194:197], v[92:95]
	v_mfma_f32_16x16x32_bf16 v[84:87], v[144:147], v[206:209], v[84:87]
	v_mfma_f32_16x16x32_bf16 v[76:79], v[162:165], v[206:209], v[76:79]
	v_mfma_f32_16x16x32_bf16 v[68:71], v[144:147], v[214:217], v[68:71]
	v_mfma_f32_16x16x32_bf16 v[64:67], v[162:165], v[214:217], v[64:67]
	v_mfma_f32_16x16x32_bf16 v[116:119], v[148:151], v[190:193], v[116:119]
	v_mfma_f32_16x16x32_bf16 v[112:115], v[166:169], v[190:193], v[112:115]
	v_mfma_f32_16x16x32_bf16 v[100:103], v[148:151], v[198:201], v[100:103]
	v_mfma_f32_16x16x32_bf16 v[92:95], v[166:169], v[198:201], v[92:95]
	v_mfma_f32_16x16x32_bf16 v[84:87], v[148:151], v[210:213], v[84:87]
	v_mfma_f32_16x16x32_bf16 v[76:79], v[166:169], v[210:213], v[76:79]
	v_mfma_f32_16x16x32_bf16 v[68:71], v[148:151], v[218:221], v[68:71]
	v_mfma_f32_16x16x32_bf16 v[64:67], v[166:169], v[218:221], v[64:67]
	s_barrier
	s_add_i32 s42, s87, s3
	v_lshl_add_u64 v[174:175], s[46:47], 0, v[176:177]
	s_mov_b32 m0, s42
	ds_read_b128 v[170:173], v205 offset:16384
	ds_read_b128 v[190:193], v205 offset:17408
	ds_read_b128 v[194:197], v205 offset:18432
	ds_read_b128 v[198:201], v205 offset:19456
	ds_read_b128 v[206:209], v205 offset:20480
	ds_read_b128 v[210:213], v205 offset:21504
	ds_read_b128 v[214:217], v205 offset:22528
	ds_read_b128 v[218:221], v205 offset:23552
	global_load_lds_dwordx4 v[174:175], off
	s_add_i32 m0, s42, 0x2000
	s_add_u32 s42, s46, 0xb0000
	v_lshl_add_u64 v[222:223], s[46:47], 0, v[152:153]
	s_addc_u32 s43, s47, 0
	s_add_i32 s87, s90, s3
	global_load_lds_dwordx4 v[222:223], off
	v_lshl_add_u64 v[224:225], s[42:43], 0, v[176:177]
	s_mov_b32 m0, s87
	v_lshl_add_u64 v[234:235], s[68:69], 0, v[154:155]
	global_load_lds_dwordx4 v[224:225], off
	v_lshl_add_u64 v[224:225], s[42:43], 0, v[152:153]
	s_add_i32 m0, s87, 0x2000
	s_nop 0
	global_load_lds_dwordx4 v[224:225], off
	v_lshl_add_u64 v[224:225], s[68:69], 0, v[156:157]
	s_mov_b32 m0, s22
	s_nop 0
	global_load_lds_dwordx4 v[224:225], off
	s_mov_b32 m0, s58
	s_nop 0
	global_load_lds_dwordx4 v[234:235], off
	s_waitcnt vmcnt(8)
	s_waitcnt lgkmcnt(0)
	s_barrier
	s_waitcnt lgkmcnt(0)
	v_mfma_f32_16x16x32_bf16 v[60:63], v[128:131], v[170:173], v[60:63]
	v_mfma_f32_16x16x32_bf16 v[56:59], v[136:139], v[170:173], v[56:59]
	v_mfma_f32_16x16x32_bf16 v[48:51], v[128:131], v[194:197], v[48:51]
	v_mfma_f32_16x16x32_bf16 v[40:43], v[136:139], v[194:197], v[40:43]
	v_mfma_f32_16x16x32_bf16 v[32:35], v[128:131], v[206:209], v[32:35]
	v_mfma_f32_16x16x32_bf16 v[24:27], v[136:139], v[206:209], v[24:27]
	v_mfma_f32_16x16x32_bf16 v[16:19], v[128:131], v[214:217], v[16:19]
	v_mfma_f32_16x16x32_bf16 v[8:11], v[136:139], v[214:217], v[8:11]
	v_mfma_f32_16x16x32_bf16 v[60:63], v[132:135], v[190:193], v[60:63]
	v_mfma_f32_16x16x32_bf16 v[56:59], v[140:143], v[190:193], v[56:59]
	v_mfma_f32_16x16x32_bf16 v[48:51], v[132:135], v[198:201], v[48:51]
	v_mfma_f32_16x16x32_bf16 v[40:43], v[140:143], v[198:201], v[40:43]
	v_mfma_f32_16x16x32_bf16 v[32:35], v[132:135], v[210:213], v[32:35]
	v_mfma_f32_16x16x32_bf16 v[24:27], v[140:143], v[210:213], v[24:27]
	v_mfma_f32_16x16x32_bf16 v[16:19], v[132:135], v[218:221], v[16:19]
	v_mfma_f32_16x16x32_bf16 v[8:11], v[140:143], v[218:221], v[8:11]
	v_mfma_f32_16x16x32_bf16 v[52:55], v[144:147], v[170:173], v[52:55]
	v_mfma_f32_16x16x32_bf16 v[44:47], v[162:165], v[170:173], v[44:47]
	v_mfma_f32_16x16x32_bf16 v[36:39], v[144:147], v[194:197], v[36:39]
	v_mfma_f32_16x16x32_bf16 v[28:31], v[162:165], v[194:197], v[28:31]
	v_mfma_f32_16x16x32_bf16 v[20:23], v[144:147], v[206:209], v[20:23]
	v_mfma_f32_16x16x32_bf16 v[12:15], v[162:165], v[206:209], v[12:15]
	v_mfma_f32_16x16x32_bf16 v[4:7], v[144:147], v[214:217], v[4:7]
	v_mfma_f32_16x16x32_bf16 v[0:3], v[162:165], v[214:217], v[0:3]
	v_mfma_f32_16x16x32_bf16 v[52:55], v[148:151], v[190:193], v[52:55]
	v_mfma_f32_16x16x32_bf16 v[44:47], v[166:169], v[190:193], v[44:47]
	v_mfma_f32_16x16x32_bf16 v[36:39], v[148:151], v[198:201], v[36:39]
	v_mfma_f32_16x16x32_bf16 v[28:31], v[166:169], v[198:201], v[28:31]
	v_mfma_f32_16x16x32_bf16 v[20:23], v[148:151], v[210:213], v[20:23]
	v_mfma_f32_16x16x32_bf16 v[12:15], v[166:169], v[210:213], v[12:15]
	v_mfma_f32_16x16x32_bf16 v[4:7], v[148:151], v[218:221], v[4:7]
	v_mfma_f32_16x16x32_bf16 v[0:3], v[166:169], v[218:221], v[0:3]
	s_barrier
	s_add_i32 s87, 0, 0x18000
	s_add_i32 s90, 0, 0x1c000
	v_add_u32_e32 v140, s87, v204
	v_add_u32_e32 v166, s90, v204
	ds_read_b128 v[128:131], v140
	ds_read_b128 v[132:135], v140 offset:1024
	ds_read_b128 v[136:139], v140 offset:2048
	ds_read_b128 v[140:143], v140 offset:3072
	ds_read_b128 v[144:147], v166
	ds_read_b128 v[148:151], v166 offset:1024
	ds_read_b128 v[162:165], v166 offset:2048
	ds_read_b128 v[166:169], v166 offset:3072
	s_add_u32 s42, s68, 0xb0000
	s_addc_u32 s43, s69, 0
	s_mov_b32 m0, s59
	v_lshl_add_u64 v[236:237], s[42:43], 0, v[156:157]
	ds_read_b128 v[170:173], v205 offset:32768
	ds_read_b128 v[190:193], v205 offset:33792
	ds_read_b128 v[194:197], v205 offset:34816
	ds_read_b128 v[198:201], v205 offset:35840
	ds_read_b128 v[206:209], v205 offset:36864
	ds_read_b128 v[210:213], v205 offset:37888
	ds_read_b128 v[214:217], v205 offset:38912
	ds_read_b128 v[218:221], v205 offset:39936
	global_load_lds_dwordx4 v[236:237], off
	v_lshl_add_u64 v[236:237], s[42:43], 0, v[154:155]
	s_mov_b32 m0, s60
	s_nop 0
	global_load_lds_dwordx4 v[236:237], off
	s_waitcnt vmcnt(8)
	s_waitcnt lgkmcnt(0)
	s_barrier
	s_waitcnt lgkmcnt(0)
	v_mfma_f32_16x16x32_bf16 v[124:127], v[128:131], v[170:173], v[124:127]
	v_mfma_f32_16x16x32_bf16 v[120:123], v[136:139], v[170:173], v[120:123]
	v_mfma_f32_16x16x32_bf16 v[108:111], v[128:131], v[194:197], v[108:111]
	v_mfma_f32_16x16x32_bf16 v[104:107], v[136:139], v[194:197], v[104:107]
	v_mfma_f32_16x16x32_bf16 v[96:99], v[128:131], v[206:209], v[96:99]
	v_mfma_f32_16x16x32_bf16 v[88:91], v[136:139], v[206:209], v[88:91]
	v_mfma_f32_16x16x32_bf16 v[80:83], v[128:131], v[214:217], v[80:83]
	v_mfma_f32_16x16x32_bf16 v[72:75], v[136:139], v[214:217], v[72:75]
	v_mfma_f32_16x16x32_bf16 v[124:127], v[132:135], v[190:193], v[124:127]
	v_mfma_f32_16x16x32_bf16 v[120:123], v[140:143], v[190:193], v[120:123]
	v_mfma_f32_16x16x32_bf16 v[108:111], v[132:135], v[198:201], v[108:111]
	v_mfma_f32_16x16x32_bf16 v[104:107], v[140:143], v[198:201], v[104:107]
	v_mfma_f32_16x16x32_bf16 v[96:99], v[132:135], v[210:213], v[96:99]
	v_mfma_f32_16x16x32_bf16 v[88:91], v[140:143], v[210:213], v[88:91]
	v_mfma_f32_16x16x32_bf16 v[80:83], v[132:135], v[218:221], v[80:83]
	v_mfma_f32_16x16x32_bf16 v[72:75], v[140:143], v[218:221], v[72:75]
	v_mfma_f32_16x16x32_bf16 v[116:119], v[144:147], v[170:173], v[116:119]
	v_mfma_f32_16x16x32_bf16 v[112:115], v[162:165], v[170:173], v[112:115]
	v_mfma_f32_16x16x32_bf16 v[100:103], v[144:147], v[194:197], v[100:103]
	v_mfma_f32_16x16x32_bf16 v[92:95], v[162:165], v[194:197], v[92:95]
	v_mfma_f32_16x16x32_bf16 v[84:87], v[144:147], v[206:209], v[84:87]
	v_mfma_f32_16x16x32_bf16 v[76:79], v[162:165], v[206:209], v[76:79]
	v_mfma_f32_16x16x32_bf16 v[68:71], v[144:147], v[214:217], v[68:71]
	v_mfma_f32_16x16x32_bf16 v[64:67], v[162:165], v[214:217], v[64:67]
	v_mfma_f32_16x16x32_bf16 v[116:119], v[148:151], v[190:193], v[116:119]
	v_mfma_f32_16x16x32_bf16 v[112:115], v[166:169], v[190:193], v[112:115]
	v_mfma_f32_16x16x32_bf16 v[100:103], v[148:151], v[198:201], v[100:103]
	v_mfma_f32_16x16x32_bf16 v[92:95], v[166:169], v[198:201], v[92:95]
	v_mfma_f32_16x16x32_bf16 v[84:87], v[148:151], v[210:213], v[84:87]
	v_mfma_f32_16x16x32_bf16 v[76:79], v[166:169], v[210:213], v[76:79]
	v_mfma_f32_16x16x32_bf16 v[68:71], v[148:151], v[218:221], v[68:71]
	v_mfma_f32_16x16x32_bf16 v[64:67], v[166:169], v[218:221], v[64:67]
	s_barrier
	s_add_i32 s42, s87, s3
	v_lshl_add_u64 v[174:175], v[174:175], 0, s[24:25]
	s_mov_b32 m0, s42
	ds_read_b128 v[170:173], v205 offset:49152
	ds_read_b128 v[190:193], v205 offset:50176
	ds_read_b128 v[194:197], v205 offset:51200
	ds_read_b128 v[198:201], v205 offset:52224
	ds_read_b128 v[206:209], v205 offset:53248
	ds_read_b128 v[210:213], v205 offset:54272
	ds_read_b128 v[214:217], v205 offset:55296
	ds_read_b128 v[218:221], v205 offset:56320
	global_load_lds_dwordx4 v[174:175], off
	s_add_i32 m0, s42, 0x2000
	s_add_u32 s42, s46, 0xb0080
	v_lshl_add_u64 v[174:175], v[222:223], 0, s[24:25]
	s_addc_u32 s43, s47, 0
	s_add_i32 s46, s90, s3
	global_load_lds_dwordx4 v[174:175], off
	v_lshl_add_u64 v[174:175], s[42:43], 0, v[176:177]
	s_mov_b32 m0, s46
	s_nop 0
	global_load_lds_dwordx4 v[174:175], off
	v_lshl_add_u64 v[174:175], s[42:43], 0, v[152:153]
	s_add_i32 m0, s46, 0x2000
	s_nop 0
	global_load_lds_dwordx4 v[174:175], off
	v_lshl_add_u64 v[174:175], v[224:225], 0, s[24:25]
	s_mov_b32 m0, s62
	s_nop 0
	global_load_lds_dwordx4 v[174:175], off
	v_lshl_add_u64 v[174:175], v[234:235], 0, s[24:25]
	s_mov_b32 m0, s63
	s_nop 0
	global_load_lds_dwordx4 v[174:175], off
	s_waitcnt vmcnt(8)
	s_waitcnt lgkmcnt(0)
	s_barrier
	s_waitcnt lgkmcnt(0)
	v_mfma_f32_16x16x32_bf16 v[60:63], v[128:131], v[170:173], v[60:63]
	v_mfma_f32_16x16x32_bf16 v[56:59], v[136:139], v[170:173], v[56:59]
	v_mfma_f32_16x16x32_bf16 v[48:51], v[128:131], v[194:197], v[48:51]
	v_mfma_f32_16x16x32_bf16 v[40:43], v[136:139], v[194:197], v[40:43]
	v_mfma_f32_16x16x32_bf16 v[32:35], v[128:131], v[206:209], v[32:35]
	v_mfma_f32_16x16x32_bf16 v[24:27], v[136:139], v[206:209], v[24:27]
	v_mfma_f32_16x16x32_bf16 v[16:19], v[128:131], v[214:217], v[16:19]
	v_mfma_f32_16x16x32_bf16 v[8:11], v[136:139], v[214:217], v[8:11]
	v_mfma_f32_16x16x32_bf16 v[60:63], v[132:135], v[190:193], v[60:63]
	v_mfma_f32_16x16x32_bf16 v[56:59], v[140:143], v[190:193], v[56:59]
	v_mfma_f32_16x16x32_bf16 v[48:51], v[132:135], v[198:201], v[48:51]
	v_mfma_f32_16x16x32_bf16 v[40:43], v[140:143], v[198:201], v[40:43]
	v_mfma_f32_16x16x32_bf16 v[32:35], v[132:135], v[210:213], v[32:35]
	v_mfma_f32_16x16x32_bf16 v[24:27], v[140:143], v[210:213], v[24:27]
	v_mfma_f32_16x16x32_bf16 v[16:19], v[132:135], v[218:221], v[16:19]
	v_mfma_f32_16x16x32_bf16 v[8:11], v[140:143], v[218:221], v[8:11]
	v_mfma_f32_16x16x32_bf16 v[52:55], v[144:147], v[170:173], v[52:55]
	v_mfma_f32_16x16x32_bf16 v[44:47], v[162:165], v[170:173], v[44:47]
	v_mfma_f32_16x16x32_bf16 v[36:39], v[144:147], v[194:197], v[36:39]
	v_mfma_f32_16x16x32_bf16 v[28:31], v[162:165], v[194:197], v[28:31]
	v_mfma_f32_16x16x32_bf16 v[20:23], v[144:147], v[206:209], v[20:23]
	v_mfma_f32_16x16x32_bf16 v[12:15], v[162:165], v[206:209], v[12:15]
	v_mfma_f32_16x16x32_bf16 v[4:7], v[144:147], v[214:217], v[4:7]
	v_mfma_f32_16x16x32_bf16 v[0:3], v[162:165], v[214:217], v[0:3]
	v_mfma_f32_16x16x32_bf16 v[52:55], v[148:151], v[190:193], v[52:55]
	v_mfma_f32_16x16x32_bf16 v[44:47], v[166:169], v[190:193], v[44:47]
	v_mfma_f32_16x16x32_bf16 v[36:39], v[148:151], v[198:201], v[36:39]
	v_mfma_f32_16x16x32_bf16 v[28:31], v[166:169], v[198:201], v[28:31]
	v_mfma_f32_16x16x32_bf16 v[20:23], v[148:151], v[210:213], v[20:23]
	v_mfma_f32_16x16x32_bf16 v[12:15], v[166:169], v[210:213], v[12:15]
	v_mfma_f32_16x16x32_bf16 v[4:7], v[148:151], v[218:221], v[4:7]
	v_mfma_f32_16x16x32_bf16 v[0:3], v[166:169], v[218:221], v[0:3]
	s_barrier
	s_add_i32 s86, s86, 2
	s_add_u32 s82, s82, 0x100
	s_addc_u32 s83, s83, 0
	s_cmp_gt_u32 s86, 41
	s_mov_b64 s[42:43], s[44:45]
	s_cbranch_scc0 .LBB0_297
	s_setprio 0
	s_and_b64 vcc, exec, s[36:37]
	s_cbranch_vccz .LBB0_300
	s_barrier

.LBB0_326:
	s_add_u32 s82, s44, 0x100
	v_mov_b32_e32 v0, 0
	s_addc_u32 s83, s45, 0
	s_mov_b32 s86, -2
	v_mov_b32_e32 v1, v0
	v_mov_b32_e32 v2, v0
	v_mov_b32_e32 v3, v0
	v_mov_b32_e32 v4, v0
	v_mov_b32_e32 v5, v0
	v_mov_b32_e32 v6, v0
	v_mov_b32_e32 v7, v0
	v_mov_b32_e32 v8, v0
	v_mov_b32_e32 v9, v0
	v_mov_b32_e32 v10, v0
	v_mov_b32_e32 v11, v0
	v_mov_b32_e32 v12, v0
	v_mov_b32_e32 v13, v0
	v_mov_b32_e32 v14, v0
	v_mov_b32_e32 v15, v0
	v_mov_b32_e32 v32, v0
	v_mov_b32_e32 v33, v0
	v_mov_b32_e32 v34, v0
	v_mov_b32_e32 v35, v0
	v_mov_b32_e32 v36, v0
	v_mov_b32_e32 v37, v0
	v_mov_b32_e32 v38, v0
	v_mov_b32_e32 v39, v0
	v_mov_b32_e32 v40, v0
	v_mov_b32_e32 v41, v0
	v_mov_b32_e32 v42, v0
	v_mov_b32_e32 v43, v0
	v_mov_b32_e32 v44, v0
	v_mov_b32_e32 v45, v0
	v_mov_b32_e32 v46, v0
	v_mov_b32_e32 v47, v0
	v_mov_b32_e32 v16, v0
	v_mov_b32_e32 v17, v0
	v_mov_b32_e32 v18, v0
	v_mov_b32_e32 v19, v0
	v_mov_b32_e32 v20, v0
	v_mov_b32_e32 v21, v0
	v_mov_b32_e32 v22, v0
	v_mov_b32_e32 v23, v0
	v_mov_b32_e32 v24, v0
	v_mov_b32_e32 v25, v0
	v_mov_b32_e32 v26, v0
	v_mov_b32_e32 v27, v0
	v_mov_b32_e32 v28, v0
	v_mov_b32_e32 v29, v0
	v_mov_b32_e32 v30, v0
	v_mov_b32_e32 v31, v0
	v_mov_b32_e32 v48, v0
	v_mov_b32_e32 v49, v0
	v_mov_b32_e32 v50, v0
	v_mov_b32_e32 v51, v0
	v_mov_b32_e32 v52, v0
	v_mov_b32_e32 v53, v0
	v_mov_b32_e32 v54, v0
	v_mov_b32_e32 v55, v0
	v_mov_b32_e32 v56, v0
	v_mov_b32_e32 v57, v0
	v_mov_b32_e32 v58, v0
	v_mov_b32_e32 v59, v0
	v_mov_b32_e32 v60, v0
	v_mov_b32_e32 v61, v0
	v_mov_b32_e32 v62, v0
	v_mov_b32_e32 v63, v0
	v_mov_b32_e32 v64, v0
	v_mov_b32_e32 v65, v0
	v_mov_b32_e32 v66, v0
	v_mov_b32_e32 v67, v0
	v_mov_b32_e32 v68, v0
	v_mov_b32_e32 v69, v0
	v_mov_b32_e32 v70, v0
	v_mov_b32_e32 v71, v0
	v_mov_b32_e32 v72, v0
	v_mov_b32_e32 v73, v0
	v_mov_b32_e32 v74, v0
	v_mov_b32_e32 v75, v0
	v_mov_b32_e32 v76, v0
	v_mov_b32_e32 v77, v0
	v_mov_b32_e32 v78, v0
	v_mov_b32_e32 v79, v0
	v_mov_b32_e32 v96, v0
	v_mov_b32_e32 v97, v0
	v_mov_b32_e32 v98, v0
	v_mov_b32_e32 v99, v0
	v_mov_b32_e32 v100, v0
	v_mov_b32_e32 v101, v0
	v_mov_b32_e32 v102, v0
	v_mov_b32_e32 v103, v0
	v_mov_b32_e32 v104, v0
	v_mov_b32_e32 v105, v0
	v_mov_b32_e32 v106, v0
	v_mov_b32_e32 v107, v0
	v_mov_b32_e32 v108, v0
	v_mov_b32_e32 v109, v0
	v_mov_b32_e32 v110, v0
	v_mov_b32_e32 v111, v0
	v_mov_b32_e32 v80, v0
	v_mov_b32_e32 v81, v0
	v_mov_b32_e32 v82, v0
	v_mov_b32_e32 v83, v0
	v_mov_b32_e32 v84, v0
	v_mov_b32_e32 v85, v0
	v_mov_b32_e32 v86, v0
	v_mov_b32_e32 v87, v0
	v_mov_b32_e32 v88, v0
	v_mov_b32_e32 v89, v0
	v_mov_b32_e32 v90, v0
	v_mov_b32_e32 v91, v0
	v_mov_b32_e32 v92, v0
	v_mov_b32_e32 v93, v0
	v_mov_b32_e32 v94, v0
	v_mov_b32_e32 v95, v0
	v_mov_b32_e32 v112, v0
	v_mov_b32_e32 v113, v0
	v_mov_b32_e32 v114, v0
	v_mov_b32_e32 v115, v0
	v_mov_b32_e32 v116, v0
	v_mov_b32_e32 v117, v0
	v_mov_b32_e32 v118, v0
	v_mov_b32_e32 v119, v0
	v_mov_b32_e32 v120, v0
	v_mov_b32_e32 v121, v0
	v_mov_b32_e32 v122, v0
	v_mov_b32_e32 v123, v0
	v_mov_b32_e32 v124, v0
	v_mov_b32_e32 v125, v0
	v_mov_b32_e32 v126, v0
	v_mov_b32_e32 v127, v0
	v_readfirstlane_b32 s44, v226
	s_nop 3
	s_bitcmp1_b32 s44, 8
	s_cbranch_scc0 .Lpr_327
	s_setprio 1
.Lpr_327:
.LBB0_327:
	s_add_u32 s44, s42, 0x100
	s_addc_u32 s45, s43, 0
	s_add_i32 s87, 0, 0x10000
	s_cmp_eq_u32 s86, 40
	s_cselect_b32 s69, s1, s45
	s_cselect_b32 s68, s0, s44
	s_cselect_b32 s47, s39, s83
	s_cselect_b32 s46, s38, s82
	s_add_i32 s90, 0, 0x14000
	v_add_u32_e32 v150, s87, v162
	v_add_u32_e32 v158, s90, v162
	ds_read_b128 v[138:141], v150
	ds_read_b128 v[142:145], v150 offset:1024
	ds_read_b128 v[146:149], v150 offset:2048
	ds_read_b128 v[150:153], v150 offset:3072
	ds_read_b128 v[154:157], v158
	ds_read_b128 v[164:167], v158 offset:1024
	ds_read_b128 v[168:171], v158 offset:2048
	ds_read_b128 v[172:175], v158 offset:3072
	v_lshl_add_u64 v[158:159], s[42:43], 0, v[136:137]
	s_add_i32 m0, s58, 0xc000
	ds_read_b128 v[190:193], v163
	ds_read_b128 v[194:197], v163 offset:1024
	ds_read_b128 v[198:201], v163 offset:2048
	ds_read_b128 v[202:205], v163 offset:3072
	ds_read_b128 v[206:209], v163 offset:4096
	ds_read_b128 v[210:213], v163 offset:5120
	ds_read_b128 v[214:217], v163 offset:6144
	ds_read_b128 v[218:221], v163 offset:7168
	global_load_lds_dwordx4 v[158:159], off
	v_lshl_add_u64 v[158:159], s[42:43], 0, v[134:135]
	s_add_i32 m0, s58, 0xe000
	s_nop 0
	global_load_lds_dwordx4 v[158:159], off
	s_waitcnt vmcnt(8)
	s_waitcnt lgkmcnt(0)
	s_barrier
	s_waitcnt lgkmcnt(0)
	v_mfma_f32_16x16x32_bf16 v[124:127], v[138:141], v[190:193], v[124:127]
	v_mfma_f32_16x16x32_bf16 v[120:123], v[146:149], v[190:193], v[120:123]
	v_mfma_f32_16x16x32_bf16 v[116:119], v[138:141], v[198:201], v[116:119]
	v_mfma_f32_16x16x32_bf16 v[112:115], v[146:149], v[198:201], v[112:115]
	v_mfma_f32_16x16x32_bf16 v[92:95], v[138:141], v[206:209], v[92:95]
	v_mfma_f32_16x16x32_bf16 v[88:91], v[146:149], v[206:209], v[88:91]
	v_mfma_f32_16x16x32_bf16 v[84:87], v[138:141], v[214:217], v[84:87]
	v_mfma_f32_16x16x32_bf16 v[80:83], v[146:149], v[214:217], v[80:83]
	v_mfma_f32_16x16x32_bf16 v[124:127], v[142:145], v[194:197], v[124:127]
	v_mfma_f32_16x16x32_bf16 v[120:123], v[150:153], v[194:197], v[120:123]
	v_mfma_f32_16x16x32_bf16 v[116:119], v[142:145], v[202:205], v[116:119]
	v_mfma_f32_16x16x32_bf16 v[112:115], v[150:153], v[202:205], v[112:115]
	v_mfma_f32_16x16x32_bf16 v[92:95], v[142:145], v[210:213], v[92:95]
	v_mfma_f32_16x16x32_bf16 v[88:91], v[150:153], v[210:213], v[88:91]
	v_mfma_f32_16x16x32_bf16 v[84:87], v[142:145], v[218:221], v[84:87]
	v_mfma_f32_16x16x32_bf16 v[80:83], v[150:153], v[218:221], v[80:83]
	v_mfma_f32_16x16x32_bf16 v[108:111], v[154:157], v[190:193], v[108:111]
	v_mfma_f32_16x16x32_bf16 v[104:107], v[168:171], v[190:193], v[104:107]
	v_mfma_f32_16x16x32_bf16 v[100:103], v[154:157], v[198:201], v[100:103]
	v_mfma_f32_16x16x32_bf16 v[96:99], v[168:171], v[198:201], v[96:99]
	v_mfma_f32_16x16x32_bf16 v[76:79], v[154:157], v[206:209], v[76:79]
	v_mfma_f32_16x16x32_bf16 v[72:75], v[168:171], v[206:209], v[72:75]
	v_mfma_f32_16x16x32_bf16 v[68:71], v[154:157], v[214:217], v[68:71]
	v_mfma_f32_16x16x32_bf16 v[64:67], v[168:171], v[214:217], v[64:67]
	v_mfma_f32_16x16x32_bf16 v[108:111], v[164:167], v[194:197], v[108:111]
	v_mfma_f32_16x16x32_bf16 v[104:107], v[172:175], v[194:197], v[104:107]
	v_mfma_f32_16x16x32_bf16 v[100:103], v[164:167], v[202:205], v[100:103]
	v_mfma_f32_16x16x32_bf16 v[96:99], v[172:175], v[202:205], v[96:99]
	v_mfma_f32_16x16x32_bf16 v[76:79], v[164:167], v[210:213], v[76:79]
	v_mfma_f32_16x16x32_bf16 v[72:75], v[172:175], v[210:213], v[72:75]
	v_mfma_f32_16x16x32_bf16 v[68:71], v[164:167], v[218:221], v[68:71]
	v_mfma_f32_16x16x32_bf16 v[64:67], v[172:175], v[218:221], v[64:67]
	s_barrier
	s_add_i32 s42, s87, s3
	v_lshl_add_u64 v[158:159], s[46:47], 0, v[176:177]
	s_mov_b32 m0, s42
	ds_read_b128 v[190:193], v163 offset:16384
	ds_read_b128 v[194:197], v163 offset:17408
	ds_read_b128 v[198:201], v163 offset:18432
	ds_read_b128 v[202:205], v163 offset:19456
	ds_read_b128 v[206:209], v163 offset:20480
	ds_read_b128 v[210:213], v163 offset:21504
	ds_read_b128 v[214:217], v163 offset:22528
	ds_read_b128 v[218:221], v163 offset:23552
	global_load_lds_dwordx4 v[158:159], off
	s_add_i32 m0, s42, 0x2000
	s_add_u32 s42, s46, 0xb0000
	v_lshl_add_u64 v[222:223], s[46:47], 0, v[128:129]
	s_addc_u32 s43, s47, 0
	s_add_i32 s87, s90, s3
	global_load_lds_dwordx4 v[222:223], off
	v_lshl_add_u64 v[224:225], s[42:43], 0, v[176:177]
	s_mov_b32 m0, s87
	v_lshl_add_u64 v[234:235], s[68:69], 0, v[130:131]
	global_load_lds_dwordx4 v[224:225], off
	v_lshl_add_u64 v[224:225], s[42:43], 0, v[128:129]
	s_add_i32 m0, s87, 0x2000
	s_nop 0
	global_load_lds_dwordx4 v[224:225], off
	v_lshl_add_u64 v[224:225], s[68:69], 0, v[132:133]
	s_mov_b32 m0, s58
	s_nop 0
	global_load_lds_dwordx4 v[224:225], off
	s_mov_b32 m0, s59
	s_nop 0
	global_load_lds_dwordx4 v[234:235], off
	s_waitcnt vmcnt(8)
	s_waitcnt lgkmcnt(0)
	s_barrier
	s_waitcnt lgkmcnt(0)
	v_mfma_f32_16x16x32_bf16 v[60:63], v[138:141], v[190:193], v[60:63]
	v_mfma_f32_16x16x32_bf16 v[56:59], v[146:149], v[190:193], v[56:59]
	v_mfma_f32_16x16x32_bf16 v[52:55], v[138:141], v[198:201], v[52:55]
	v_mfma_f32_16x16x32_bf16 v[48:51], v[146:149], v[198:201], v[48:51]
	v_mfma_f32_16x16x32_bf16 v[28:31], v[138:141], v[206:209], v[28:31]
	v_mfma_f32_16x16x32_bf16 v[24:27], v[146:149], v[206:209], v[24:27]
	v_mfma_f32_16x16x32_bf16 v[20:23], v[138:141], v[214:217], v[20:23]
	v_mfma_f32_16x16x32_bf16 v[16:19], v[146:149], v[214:217], v[16:19]
	v_mfma_f32_16x16x32_bf16 v[60:63], v[142:145], v[194:197], v[60:63]
	v_mfma_f32_16x16x32_bf16 v[56:59], v[150:153], v[194:197], v[56:59]
	v_mfma_f32_16x16x32_bf16 v[52:55], v[142:145], v[202:205], v[52:55]
	v_mfma_f32_16x16x32_bf16 v[48:51], v[150:153], v[202:205], v[48:51]
	v_mfma_f32_16x16x32_bf16 v[28:31], v[142:145], v[210:213], v[28:31]
	v_mfma_f32_16x16x32_bf16 v[24:27], v[150:153], v[210:213], v[24:27]
	v_mfma_f32_16x16x32_bf16 v[20:23], v[142:145], v[218:221], v[20:23]
	v_mfma_f32_16x16x32_bf16 v[16:19], v[150:153], v[218:221], v[16:19]
	v_mfma_f32_16x16x32_bf16 v[44:47], v[154:157], v[190:193], v[44:47]
	v_mfma_f32_16x16x32_bf16 v[40:43], v[168:171], v[190:193], v[40:43]
	v_mfma_f32_16x16x32_bf16 v[36:39], v[154:157], v[198:201], v[36:39]
	v_mfma_f32_16x16x32_bf16 v[32:35], v[168:171], v[198:201], v[32:35]
	v_mfma_f32_16x16x32_bf16 v[12:15], v[154:157], v[206:209], v[12:15]
	v_mfma_f32_16x16x32_bf16 v[8:11], v[168:171], v[206:209], v[8:11]
	v_mfma_f32_16x16x32_bf16 v[4:7], v[154:157], v[214:217], v[4:7]
	v_mfma_f32_16x16x32_bf16 v[0:3], v[168:171], v[214:217], v[0:3]
	v_mfma_f32_16x16x32_bf16 v[44:47], v[164:167], v[194:197], v[44:47]
	v_mfma_f32_16x16x32_bf16 v[40:43], v[172:175], v[194:197], v[40:43]
	v_mfma_f32_16x16x32_bf16 v[36:39], v[164:167], v[202:205], v[36:39]
	v_mfma_f32_16x16x32_bf16 v[32:35], v[172:175], v[202:205], v[32:35]
	v_mfma_f32_16x16x32_bf16 v[12:15], v[164:167], v[210:213], v[12:15]
	v_mfma_f32_16x16x32_bf16 v[8:11], v[172:175], v[210:213], v[8:11]
	v_mfma_f32_16x16x32_bf16 v[4:7], v[164:167], v[218:221], v[4:7]
	v_mfma_f32_16x16x32_bf16 v[0:3], v[172:175], v[218:221], v[0:3]
	s_barrier
	s_add_i32 s87, 0, 0x18000
	s_add_i32 s90, 0, 0x1c000
	v_add_u32_e32 v150, s87, v162
	v_add_u32_e32 v172, s90, v162
	ds_read_b128 v[138:141], v150
	ds_read_b128 v[142:145], v150 offset:1024
	ds_read_b128 v[146:149], v150 offset:2048
	ds_read_b128 v[150:153], v150 offset:3072
	ds_read_b128 v[154:157], v172
	ds_read_b128 v[164:167], v172 offset:1024
	ds_read_b128 v[168:171], v172 offset:2048
	ds_read_b128 v[172:175], v172 offset:3072
	s_add_u32 s42, s68, 0xb0000
	s_addc_u32 s43, s69, 0
	s_mov_b32 m0, s60
	v_lshl_add_u64 v[236:237], s[42:43], 0, v[132:133]
	ds_read_b128 v[190:193], v163 offset:32768
	ds_read_b128 v[194:197], v163 offset:33792
	ds_read_b128 v[198:201], v163 offset:34816
	ds_read_b128 v[202:205], v163 offset:35840
	ds_read_b128 v[206:209], v163 offset:36864
	ds_read_b128 v[210:213], v163 offset:37888
	ds_read_b128 v[214:217], v163 offset:38912
	ds_read_b128 v[218:221], v163 offset:39936
	global_load_lds_dwordx4 v[236:237], off
	v_lshl_add_u64 v[236:237], s[42:43], 0, v[130:131]
	s_mov_b32 m0, s61
	s_nop 0
	global_load_lds_dwordx4 v[236:237], off
	s_waitcnt vmcnt(8)
	s_waitcnt lgkmcnt(0)
	s_barrier
	s_waitcnt lgkmcnt(0)
	v_mfma_f32_16x16x32_bf16 v[124:127], v[138:141], v[190:193], v[124:127]
	v_mfma_f32_16x16x32_bf16 v[120:123], v[146:149], v[190:193], v[120:123]
	v_mfma_f32_16x16x32_bf16 v[116:119], v[138:141], v[198:201], v[116:119]
	v_mfma_f32_16x16x32_bf16 v[112:115], v[146:149], v[198:201], v[112:115]
	v_mfma_f32_16x16x32_bf16 v[92:95], v[138:141], v[206:209], v[92:95]
	v_mfma_f32_16x16x32_bf16 v[88:91], v[146:149], v[206:209], v[88:91]
	v_mfma_f32_16x16x32_bf16 v[84:87], v[138:141], v[214:217], v[84:87]
	v_mfma_f32_16x16x32_bf16 v[80:83], v[146:149], v[214:217], v[80:83]
	v_mfma_f32_16x16x32_bf16 v[124:127], v[142:145], v[194:197], v[124:127]
	v_mfma_f32_16x16x32_bf16 v[120:123], v[150:153], v[194:197], v[120:123]
	v_mfma_f32_16x16x32_bf16 v[116:119], v[142:145], v[202:205], v[116:119]
	v_mfma_f32_16x16x32_bf16 v[112:115], v[150:153], v[202:205], v[112:115]
	v_mfma_f32_16x16x32_bf16 v[92:95], v[142:145], v[210:213], v[92:95]
	v_mfma_f32_16x16x32_bf16 v[88:91], v[150:153], v[210:213], v[88:91]
	v_mfma_f32_16x16x32_bf16 v[84:87], v[142:145], v[218:221], v[84:87]
	v_mfma_f32_16x16x32_bf16 v[80:83], v[150:153], v[218:221], v[80:83]
	v_mfma_f32_16x16x32_bf16 v[108:111], v[154:157], v[190:193], v[108:111]
	v_mfma_f32_16x16x32_bf16 v[104:107], v[168:171], v[190:193], v[104:107]
	v_mfma_f32_16x16x32_bf16 v[100:103], v[154:157], v[198:201], v[100:103]
	v_mfma_f32_16x16x32_bf16 v[96:99], v[168:171], v[198:201], v[96:99]
	v_mfma_f32_16x16x32_bf16 v[76:79], v[154:157], v[206:209], v[76:79]
	v_mfma_f32_16x16x32_bf16 v[72:75], v[168:171], v[206:209], v[72:75]
	v_mfma_f32_16x16x32_bf16 v[68:71], v[154:157], v[214:217], v[68:71]
	v_mfma_f32_16x16x32_bf16 v[64:67], v[168:171], v[214:217], v[64:67]
	v_mfma_f32_16x16x32_bf16 v[108:111], v[164:167], v[194:197], v[108:111]
	v_mfma_f32_16x16x32_bf16 v[104:107], v[172:175], v[194:197], v[104:107]
	v_mfma_f32_16x16x32_bf16 v[100:103], v[164:167], v[202:205], v[100:103]
	v_mfma_f32_16x16x32_bf16 v[96:99], v[172:175], v[202:205], v[96:99]
	v_mfma_f32_16x16x32_bf16 v[76:79], v[164:167], v[210:213], v[76:79]
	v_mfma_f32_16x16x32_bf16 v[72:75], v[172:175], v[210:213], v[72:75]
	v_mfma_f32_16x16x32_bf16 v[68:71], v[164:167], v[218:221], v[68:71]
	v_mfma_f32_16x16x32_bf16 v[64:67], v[172:175], v[218:221], v[64:67]
	s_barrier
	s_add_i32 s42, s87, s3
	v_lshl_add_u64 v[158:159], v[158:159], 0, s[24:25]
	s_mov_b32 m0, s42
	ds_read_b128 v[190:193], v163 offset:49152
	ds_read_b128 v[194:197], v163 offset:50176
	ds_read_b128 v[198:201], v163 offset:51200
	ds_read_b128 v[202:205], v163 offset:52224
	ds_read_b128 v[206:209], v163 offset:53248
	ds_read_b128 v[210:213], v163 offset:54272
	ds_read_b128 v[214:217], v163 offset:55296
	ds_read_b128 v[218:221], v163 offset:56320
	global_load_lds_dwordx4 v[158:159], off
	s_add_i32 m0, s42, 0x2000
	s_add_u32 s42, s46, 0xb0080
	v_lshl_add_u64 v[158:159], v[222:223], 0, s[24:25]
	s_addc_u32 s43, s47, 0
	s_add_i32 s46, s90, s3
	global_load_lds_dwordx4 v[158:159], off
	v_lshl_add_u64 v[158:159], s[42:43], 0, v[176:177]
	s_mov_b32 m0, s46
	s_nop 0
	global_load_lds_dwordx4 v[158:159], off
	v_lshl_add_u64 v[158:159], s[42:43], 0, v[128:129]
	s_add_i32 m0, s46, 0x2000
	s_nop 0
	global_load_lds_dwordx4 v[158:159], off
	v_lshl_add_u64 v[158:159], v[224:225], 0, s[24:25]
	s_mov_b32 m0, s76
	s_nop 0
	global_load_lds_dwordx4 v[158:159], off
	v_lshl_add_u64 v[158:159], v[234:235], 0, s[24:25]
	s_mov_b32 m0, s77
	s_nop 0
	global_load_lds_dwordx4 v[158:159], off
	s_waitcnt vmcnt(8)
	s_waitcnt lgkmcnt(0)
	s_barrier
	s_waitcnt lgkmcnt(0)
	v_mfma_f32_16x16x32_bf16 v[60:63], v[138:141], v[190:193], v[60:63]
	v_mfma_f32_16x16x32_bf16 v[56:59], v[146:149], v[190:193], v[56:59]
	v_mfma_f32_16x16x32_bf16 v[52:55], v[138:141], v[198:201], v[52:55]
	v_mfma_f32_16x16x32_bf16 v[48:51], v[146:149], v[198:201], v[48:51]
	v_mfma_f32_16x16x32_bf16 v[28:31], v[138:141], v[206:209], v[28:31]
	v_mfma_f32_16x16x32_bf16 v[24:27], v[146:149], v[206:209], v[24:27]
	v_mfma_f32_16x16x32_bf16 v[20:23], v[138:141], v[214:217], v[20:23]
	v_mfma_f32_16x16x32_bf16 v[16:19], v[146:149], v[214:217], v[16:19]
	v_mfma_f32_16x16x32_bf16 v[60:63], v[142:145], v[194:197], v[60:63]
	v_mfma_f32_16x16x32_bf16 v[56:59], v[150:153], v[194:197], v[56:59]
	v_mfma_f32_16x16x32_bf16 v[52:55], v[142:145], v[202:205], v[52:55]
	v_mfma_f32_16x16x32_bf16 v[48:51], v[150:153], v[202:205], v[48:51]
	v_mfma_f32_16x16x32_bf16 v[28:31], v[142:145], v[210:213], v[28:31]
	v_mfma_f32_16x16x32_bf16 v[24:27], v[150:153], v[210:213], v[24:27]
	v_mfma_f32_16x16x32_bf16 v[20:23], v[142:145], v[218:221], v[20:23]
	v_mfma_f32_16x16x32_bf16 v[16:19], v[150:153], v[218:221], v[16:19]
	v_mfma_f32_16x16x32_bf16 v[44:47], v[154:157], v[190:193], v[44:47]
	v_mfma_f32_16x16x32_bf16 v[40:43], v[168:171], v[190:193], v[40:43]
	v_mfma_f32_16x16x32_bf16 v[36:39], v[154:157], v[198:201], v[36:39]
	v_mfma_f32_16x16x32_bf16 v[32:35], v[168:171], v[198:201], v[32:35]
	v_mfma_f32_16x16x32_bf16 v[12:15], v[154:157], v[206:209], v[12:15]
	v_mfma_f32_16x16x32_bf16 v[8:11], v[168:171], v[206:209], v[8:11]
	v_mfma_f32_16x16x32_bf16 v[4:7], v[154:157], v[214:217], v[4:7]
	v_mfma_f32_16x16x32_bf16 v[0:3], v[168:171], v[214:217], v[0:3]
	v_mfma_f32_16x16x32_bf16 v[44:47], v[164:167], v[194:197], v[44:47]
	v_mfma_f32_16x16x32_bf16 v[40:43], v[172:175], v[194:197], v[40:43]
	v_mfma_f32_16x16x32_bf16 v[36:39], v[164:167], v[202:205], v[36:39]
	v_mfma_f32_16x16x32_bf16 v[32:35], v[172:175], v[202:205], v[32:35]
	v_mfma_f32_16x16x32_bf16 v[12:15], v[164:167], v[210:213], v[12:15]
	v_mfma_f32_16x16x32_bf16 v[8:11], v[172:175], v[210:213], v[8:11]
	v_mfma_f32_16x16x32_bf16 v[4:7], v[164:167], v[218:221], v[4:7]
	v_mfma_f32_16x16x32_bf16 v[0:3], v[172:175], v[218:221], v[0:3]
	s_barrier
	s_add_i32 s86, s86, 2
	s_add_u32 s82, s82, 0x100
	s_addc_u32 s83, s83, 0
	s_cmp_gt_u32 s86, 41
	s_mov_b64 s[42:43], s[44:45]
	s_cbranch_scc0 .LBB0_327
	s_setprio 0
	s_and_b64 vcc, exec, s[36:37]
	s_cbranch_vccz .LBB0_330
	s_barrier

.LBB0_461:
	s_ashr_i32 s35, s34, 31
	s_lshl_b64 s[38:39], s[34:35], 19
	s_add_u32 s38, s52, s38
	s_addc_u32 s39, s74, s39
	s_and_b64 s[46:47], s[40:41], exec
	s_cselect_b32 s35, s39, s71
	s_cselect_b32 s86, s38, s70
	s_ashr_i32 s37, s36, 31
	s_lshl_b64 s[46:47], s[36:37], 19
	s_add_u32 s46, s75, s46
	s_addc_u32 s47, s76, s47
	s_and_b64 s[72:73], s[40:41], exec
	s_cselect_b32 s37, s47, s69
	s_cselect_b32 s87, s46, s68
	s_add_u32 vcc_lo, s68, 0x100
	s_addc_u32 vcc_hi, s69, 0
	s_add_u32 s68, s70, 0x40080
	v_mov_b32_e32 v0, 0
	s_addc_u32 s69, s71, 0
	s_mov_b32 s90, -2
	v_mov_b32_e32 v1, v0
	v_mov_b32_e32 v2, v0
	v_mov_b32_e32 v3, v0
	v_mov_b32_e32 v4, v0
	v_mov_b32_e32 v5, v0
	v_mov_b32_e32 v6, v0
	v_mov_b32_e32 v7, v0
	v_mov_b32_e32 v16, v0
	v_mov_b32_e32 v17, v0
	v_mov_b32_e32 v18, v0
	v_mov_b32_e32 v19, v0
	v_mov_b32_e32 v20, v0
	v_mov_b32_e32 v21, v0
	v_mov_b32_e32 v22, v0
	v_mov_b32_e32 v23, v0
	v_mov_b32_e32 v32, v0
	v_mov_b32_e32 v33, v0
	v_mov_b32_e32 v34, v0
	v_mov_b32_e32 v35, v0
	v_mov_b32_e32 v36, v0
	v_mov_b32_e32 v37, v0
	v_mov_b32_e32 v38, v0
	v_mov_b32_e32 v39, v0
	v_mov_b32_e32 v48, v0
	v_mov_b32_e32 v49, v0
	v_mov_b32_e32 v50, v0
	v_mov_b32_e32 v51, v0
	v_mov_b32_e32 v52, v0
	v_mov_b32_e32 v53, v0
	v_mov_b32_e32 v54, v0
	v_mov_b32_e32 v55, v0
	v_mov_b32_e32 v8, v0
	v_mov_b32_e32 v9, v0
	v_mov_b32_e32 v10, v0
	v_mov_b32_e32 v11, v0
	v_mov_b32_e32 v12, v0
	v_mov_b32_e32 v13, v0
	v_mov_b32_e32 v14, v0
	v_mov_b32_e32 v15, v0
	v_mov_b32_e32 v24, v0
	v_mov_b32_e32 v25, v0
	v_mov_b32_e32 v26, v0
	v_mov_b32_e32 v27, v0
	v_mov_b32_e32 v28, v0
	v_mov_b32_e32 v29, v0
	v_mov_b32_e32 v30, v0
	v_mov_b32_e32 v31, v0
	v_mov_b32_e32 v40, v0
	v_mov_b32_e32 v41, v0
	v_mov_b32_e32 v42, v0
	v_mov_b32_e32 v43, v0
	v_mov_b32_e32 v44, v0
	v_mov_b32_e32 v45, v0
	v_mov_b32_e32 v46, v0
	v_mov_b32_e32 v47, v0
	v_mov_b32_e32 v56, v0
	v_mov_b32_e32 v57, v0
	v_mov_b32_e32 v58, v0
	v_mov_b32_e32 v59, v0
	v_mov_b32_e32 v60, v0
	v_mov_b32_e32 v61, v0
	v_mov_b32_e32 v62, v0
	v_mov_b32_e32 v63, v0
	v_mov_b32_e32 v64, v0
	v_mov_b32_e32 v65, v0
	v_mov_b32_e32 v66, v0
	v_mov_b32_e32 v67, v0
	v_mov_b32_e32 v68, v0
	v_mov_b32_e32 v69, v0
	v_mov_b32_e32 v70, v0
	v_mov_b32_e32 v71, v0
	v_mov_b32_e32 v80, v0
	v_mov_b32_e32 v81, v0
	v_mov_b32_e32 v82, v0
	v_mov_b32_e32 v83, v0
	v_mov_b32_e32 v84, v0
	v_mov_b32_e32 v85, v0
	v_mov_b32_e32 v86, v0
	v_mov_b32_e32 v87, v0
	v_mov_b32_e32 v96, v0
	v_mov_b32_e32 v97, v0
	v_mov_b32_e32 v98, v0
	v_mov_b32_e32 v99, v0
	v_mov_b32_e32 v100, v0
	v_mov_b32_e32 v101, v0
	v_mov_b32_e32 v102, v0
	v_mov_b32_e32 v103, v0
	v_mov_b32_e32 v112, v0
	v_mov_b32_e32 v113, v0
	v_mov_b32_e32 v114, v0
	v_mov_b32_e32 v115, v0
	v_mov_b32_e32 v116, v0
	v_mov_b32_e32 v117, v0
	v_mov_b32_e32 v118, v0
	v_mov_b32_e32 v119, v0
	v_mov_b32_e32 v72, v0
	v_mov_b32_e32 v73, v0
	v_mov_b32_e32 v74, v0
	v_mov_b32_e32 v75, v0
	v_mov_b32_e32 v76, v0
	v_mov_b32_e32 v77, v0
	v_mov_b32_e32 v78, v0
	v_mov_b32_e32 v79, v0
	v_mov_b32_e32 v88, v0
	v_mov_b32_e32 v89, v0
	v_mov_b32_e32 v90, v0
	v_mov_b32_e32 v91, v0
	v_mov_b32_e32 v92, v0
	v_mov_b32_e32 v93, v0
	v_mov_b32_e32 v94, v0
	v_mov_b32_e32 v95, v0
	v_mov_b32_e32 v104, v0
	v_mov_b32_e32 v105, v0
	v_mov_b32_e32 v106, v0
	v_mov_b32_e32 v107, v0
	v_mov_b32_e32 v108, v0
	v_mov_b32_e32 v109, v0
	v_mov_b32_e32 v110, v0
	v_mov_b32_e32 v111, v0
	v_mov_b32_e32 v120, v0
	v_mov_b32_e32 v121, v0
	v_mov_b32_e32 v122, v0
	v_mov_b32_e32 v123, v0
	v_mov_b32_e32 v124, v0
	v_mov_b32_e32 v125, v0
	v_mov_b32_e32 v126, v0
	v_mov_b32_e32 v127, v0
	v_readfirstlane_b32 s70, v226
	s_nop 3
	s_bitcmp1_b32 s70, 8
	s_cbranch_scc0 .Lpr_462
	s_setprio 1
.Lpr_462:
.LBB0_462:
	s_add_u32 s70, s68, 0xfffc0080
	s_addc_u32 s71, s69, -1
	s_add_i32 s91, 0, 0x10000
	s_cmp_eq_u32 s90, 12
	s_cselect_b32 s73, s35, s71
	s_cselect_b32 s72, s86, s70
	s_cselect_b32 s71, s37, vcc_hi
	s_cselect_b32 s70, s87, vcc_lo
	s_add_i32 s48, 0, 0x14000
	v_add_u32_e32 v152, s91, v163
	v_add_u32_e32 v160, s48, v163
	ds_read_b128 v[140:143], v152
	ds_read_b128 v[144:147], v152 offset:1024
	ds_read_b128 v[148:151], v152 offset:2048
	ds_read_b128 v[152:155], v152 offset:3072
	ds_read_b128 v[156:159], v160
	ds_read_b128 v[170:173], v160 offset:1024
	ds_read_b128 v[190:193], v160 offset:2048
	ds_read_b128 v[194:197], v160 offset:3072
	v_lshl_add_u64 v[160:161], s[68:69], 0, v[138:139]
	s_add_i32 m0, s78, 0xc000
	ds_read_b128 v[198:201], v167
	ds_read_b128 v[202:205], v167 offset:1024
	ds_read_b128 v[206:209], v167 offset:2048
	ds_read_b128 v[210:213], v167 offset:3072
	ds_read_b128 v[214:217], v167 offset:4096
	ds_read_b128 v[218:221], v167 offset:5120
	ds_read_b128 v[222:225], v167 offset:6144
	ds_read_b128 v[234:237], v167 offset:7168
	global_load_lds_dwordx4 v[160:161], off
	v_lshl_add_u64 v[160:161], s[68:69], 0, v[136:137]
	s_add_i32 m0, s78, 0xe000
	s_nop 0
	global_load_lds_dwordx4 v[160:161], off
	s_waitcnt vmcnt(8)
	s_waitcnt lgkmcnt(0)
	s_barrier
	s_waitcnt lgkmcnt(0)
	v_mfma_f32_16x16x32_bf16 v[124:127], v[140:143], v[198:201], v[124:127]
	v_mfma_f32_16x16x32_bf16 v[120:123], v[148:151], v[198:201], v[120:123]
	v_mfma_f32_16x16x32_bf16 v[108:111], v[140:143], v[206:209], v[108:111]
	v_mfma_f32_16x16x32_bf16 v[104:107], v[148:151], v[206:209], v[104:107]
	v_mfma_f32_16x16x32_bf16 v[92:95], v[140:143], v[214:217], v[92:95]
	v_mfma_f32_16x16x32_bf16 v[88:91], v[148:151], v[214:217], v[88:91]
	v_mfma_f32_16x16x32_bf16 v[76:79], v[140:143], v[222:225], v[76:79]
	v_mfma_f32_16x16x32_bf16 v[72:75], v[148:151], v[222:225], v[72:75]
	v_mfma_f32_16x16x32_bf16 v[124:127], v[144:147], v[202:205], v[124:127]
	v_mfma_f32_16x16x32_bf16 v[120:123], v[152:155], v[202:205], v[120:123]
	v_mfma_f32_16x16x32_bf16 v[108:111], v[144:147], v[210:213], v[108:111]
	v_mfma_f32_16x16x32_bf16 v[104:107], v[152:155], v[210:213], v[104:107]
	v_mfma_f32_16x16x32_bf16 v[92:95], v[144:147], v[218:221], v[92:95]
	v_mfma_f32_16x16x32_bf16 v[88:91], v[152:155], v[218:221], v[88:91]
	v_mfma_f32_16x16x32_bf16 v[76:79], v[144:147], v[234:237], v[76:79]
	v_mfma_f32_16x16x32_bf16 v[72:75], v[152:155], v[234:237], v[72:75]
	v_mfma_f32_16x16x32_bf16 v[116:119], v[156:159], v[198:201], v[116:119]
	v_mfma_f32_16x16x32_bf16 v[112:115], v[190:193], v[198:201], v[112:115]
	v_mfma_f32_16x16x32_bf16 v[100:103], v[156:159], v[206:209], v[100:103]
	v_mfma_f32_16x16x32_bf16 v[96:99], v[190:193], v[206:209], v[96:99]
	v_mfma_f32_16x16x32_bf16 v[84:87], v[156:159], v[214:217], v[84:87]
	v_mfma_f32_16x16x32_bf16 v[80:83], v[190:193], v[214:217], v[80:83]
	v_mfma_f32_16x16x32_bf16 v[68:71], v[156:159], v[222:225], v[68:71]
	v_mfma_f32_16x16x32_bf16 v[64:67], v[190:193], v[222:225], v[64:67]
	v_mfma_f32_16x16x32_bf16 v[116:119], v[170:173], v[202:205], v[116:119]
	v_mfma_f32_16x16x32_bf16 v[112:115], v[194:197], v[202:205], v[112:115]
	v_mfma_f32_16x16x32_bf16 v[100:103], v[170:173], v[210:213], v[100:103]
	v_mfma_f32_16x16x32_bf16 v[96:99], v[194:197], v[210:213], v[96:99]
	v_mfma_f32_16x16x32_bf16 v[84:87], v[170:173], v[218:221], v[84:87]
	v_mfma_f32_16x16x32_bf16 v[80:83], v[194:197], v[218:221], v[80:83]
	v_mfma_f32_16x16x32_bf16 v[68:71], v[170:173], v[234:237], v[68:71]
	v_mfma_f32_16x16x32_bf16 v[64:67], v[194:197], v[234:237], v[64:67]
	s_barrier
	s_add_i32 s49, s91, s77
	v_lshl_add_u64 v[160:161], s[70:71], 0, v[132:133]
	s_mov_b32 m0, s49
	ds_read_b128 v[198:201], v167 offset:16384
	ds_read_b128 v[202:205], v167 offset:17408
	ds_read_b128 v[206:209], v167 offset:18432
	ds_read_b128 v[210:213], v167 offset:19456
	ds_read_b128 v[214:217], v167 offset:20480
	ds_read_b128 v[218:221], v167 offset:21504
	ds_read_b128 v[222:225], v167 offset:22528
	ds_read_b128 v[234:237], v167 offset:23552
	global_load_lds_dwordx4 v[160:161], off
	s_add_i32 m0, s49, 0x2000
	s_add_u32 s96, s70, 0x40000
	v_lshl_add_u64 v[174:175], s[70:71], 0, v[128:129]
	s_addc_u32 s97, s71, 0
	s_add_i32 s48, s48, s77
	global_load_lds_dwordx4 v[174:175], off
	v_lshl_add_u64 v[238:239], s[96:97], 0, v[132:133]
	s_mov_b32 m0, s48
	v_lshl_add_u64 v[240:241], s[72:73], 0, v[130:131]
	global_load_lds_dwordx4 v[238:239], off
	v_lshl_add_u64 v[238:239], s[96:97], 0, v[128:129]
	s_add_i32 m0, s48, 0x2000
	s_nop 0
	global_load_lds_dwordx4 v[238:239], off
	v_lshl_add_u64 v[238:239], s[72:73], 0, v[134:135]
	s_mov_b32 m0, s78
	s_nop 0
	global_load_lds_dwordx4 v[238:239], off
	s_mov_b32 m0, s79
	s_nop 0
	global_load_lds_dwordx4 v[240:241], off
	s_waitcnt vmcnt(8)
	s_waitcnt lgkmcnt(0)
	s_barrier
	s_waitcnt lgkmcnt(0)
	v_mfma_f32_16x16x32_bf16 v[60:63], v[140:143], v[198:201], v[60:63]
	v_mfma_f32_16x16x32_bf16 v[56:59], v[148:151], v[198:201], v[56:59]
	v_mfma_f32_16x16x32_bf16 v[44:47], v[140:143], v[206:209], v[44:47]
	v_mfma_f32_16x16x32_bf16 v[40:43], v[148:151], v[206:209], v[40:43]
	v_mfma_f32_16x16x32_bf16 v[28:31], v[140:143], v[214:217], v[28:31]
	v_mfma_f32_16x16x32_bf16 v[24:27], v[148:151], v[214:217], v[24:27]
	v_mfma_f32_16x16x32_bf16 v[12:15], v[140:143], v[222:225], v[12:15]
	v_mfma_f32_16x16x32_bf16 v[8:11], v[148:151], v[222:225], v[8:11]
	v_mfma_f32_16x16x32_bf16 v[60:63], v[144:147], v[202:205], v[60:63]
	v_mfma_f32_16x16x32_bf16 v[56:59], v[152:155], v[202:205], v[56:59]
	v_mfma_f32_16x16x32_bf16 v[44:47], v[144:147], v[210:213], v[44:47]
	v_mfma_f32_16x16x32_bf16 v[40:43], v[152:155], v[210:213], v[40:43]
	v_mfma_f32_16x16x32_bf16 v[28:31], v[144:147], v[218:221], v[28:31]
	v_mfma_f32_16x16x32_bf16 v[24:27], v[152:155], v[218:221], v[24:27]
	v_mfma_f32_16x16x32_bf16 v[12:15], v[144:147], v[234:237], v[12:15]
	v_mfma_f32_16x16x32_bf16 v[8:11], v[152:155], v[234:237], v[8:11]
	v_mfma_f32_16x16x32_bf16 v[52:55], v[156:159], v[198:201], v[52:55]
	v_mfma_f32_16x16x32_bf16 v[48:51], v[190:193], v[198:201], v[48:51]
	v_mfma_f32_16x16x32_bf16 v[36:39], v[156:159], v[206:209], v[36:39]
	v_mfma_f32_16x16x32_bf16 v[32:35], v[190:193], v[206:209], v[32:35]
	v_mfma_f32_16x16x32_bf16 v[20:23], v[156:159], v[214:217], v[20:23]
	v_mfma_f32_16x16x32_bf16 v[16:19], v[190:193], v[214:217], v[16:19]
	v_mfma_f32_16x16x32_bf16 v[4:7], v[156:159], v[222:225], v[4:7]
	v_mfma_f32_16x16x32_bf16 v[0:3], v[190:193], v[222:225], v[0:3]
	v_mfma_f32_16x16x32_bf16 v[52:55], v[170:173], v[202:205], v[52:55]
	v_mfma_f32_16x16x32_bf16 v[48:51], v[194:197], v[202:205], v[48:51]
	v_mfma_f32_16x16x32_bf16 v[36:39], v[170:173], v[210:213], v[36:39]
	v_mfma_f32_16x16x32_bf16 v[32:35], v[194:197], v[210:213], v[32:35]
	v_mfma_f32_16x16x32_bf16 v[20:23], v[170:173], v[218:221], v[20:23]
	v_mfma_f32_16x16x32_bf16 v[16:19], v[194:197], v[218:221], v[16:19]
	v_mfma_f32_16x16x32_bf16 v[4:7], v[170:173], v[234:237], v[4:7]
	v_mfma_f32_16x16x32_bf16 v[0:3], v[194:197], v[234:237], v[0:3]
	s_barrier
	s_add_i32 s48, 0, 0x18000
	s_add_i32 s49, 0, 0x1c000
	v_add_u32_e32 v152, s48, v163
	v_add_u32_e32 v169, s49, v163
	ds_read_b128 v[140:143], v152
	ds_read_b128 v[144:147], v152 offset:1024
	ds_read_b128 v[148:151], v152 offset:2048
	ds_read_b128 v[152:155], v152 offset:3072
	ds_read_b128 v[156:159], v169
	ds_read_b128 v[170:173], v169 offset:1024
	ds_read_b128 v[190:193], v169 offset:2048
	ds_read_b128 v[194:197], v169 offset:3072
	s_add_u32 s72, s72, 0x40000
	s_addc_u32 s73, s73, 0
	s_mov_b32 m0, s80
	v_lshl_add_u64 v[242:243], s[72:73], 0, v[134:135]
	ds_read_b128 v[198:201], v167 offset:32768
	ds_read_b128 v[202:205], v167 offset:33792
	ds_read_b128 v[206:209], v167 offset:34816
	ds_read_b128 v[210:213], v167 offset:35840
	ds_read_b128 v[214:217], v167 offset:36864
	ds_read_b128 v[218:221], v167 offset:37888
	ds_read_b128 v[222:225], v167 offset:38912
	ds_read_b128 v[234:237], v167 offset:39936
	global_load_lds_dwordx4 v[242:243], off
	v_lshl_add_u64 v[242:243], s[72:73], 0, v[130:131]
	s_mov_b32 m0, s81
	s_nop 0
	global_load_lds_dwordx4 v[242:243], off
	s_waitcnt vmcnt(8)
	s_waitcnt lgkmcnt(0)
	s_barrier
	s_waitcnt lgkmcnt(0)
	v_mfma_f32_16x16x32_bf16 v[124:127], v[140:143], v[198:201], v[124:127]
	v_mfma_f32_16x16x32_bf16 v[120:123], v[148:151], v[198:201], v[120:123]
	v_mfma_f32_16x16x32_bf16 v[108:111], v[140:143], v[206:209], v[108:111]
	v_mfma_f32_16x16x32_bf16 v[104:107], v[148:151], v[206:209], v[104:107]
	v_mfma_f32_16x16x32_bf16 v[92:95], v[140:143], v[214:217], v[92:95]
	v_mfma_f32_16x16x32_bf16 v[88:91], v[148:151], v[214:217], v[88:91]
	v_mfma_f32_16x16x32_bf16 v[76:79], v[140:143], v[222:225], v[76:79]
	v_mfma_f32_16x16x32_bf16 v[72:75], v[148:151], v[222:225], v[72:75]
	v_mfma_f32_16x16x32_bf16 v[124:127], v[144:147], v[202:205], v[124:127]
	v_mfma_f32_16x16x32_bf16 v[120:123], v[152:155], v[202:205], v[120:123]
	v_mfma_f32_16x16x32_bf16 v[108:111], v[144:147], v[210:213], v[108:111]
	v_mfma_f32_16x16x32_bf16 v[104:107], v[152:155], v[210:213], v[104:107]
	v_mfma_f32_16x16x32_bf16 v[92:95], v[144:147], v[218:221], v[92:95]
	v_mfma_f32_16x16x32_bf16 v[88:91], v[152:155], v[218:221], v[88:91]
	v_mfma_f32_16x16x32_bf16 v[76:79], v[144:147], v[234:237], v[76:79]
	v_mfma_f32_16x16x32_bf16 v[72:75], v[152:155], v[234:237], v[72:75]
	v_mfma_f32_16x16x32_bf16 v[116:119], v[156:159], v[198:201], v[116:119]
	v_mfma_f32_16x16x32_bf16 v[112:115], v[190:193], v[198:201], v[112:115]
	v_mfma_f32_16x16x32_bf16 v[100:103], v[156:159], v[206:209], v[100:103]
	v_mfma_f32_16x16x32_bf16 v[96:99], v[190:193], v[206:209], v[96:99]
	v_mfma_f32_16x16x32_bf16 v[84:87], v[156:159], v[214:217], v[84:87]
	v_mfma_f32_16x16x32_bf16 v[80:83], v[190:193], v[214:217], v[80:83]
	v_mfma_f32_16x16x32_bf16 v[68:71], v[156:159], v[222:225], v[68:71]
	v_mfma_f32_16x16x32_bf16 v[64:67], v[190:193], v[222:225], v[64:67]
	v_mfma_f32_16x16x32_bf16 v[116:119], v[170:173], v[202:205], v[116:119]
	v_mfma_f32_16x16x32_bf16 v[112:115], v[194:197], v[202:205], v[112:115]
	v_mfma_f32_16x16x32_bf16 v[100:103], v[170:173], v[210:213], v[100:103]
	v_mfma_f32_16x16x32_bf16 v[96:99], v[194:197], v[210:213], v[96:99]
	v_mfma_f32_16x16x32_bf16 v[84:87], v[170:173], v[218:221], v[84:87]
	v_mfma_f32_16x16x32_bf16 v[80:83], v[194:197], v[218:221], v[80:83]
	v_mfma_f32_16x16x32_bf16 v[68:71], v[170:173], v[234:237], v[68:71]
	v_mfma_f32_16x16x32_bf16 v[64:67], v[194:197], v[234:237], v[64:67]
	s_barrier
	s_add_i32 s48, s48, s77
	v_lshl_add_u64 v[160:161], v[160:161], 0, s[24:25]
	s_mov_b32 m0, s48
	ds_read_b128 v[198:201], v167 offset:49152
	ds_read_b128 v[202:205], v167 offset:50176
	ds_read_b128 v[206:209], v167 offset:51200
	ds_read_b128 v[210:213], v167 offset:52224
	ds_read_b128 v[214:217], v167 offset:53248
	ds_read_b128 v[218:221], v167 offset:54272
	ds_read_b128 v[222:225], v167 offset:55296
	ds_read_b128 v[234:237], v167 offset:56320
	global_load_lds_dwordx4 v[160:161], off
	s_add_i32 m0, s48, 0x2000
	s_add_u32 s70, s70, 0x40080
	v_lshl_add_u64 v[160:161], v[174:175], 0, s[24:25]
	s_addc_u32 s71, s71, 0
	s_add_i32 s48, s49, s77
	global_load_lds_dwordx4 v[160:161], off
	v_lshl_add_u64 v[160:161], s[70:71], 0, v[132:133]
	s_mov_b32 m0, s48
	s_nop 0
	global_load_lds_dwordx4 v[160:161], off
	v_lshl_add_u64 v[160:161], s[70:71], 0, v[128:129]
	s_add_i32 m0, s48, 0x2000
	s_nop 0
	global_load_lds_dwordx4 v[160:161], off
	v_lshl_add_u64 v[160:161], v[238:239], 0, s[24:25]
	s_mov_b32 m0, s59
	s_nop 0
	global_load_lds_dwordx4 v[160:161], off
	v_lshl_add_u64 v[160:161], v[240:241], 0, s[24:25]
	s_mov_b32 m0, s60
	s_nop 0
	global_load_lds_dwordx4 v[160:161], off
	s_waitcnt vmcnt(8)
	s_waitcnt lgkmcnt(0)
	s_barrier
	s_waitcnt lgkmcnt(0)
	v_mfma_f32_16x16x32_bf16 v[60:63], v[140:143], v[198:201], v[60:63]
	v_mfma_f32_16x16x32_bf16 v[56:59], v[148:151], v[198:201], v[56:59]
	v_mfma_f32_16x16x32_bf16 v[44:47], v[140:143], v[206:209], v[44:47]
	v_mfma_f32_16x16x32_bf16 v[40:43], v[148:151], v[206:209], v[40:43]
	v_mfma_f32_16x16x32_bf16 v[28:31], v[140:143], v[214:217], v[28:31]
	v_mfma_f32_16x16x32_bf16 v[24:27], v[148:151], v[214:217], v[24:27]
	v_mfma_f32_16x16x32_bf16 v[12:15], v[140:143], v[222:225], v[12:15]
	v_mfma_f32_16x16x32_bf16 v[8:11], v[148:151], v[222:225], v[8:11]
	v_mfma_f32_16x16x32_bf16 v[60:63], v[144:147], v[202:205], v[60:63]
	v_mfma_f32_16x16x32_bf16 v[56:59], v[152:155], v[202:205], v[56:59]
	v_mfma_f32_16x16x32_bf16 v[44:47], v[144:147], v[210:213], v[44:47]
	v_mfma_f32_16x16x32_bf16 v[40:43], v[152:155], v[210:213], v[40:43]
	v_mfma_f32_16x16x32_bf16 v[28:31], v[144:147], v[218:221], v[28:31]
	v_mfma_f32_16x16x32_bf16 v[24:27], v[152:155], v[218:221], v[24:27]
	v_mfma_f32_16x16x32_bf16 v[12:15], v[144:147], v[234:237], v[12:15]
	v_mfma_f32_16x16x32_bf16 v[8:11], v[152:155], v[234:237], v[8:11]
	v_mfma_f32_16x16x32_bf16 v[52:55], v[156:159], v[198:201], v[52:55]
	v_mfma_f32_16x16x32_bf16 v[48:51], v[190:193], v[198:201], v[48:51]
	v_mfma_f32_16x16x32_bf16 v[36:39], v[156:159], v[206:209], v[36:39]
	v_mfma_f32_16x16x32_bf16 v[32:35], v[190:193], v[206:209], v[32:35]
	v_mfma_f32_16x16x32_bf16 v[20:23], v[156:159], v[214:217], v[20:23]
	v_mfma_f32_16x16x32_bf16 v[16:19], v[190:193], v[214:217], v[16:19]
	v_mfma_f32_16x16x32_bf16 v[4:7], v[156:159], v[222:225], v[4:7]
	v_mfma_f32_16x16x32_bf16 v[0:3], v[190:193], v[222:225], v[0:3]
	v_mfma_f32_16x16x32_bf16 v[52:55], v[170:173], v[202:205], v[52:55]
	v_mfma_f32_16x16x32_bf16 v[48:51], v[194:197], v[202:205], v[48:51]
	v_mfma_f32_16x16x32_bf16 v[36:39], v[170:173], v[210:213], v[36:39]
	v_mfma_f32_16x16x32_bf16 v[32:35], v[194:197], v[210:213], v[32:35]
	v_mfma_f32_16x16x32_bf16 v[20:23], v[170:173], v[218:221], v[20:23]
	v_mfma_f32_16x16x32_bf16 v[16:19], v[194:197], v[218:221], v[16:19]
	v_mfma_f32_16x16x32_bf16 v[4:7], v[170:173], v[234:237], v[4:7]
	v_mfma_f32_16x16x32_bf16 v[0:3], v[194:197], v[234:237], v[0:3]
	s_barrier
	s_add_i32 s90, s90, 2
	s_add_u32 vcc_lo, vcc_lo, 0x100
	s_addc_u32 vcc_hi, vcc_hi, 0
	s_add_u32 s68, s68, 0x100
	s_addc_u32 s69, s69, 0
	s_cmp_gt_u32 s90, 13
	s_cbranch_scc0 .LBB0_462
	s_setprio 0
	s_and_b64 vcc, exec, s[42:43]
	s_cbranch_vccz .LBB0_465
	s_barrier

.LBB0_481:
	s_ashr_i32 s39, s38, 31
	s_lshl_b64 s[46:47], s[38:39], 19
	s_add_u32 s46, s3, s46
	s_addc_u32 s47, s22, s47
	s_and_b64 s[68:69], s[42:43], exec
	s_cselect_b32 s39, s47, s73
	s_cselect_b32 s87, s46, s72
	s_ashr_i32 s37, s36, 31
	s_lshl_b64 s[68:69], s[36:37], 19
	s_add_u32 s68, s58, s68
	s_addc_u32 s69, s59, s69
	s_and_b64 s[74:75], s[42:43], exec
	s_cselect_b32 s37, s69, s71
	s_cselect_b32 vcc_lo, s68, s70
	s_add_u32 vcc_hi, s70, 0x100
	s_addc_u32 s90, s71, 0
	s_add_u32 s70, s72, 0x40080
	v_mov_b32_e32 v0, 0
	s_addc_u32 s71, s73, 0
	s_mov_b32 s91, -2
	v_mov_b32_e32 v1, v0
	v_mov_b32_e32 v2, v0
	v_mov_b32_e32 v3, v0
	v_mov_b32_e32 v4, v0
	v_mov_b32_e32 v5, v0
	v_mov_b32_e32 v6, v0
	v_mov_b32_e32 v7, v0
	v_mov_b32_e32 v8, v0
	v_mov_b32_e32 v9, v0
	v_mov_b32_e32 v10, v0
	v_mov_b32_e32 v11, v0
	v_mov_b32_e32 v12, v0
	v_mov_b32_e32 v13, v0
	v_mov_b32_e32 v14, v0
	v_mov_b32_e32 v15, v0
	v_mov_b32_e32 v24, v0
	v_mov_b32_e32 v25, v0
	v_mov_b32_e32 v26, v0
	v_mov_b32_e32 v27, v0
	v_mov_b32_e32 v28, v0
	v_mov_b32_e32 v29, v0
	v_mov_b32_e32 v30, v0
	v_mov_b32_e32 v31, v0
	v_mov_b32_e32 v40, v0
	v_mov_b32_e32 v41, v0
	v_mov_b32_e32 v42, v0
	v_mov_b32_e32 v43, v0
	v_mov_b32_e32 v44, v0
	v_mov_b32_e32 v45, v0
	v_mov_b32_e32 v46, v0
	v_mov_b32_e32 v47, v0
	v_mov_b32_e32 v16, v0
	v_mov_b32_e32 v17, v0
	v_mov_b32_e32 v18, v0
	v_mov_b32_e32 v19, v0
	v_mov_b32_e32 v20, v0
	v_mov_b32_e32 v21, v0
	v_mov_b32_e32 v22, v0
	v_mov_b32_e32 v23, v0
	v_mov_b32_e32 v32, v0
	v_mov_b32_e32 v33, v0
	v_mov_b32_e32 v34, v0
	v_mov_b32_e32 v35, v0
	v_mov_b32_e32 v36, v0
	v_mov_b32_e32 v37, v0
	v_mov_b32_e32 v38, v0
	v_mov_b32_e32 v39, v0
	v_mov_b32_e32 v48, v0
	v_mov_b32_e32 v49, v0
	v_mov_b32_e32 v50, v0
	v_mov_b32_e32 v51, v0
	v_mov_b32_e32 v52, v0
	v_mov_b32_e32 v53, v0
	v_mov_b32_e32 v54, v0
	v_mov_b32_e32 v55, v0
	v_mov_b32_e32 v56, v0
	v_mov_b32_e32 v57, v0
	v_mov_b32_e32 v58, v0
	v_mov_b32_e32 v59, v0
	v_mov_b32_e32 v60, v0
	v_mov_b32_e32 v61, v0
	v_mov_b32_e32 v62, v0
	v_mov_b32_e32 v63, v0
	v_mov_b32_e32 v64, v0
	v_mov_b32_e32 v65, v0
	v_mov_b32_e32 v66, v0
	v_mov_b32_e32 v67, v0
	v_mov_b32_e32 v68, v0
	v_mov_b32_e32 v69, v0
	v_mov_b32_e32 v70, v0
	v_mov_b32_e32 v71, v0
	v_mov_b32_e32 v72, v0
	v_mov_b32_e32 v73, v0
	v_mov_b32_e32 v74, v0
	v_mov_b32_e32 v75, v0
	v_mov_b32_e32 v76, v0
	v_mov_b32_e32 v77, v0
	v_mov_b32_e32 v78, v0
	v_mov_b32_e32 v79, v0
	v_mov_b32_e32 v88, v0
	v_mov_b32_e32 v89, v0
	v_mov_b32_e32 v90, v0
	v_mov_b32_e32 v91, v0
	v_mov_b32_e32 v92, v0
	v_mov_b32_e32 v93, v0
	v_mov_b32_e32 v94, v0
	v_mov_b32_e32 v95, v0
	v_mov_b32_e32 v104, v0
	v_mov_b32_e32 v105, v0
	v_mov_b32_e32 v106, v0
	v_mov_b32_e32 v107, v0
	v_mov_b32_e32 v108, v0
	v_mov_b32_e32 v109, v0
	v_mov_b32_e32 v110, v0
	v_mov_b32_e32 v111, v0
	v_mov_b32_e32 v80, v0
	v_mov_b32_e32 v81, v0
	v_mov_b32_e32 v82, v0
	v_mov_b32_e32 v83, v0
	v_mov_b32_e32 v84, v0
	v_mov_b32_e32 v85, v0
	v_mov_b32_e32 v86, v0
	v_mov_b32_e32 v87, v0
	v_mov_b32_e32 v96, v0
	v_mov_b32_e32 v97, v0
	v_mov_b32_e32 v98, v0
	v_mov_b32_e32 v99, v0
	v_mov_b32_e32 v100, v0
	v_mov_b32_e32 v101, v0
	v_mov_b32_e32 v102, v0
	v_mov_b32_e32 v103, v0
	v_mov_b32_e32 v112, v0
	v_mov_b32_e32 v113, v0
	v_mov_b32_e32 v114, v0
	v_mov_b32_e32 v115, v0
	v_mov_b32_e32 v116, v0
	v_mov_b32_e32 v117, v0
	v_mov_b32_e32 v118, v0
	v_mov_b32_e32 v119, v0
	v_mov_b32_e32 v120, v0
	v_mov_b32_e32 v121, v0
	v_mov_b32_e32 v122, v0
	v_mov_b32_e32 v123, v0
	v_mov_b32_e32 v124, v0
	v_mov_b32_e32 v125, v0
	v_mov_b32_e32 v126, v0
	v_mov_b32_e32 v127, v0
	v_readfirstlane_b32 s48, v226
	s_nop 3
	s_bitcmp1_b32 s48, 8
	s_cbranch_scc0 .Lpr_482
	s_setprio 1
.Lpr_482:
.LBB0_482:
	s_add_u32 s48, s70, 0xfffc0080
	s_addc_u32 s49, s71, -1
	s_add_i32 s96, 0, 0x10000
	s_cmp_eq_u32 s91, 12
	s_cselect_b32 s75, s39, s49
	s_cselect_b32 s74, s87, s48
	s_cselect_b32 s73, s37, s90
	s_cselect_b32 s72, vcc_lo, vcc_hi
	s_add_i32 s48, 0, 0x14000
	v_add_u32_e32 v170, s96, v156
	v_add_u32_e32 v174, s48, v156
	ds_read_b128 v[158:161], v170
	ds_read_b128 v[162:165], v170 offset:1024
	ds_read_b128 v[166:169], v170 offset:2048
	ds_read_b128 v[170:173], v170 offset:3072
	ds_read_b128 v[190:193], v174
	ds_read_b128 v[194:197], v174 offset:1024
	ds_read_b128 v[198:201], v174 offset:2048
	ds_read_b128 v[202:205], v174 offset:3072
	v_lshl_add_u64 v[174:175], s[70:71], 0, v[154:155]
	s_add_i32 m0, s61, 0xc000
	ds_read_b128 v[206:209], v157
	ds_read_b128 v[210:213], v157 offset:1024
	ds_read_b128 v[214:217], v157 offset:2048
	ds_read_b128 v[218:221], v157 offset:3072
	ds_read_b128 v[222:225], v157 offset:4096
	ds_read_b128 v[234:237], v157 offset:5120
	ds_read_b128 v[238:241], v157 offset:6144
	ds_read_b128 v[242:245], v157 offset:7168
	global_load_lds_dwordx4 v[174:175], off
	v_lshl_add_u64 v[174:175], s[70:71], 0, v[152:153]
	s_add_i32 m0, s61, 0xe000
	s_nop 0
	global_load_lds_dwordx4 v[174:175], off
	s_waitcnt vmcnt(8)
	s_waitcnt lgkmcnt(0)
	s_barrier
	s_waitcnt lgkmcnt(0)
	v_mfma_f32_16x16x32_bf16 v[124:127], v[158:161], v[206:209], v[124:127]
	v_mfma_f32_16x16x32_bf16 v[120:123], v[166:169], v[206:209], v[120:123]
	v_mfma_f32_16x16x32_bf16 v[116:119], v[158:161], v[214:217], v[116:119]
	v_mfma_f32_16x16x32_bf16 v[112:115], v[166:169], v[214:217], v[112:115]
	v_mfma_f32_16x16x32_bf16 v[100:103], v[158:161], v[222:225], v[100:103]
	v_mfma_f32_16x16x32_bf16 v[96:99], v[166:169], v[222:225], v[96:99]
	v_mfma_f32_16x16x32_bf16 v[84:87], v[158:161], v[238:241], v[84:87]
	v_mfma_f32_16x16x32_bf16 v[80:83], v[166:169], v[238:241], v[80:83]
	v_mfma_f32_16x16x32_bf16 v[124:127], v[162:165], v[210:213], v[124:127]
	v_mfma_f32_16x16x32_bf16 v[120:123], v[170:173], v[210:213], v[120:123]
	v_mfma_f32_16x16x32_bf16 v[116:119], v[162:165], v[218:221], v[116:119]
	v_mfma_f32_16x16x32_bf16 v[112:115], v[170:173], v[218:221], v[112:115]
	v_mfma_f32_16x16x32_bf16 v[100:103], v[162:165], v[234:237], v[100:103]
	v_mfma_f32_16x16x32_bf16 v[96:99], v[170:173], v[234:237], v[96:99]
	v_mfma_f32_16x16x32_bf16 v[84:87], v[162:165], v[242:245], v[84:87]
	v_mfma_f32_16x16x32_bf16 v[80:83], v[170:173], v[242:245], v[80:83]
	v_mfma_f32_16x16x32_bf16 v[108:111], v[190:193], v[206:209], v[108:111]
	v_mfma_f32_16x16x32_bf16 v[104:107], v[198:201], v[206:209], v[104:107]
	v_mfma_f32_16x16x32_bf16 v[92:95], v[190:193], v[214:217], v[92:95]
	v_mfma_f32_16x16x32_bf16 v[88:91], v[198:201], v[214:217], v[88:91]
	v_mfma_f32_16x16x32_bf16 v[76:79], v[190:193], v[222:225], v[76:79]
	v_mfma_f32_16x16x32_bf16 v[72:75], v[198:201], v[222:225], v[72:75]
	v_mfma_f32_16x16x32_bf16 v[68:71], v[190:193], v[238:241], v[68:71]
	v_mfma_f32_16x16x32_bf16 v[64:67], v[198:201], v[238:241], v[64:67]
	v_mfma_f32_16x16x32_bf16 v[108:111], v[194:197], v[210:213], v[108:111]
	v_mfma_f32_16x16x32_bf16 v[104:107], v[202:205], v[210:213], v[104:107]
	v_mfma_f32_16x16x32_bf16 v[92:95], v[194:197], v[218:221], v[92:95]
	v_mfma_f32_16x16x32_bf16 v[88:91], v[202:205], v[218:221], v[88:91]
	v_mfma_f32_16x16x32_bf16 v[76:79], v[194:197], v[234:237], v[76:79]
	v_mfma_f32_16x16x32_bf16 v[72:75], v[202:205], v[234:237], v[72:75]
	v_mfma_f32_16x16x32_bf16 v[68:71], v[194:197], v[242:245], v[68:71]
	v_mfma_f32_16x16x32_bf16 v[64:67], v[202:205], v[242:245], v[64:67]
	s_barrier
	s_add_i32 s49, s96, s60
	v_lshl_add_u64 v[174:175], s[72:73], 0, v[132:133]
	s_mov_b32 m0, s49
	ds_read_b128 v[206:209], v157 offset:16384
	ds_read_b128 v[210:213], v157 offset:17408
	ds_read_b128 v[214:217], v157 offset:18432
	ds_read_b128 v[218:221], v157 offset:19456
	ds_read_b128 v[222:225], v157 offset:20480
	ds_read_b128 v[234:237], v157 offset:21504
	ds_read_b128 v[238:241], v157 offset:22528
	ds_read_b128 v[242:245], v157 offset:23552
	global_load_lds_dwordx4 v[174:175], off
	s_add_i32 m0, s49, 0x2000
	s_add_u32 s96, s72, 0x40000
	v_lshl_add_u64 v[246:247], s[72:73], 0, v[128:129]
	s_addc_u32 s97, s73, 0
	s_add_i32 s48, s48, s60
	global_load_lds_dwordx4 v[246:247], off
	v_lshl_add_u64 v[248:249], s[96:97], 0, v[132:133]
	s_mov_b32 m0, s48
	v_lshl_add_u64 v[250:251], s[74:75], 0, v[130:131]
	global_load_lds_dwordx4 v[248:249], off
	v_lshl_add_u64 v[248:249], s[96:97], 0, v[128:129]
	s_add_i32 m0, s48, 0x2000
	s_nop 0
	global_load_lds_dwordx4 v[248:249], off
	v_lshl_add_u64 v[248:249], s[74:75], 0, v[134:135]
	s_mov_b32 m0, s61
	s_nop 0
	global_load_lds_dwordx4 v[248:249], off
	s_mov_b32 m0, s62
	s_nop 0
	global_load_lds_dwordx4 v[250:251], off
	s_waitcnt vmcnt(8)
	s_waitcnt lgkmcnt(0)
	s_barrier
	s_waitcnt lgkmcnt(0)
	v_mfma_f32_16x16x32_bf16 v[60:63], v[158:161], v[206:209], v[60:63]
	v_mfma_f32_16x16x32_bf16 v[56:59], v[166:169], v[206:209], v[56:59]
	v_mfma_f32_16x16x32_bf16 v[52:55], v[158:161], v[214:217], v[52:55]
	v_mfma_f32_16x16x32_bf16 v[48:51], v[166:169], v[214:217], v[48:51]
	v_mfma_f32_16x16x32_bf16 v[36:39], v[158:161], v[222:225], v[36:39]
	v_mfma_f32_16x16x32_bf16 v[32:35], v[166:169], v[222:225], v[32:35]
	v_mfma_f32_16x16x32_bf16 v[20:23], v[158:161], v[238:241], v[20:23]
	v_mfma_f32_16x16x32_bf16 v[16:19], v[166:169], v[238:241], v[16:19]
	v_mfma_f32_16x16x32_bf16 v[60:63], v[162:165], v[210:213], v[60:63]
	v_mfma_f32_16x16x32_bf16 v[56:59], v[170:173], v[210:213], v[56:59]
	v_mfma_f32_16x16x32_bf16 v[52:55], v[162:165], v[218:221], v[52:55]
	v_mfma_f32_16x16x32_bf16 v[48:51], v[170:173], v[218:221], v[48:51]
	v_mfma_f32_16x16x32_bf16 v[36:39], v[162:165], v[234:237], v[36:39]
	v_mfma_f32_16x16x32_bf16 v[32:35], v[170:173], v[234:237], v[32:35]
	v_mfma_f32_16x16x32_bf16 v[20:23], v[162:165], v[242:245], v[20:23]
	v_mfma_f32_16x16x32_bf16 v[16:19], v[170:173], v[242:245], v[16:19]
	v_mfma_f32_16x16x32_bf16 v[44:47], v[190:193], v[206:209], v[44:47]
	v_mfma_f32_16x16x32_bf16 v[40:43], v[198:201], v[206:209], v[40:43]
	v_mfma_f32_16x16x32_bf16 v[28:31], v[190:193], v[214:217], v[28:31]
	v_mfma_f32_16x16x32_bf16 v[24:27], v[198:201], v[214:217], v[24:27]
	v_mfma_f32_16x16x32_bf16 v[12:15], v[190:193], v[222:225], v[12:15]
	v_mfma_f32_16x16x32_bf16 v[8:11], v[198:201], v[222:225], v[8:11]
	v_mfma_f32_16x16x32_bf16 v[4:7], v[190:193], v[238:241], v[4:7]
	v_mfma_f32_16x16x32_bf16 v[0:3], v[198:201], v[238:241], v[0:3]
	v_mfma_f32_16x16x32_bf16 v[44:47], v[194:197], v[210:213], v[44:47]
	v_mfma_f32_16x16x32_bf16 v[40:43], v[202:205], v[210:213], v[40:43]
	v_mfma_f32_16x16x32_bf16 v[28:31], v[194:197], v[218:221], v[28:31]
	v_mfma_f32_16x16x32_bf16 v[24:27], v[202:205], v[218:221], v[24:27]
	v_mfma_f32_16x16x32_bf16 v[12:15], v[194:197], v[234:237], v[12:15]
	v_mfma_f32_16x16x32_bf16 v[8:11], v[202:205], v[234:237], v[8:11]
	v_mfma_f32_16x16x32_bf16 v[4:7], v[194:197], v[242:245], v[4:7]
	v_mfma_f32_16x16x32_bf16 v[0:3], v[202:205], v[242:245], v[0:3]
	s_barrier
	s_add_i32 s48, 0, 0x18000
	s_add_i32 s49, 0, 0x1c000
	v_add_u32_e32 v170, s48, v156
	v_add_u32_e32 v186, s49, v156
	ds_read_b128 v[158:161], v170
	ds_read_b128 v[162:165], v170 offset:1024
	ds_read_b128 v[166:169], v170 offset:2048
	ds_read_b128 v[170:173], v170 offset:3072
	ds_read_b128 v[190:193], v186
	ds_read_b128 v[194:197], v186 offset:1024
	ds_read_b128 v[198:201], v186 offset:2048
	ds_read_b128 v[202:205], v186 offset:3072
	s_add_u32 s74, s74, 0x40000
	s_addc_u32 s75, s75, 0
	s_mov_b32 m0, s63
	v_lshl_add_u64 v[186:187], s[74:75], 0, v[134:135]
	ds_read_b128 v[206:209], v157 offset:32768
	ds_read_b128 v[210:213], v157 offset:33792
	ds_read_b128 v[214:217], v157 offset:34816
	ds_read_b128 v[218:221], v157 offset:35840
	ds_read_b128 v[222:225], v157 offset:36864
	ds_read_b128 v[234:237], v157 offset:37888
	ds_read_b128 v[238:241], v157 offset:38912
	ds_read_b128 v[242:245], v157 offset:39936
	global_load_lds_dwordx4 v[186:187], off
	v_lshl_add_u64 v[186:187], s[74:75], 0, v[130:131]
	s_mov_b32 m0, s76
	s_nop 0
	global_load_lds_dwordx4 v[186:187], off
	s_waitcnt vmcnt(8)
	s_waitcnt lgkmcnt(0)
	s_barrier
	s_waitcnt lgkmcnt(0)
	v_mfma_f32_16x16x32_bf16 v[124:127], v[158:161], v[206:209], v[124:127]
	v_mfma_f32_16x16x32_bf16 v[120:123], v[166:169], v[206:209], v[120:123]
	v_mfma_f32_16x16x32_bf16 v[116:119], v[158:161], v[214:217], v[116:119]
	v_mfma_f32_16x16x32_bf16 v[112:115], v[166:169], v[214:217], v[112:115]
	v_mfma_f32_16x16x32_bf16 v[100:103], v[158:161], v[222:225], v[100:103]
	v_mfma_f32_16x16x32_bf16 v[96:99], v[166:169], v[222:225], v[96:99]
	v_mfma_f32_16x16x32_bf16 v[84:87], v[158:161], v[238:241], v[84:87]
	v_mfma_f32_16x16x32_bf16 v[80:83], v[166:169], v[238:241], v[80:83]
	v_mfma_f32_16x16x32_bf16 v[124:127], v[162:165], v[210:213], v[124:127]
	v_mfma_f32_16x16x32_bf16 v[120:123], v[170:173], v[210:213], v[120:123]
	v_mfma_f32_16x16x32_bf16 v[116:119], v[162:165], v[218:221], v[116:119]
	v_mfma_f32_16x16x32_bf16 v[112:115], v[170:173], v[218:221], v[112:115]
	v_mfma_f32_16x16x32_bf16 v[100:103], v[162:165], v[234:237], v[100:103]
	v_mfma_f32_16x16x32_bf16 v[96:99], v[170:173], v[234:237], v[96:99]
	v_mfma_f32_16x16x32_bf16 v[84:87], v[162:165], v[242:245], v[84:87]
	v_mfma_f32_16x16x32_bf16 v[80:83], v[170:173], v[242:245], v[80:83]
	v_mfma_f32_16x16x32_bf16 v[108:111], v[190:193], v[206:209], v[108:111]
	v_mfma_f32_16x16x32_bf16 v[104:107], v[198:201], v[206:209], v[104:107]
	v_mfma_f32_16x16x32_bf16 v[92:95], v[190:193], v[214:217], v[92:95]
	v_mfma_f32_16x16x32_bf16 v[88:91], v[198:201], v[214:217], v[88:91]
	v_mfma_f32_16x16x32_bf16 v[76:79], v[190:193], v[222:225], v[76:79]
	v_mfma_f32_16x16x32_bf16 v[72:75], v[198:201], v[222:225], v[72:75]
	v_mfma_f32_16x16x32_bf16 v[68:71], v[190:193], v[238:241], v[68:71]
	v_mfma_f32_16x16x32_bf16 v[64:67], v[198:201], v[238:241], v[64:67]
	v_mfma_f32_16x16x32_bf16 v[108:111], v[194:197], v[210:213], v[108:111]
	v_mfma_f32_16x16x32_bf16 v[104:107], v[202:205], v[210:213], v[104:107]
	v_mfma_f32_16x16x32_bf16 v[92:95], v[194:197], v[218:221], v[92:95]
	v_mfma_f32_16x16x32_bf16 v[88:91], v[202:205], v[218:221], v[88:91]
	v_mfma_f32_16x16x32_bf16 v[76:79], v[194:197], v[234:237], v[76:79]
	v_mfma_f32_16x16x32_bf16 v[72:75], v[202:205], v[234:237], v[72:75]
	v_mfma_f32_16x16x32_bf16 v[68:71], v[194:197], v[242:245], v[68:71]
	v_mfma_f32_16x16x32_bf16 v[64:67], v[202:205], v[242:245], v[64:67]
	s_barrier
	s_add_i32 s48, s48, s60
	v_lshl_add_u64 v[174:175], v[174:175], 0, s[24:25]
	s_mov_b32 m0, s48
	ds_read_b128 v[206:209], v157 offset:49152
	ds_read_b128 v[210:213], v157 offset:50176
	ds_read_b128 v[214:217], v157 offset:51200
	ds_read_b128 v[218:221], v157 offset:52224
	ds_read_b128 v[222:225], v157 offset:53248
	ds_read_b128 v[234:237], v157 offset:54272
	ds_read_b128 v[238:241], v157 offset:55296
	ds_read_b128 v[242:245], v157 offset:56320
	global_load_lds_dwordx4 v[174:175], off
	s_add_i32 m0, s48, 0x2000
	s_add_u32 s72, s72, 0x40080
	v_lshl_add_u64 v[174:175], v[246:247], 0, s[24:25]
	s_addc_u32 s73, s73, 0
	s_add_i32 s48, s49, s60
	global_load_lds_dwordx4 v[174:175], off
	v_lshl_add_u64 v[174:175], s[72:73], 0, v[132:133]
	s_mov_b32 m0, s48
	s_nop 0
	global_load_lds_dwordx4 v[174:175], off
	v_lshl_add_u64 v[174:175], s[72:73], 0, v[128:129]
	s_add_i32 m0, s48, 0x2000
	s_nop 0
	global_load_lds_dwordx4 v[174:175], off
	v_lshl_add_u64 v[174:175], v[248:249], 0, s[24:25]
	s_mov_b32 m0, s79
	s_nop 0
	global_load_lds_dwordx4 v[174:175], off
	v_lshl_add_u64 v[174:175], v[250:251], 0, s[24:25]
	s_mov_b32 m0, s80
	s_nop 0
	global_load_lds_dwordx4 v[174:175], off
	s_waitcnt vmcnt(8)
	s_waitcnt lgkmcnt(0)
	s_barrier
	s_waitcnt lgkmcnt(0)
	v_mfma_f32_16x16x32_bf16 v[60:63], v[158:161], v[206:209], v[60:63]
	v_mfma_f32_16x16x32_bf16 v[56:59], v[166:169], v[206:209], v[56:59]
	v_mfma_f32_16x16x32_bf16 v[52:55], v[158:161], v[214:217], v[52:55]
	v_mfma_f32_16x16x32_bf16 v[48:51], v[166:169], v[214:217], v[48:51]
	v_mfma_f32_16x16x32_bf16 v[36:39], v[158:161], v[222:225], v[36:39]
	v_mfma_f32_16x16x32_bf16 v[32:35], v[166:169], v[222:225], v[32:35]
	v_mfma_f32_16x16x32_bf16 v[20:23], v[158:161], v[238:241], v[20:23]
	v_mfma_f32_16x16x32_bf16 v[16:19], v[166:169], v[238:241], v[16:19]
	v_mfma_f32_16x16x32_bf16 v[60:63], v[162:165], v[210:213], v[60:63]
	v_mfma_f32_16x16x32_bf16 v[56:59], v[170:173], v[210:213], v[56:59]
	v_mfma_f32_16x16x32_bf16 v[52:55], v[162:165], v[218:221], v[52:55]
	v_mfma_f32_16x16x32_bf16 v[48:51], v[170:173], v[218:221], v[48:51]
	v_mfma_f32_16x16x32_bf16 v[36:39], v[162:165], v[234:237], v[36:39]
	v_mfma_f32_16x16x32_bf16 v[32:35], v[170:173], v[234:237], v[32:35]
	v_mfma_f32_16x16x32_bf16 v[20:23], v[162:165], v[242:245], v[20:23]
	v_mfma_f32_16x16x32_bf16 v[16:19], v[170:173], v[242:245], v[16:19]
	v_mfma_f32_16x16x32_bf16 v[44:47], v[190:193], v[206:209], v[44:47]
	v_mfma_f32_16x16x32_bf16 v[40:43], v[198:201], v[206:209], v[40:43]
	v_mfma_f32_16x16x32_bf16 v[28:31], v[190:193], v[214:217], v[28:31]
	v_mfma_f32_16x16x32_bf16 v[24:27], v[198:201], v[214:217], v[24:27]
	v_mfma_f32_16x16x32_bf16 v[12:15], v[190:193], v[222:225], v[12:15]
	v_mfma_f32_16x16x32_bf16 v[8:11], v[198:201], v[222:225], v[8:11]
	v_mfma_f32_16x16x32_bf16 v[4:7], v[190:193], v[238:241], v[4:7]
	v_mfma_f32_16x16x32_bf16 v[0:3], v[198:201], v[238:241], v[0:3]
	v_mfma_f32_16x16x32_bf16 v[44:47], v[194:197], v[210:213], v[44:47]
	v_mfma_f32_16x16x32_bf16 v[40:43], v[202:205], v[210:213], v[40:43]
	v_mfma_f32_16x16x32_bf16 v[28:31], v[194:197], v[218:221], v[28:31]
	v_mfma_f32_16x16x32_bf16 v[24:27], v[202:205], v[218:221], v[24:27]
	v_mfma_f32_16x16x32_bf16 v[12:15], v[194:197], v[234:237], v[12:15]
	v_mfma_f32_16x16x32_bf16 v[8:11], v[202:205], v[234:237], v[8:11]
	v_mfma_f32_16x16x32_bf16 v[4:7], v[194:197], v[242:245], v[4:7]
	v_mfma_f32_16x16x32_bf16 v[0:3], v[202:205], v[242:245], v[0:3]
	s_barrier
	s_add_i32 s91, s91, 2
	s_add_u32 vcc_hi, vcc_hi, 0x100
	s_addc_u32 s90, s90, 0
	s_add_u32 s70, s70, 0x100
	s_addc_u32 s71, s71, 0
	s_cmp_gt_u32 s91, 13
	s_cbranch_scc0 .LBB0_482
	s_setprio 0
	s_and_b64 vcc, exec, s[34:35]
	s_cbranch_vccz .LBB0_485
	s_barrier

.LBB0_497:
	s_ashr_i32 s37, s36, 31
	s_lshl_b64 s[40:41], s[36:37], 19
	s_add_u32 s40, s3, s40
	s_addc_u32 s41, s58, s41
	s_and_b64 s[46:47], s[42:43], exec
	s_cselect_b32 s22, s41, s71
	s_cselect_b32 s37, s40, s70
	s_ashr_i32 s39, s38, 31
	s_lshl_b64 s[46:47], s[38:39], 19
	s_add_u32 s46, s59, s46
	s_addc_u32 s47, s60, s47
	s_and_b64 s[72:73], s[42:43], exec
	s_cselect_b32 s39, s47, s69
	s_cselect_b32 vcc_lo, s46, s68
	s_add_u32 vcc_hi, s68, 0x100
	s_addc_u32 s90, s69, 0
	s_add_u32 s68, s70, 0x40080
	v_mov_b32_e32 v0, 0
	s_addc_u32 s69, s71, 0
	s_mov_b32 s91, -2
	v_mov_b32_e32 v1, v0
	v_mov_b32_e32 v2, v0
	v_mov_b32_e32 v3, v0
	v_mov_b32_e32 v4, v0
	v_mov_b32_e32 v5, v0
	v_mov_b32_e32 v6, v0
	v_mov_b32_e32 v7, v0
	v_mov_b32_e32 v8, v0
	v_mov_b32_e32 v9, v0
	v_mov_b32_e32 v10, v0
	v_mov_b32_e32 v11, v0
	v_mov_b32_e32 v12, v0
	v_mov_b32_e32 v13, v0
	v_mov_b32_e32 v14, v0
	v_mov_b32_e32 v15, v0
	v_mov_b32_e32 v24, v0
	v_mov_b32_e32 v25, v0
	v_mov_b32_e32 v26, v0
	v_mov_b32_e32 v27, v0
	v_mov_b32_e32 v28, v0
	v_mov_b32_e32 v29, v0
	v_mov_b32_e32 v30, v0
	v_mov_b32_e32 v31, v0
	v_mov_b32_e32 v40, v0
	v_mov_b32_e32 v41, v0
	v_mov_b32_e32 v42, v0
	v_mov_b32_e32 v43, v0
	v_mov_b32_e32 v44, v0
	v_mov_b32_e32 v45, v0
	v_mov_b32_e32 v46, v0
	v_mov_b32_e32 v47, v0
	v_mov_b32_e32 v16, v0
	v_mov_b32_e32 v17, v0
	v_mov_b32_e32 v18, v0
	v_mov_b32_e32 v19, v0
	v_mov_b32_e32 v20, v0
	v_mov_b32_e32 v21, v0
	v_mov_b32_e32 v22, v0
	v_mov_b32_e32 v23, v0
	v_mov_b32_e32 v32, v0
	v_mov_b32_e32 v33, v0
	v_mov_b32_e32 v34, v0
	v_mov_b32_e32 v35, v0
	v_mov_b32_e32 v36, v0
	v_mov_b32_e32 v37, v0
	v_mov_b32_e32 v38, v0
	v_mov_b32_e32 v39, v0
	v_mov_b32_e32 v48, v0
	v_mov_b32_e32 v49, v0
	v_mov_b32_e32 v50, v0
	v_mov_b32_e32 v51, v0
	v_mov_b32_e32 v52, v0
	v_mov_b32_e32 v53, v0
	v_mov_b32_e32 v54, v0
	v_mov_b32_e32 v55, v0
	v_mov_b32_e32 v56, v0
	v_mov_b32_e32 v57, v0
	v_mov_b32_e32 v58, v0
	v_mov_b32_e32 v59, v0
	v_mov_b32_e32 v60, v0
	v_mov_b32_e32 v61, v0
	v_mov_b32_e32 v62, v0
	v_mov_b32_e32 v63, v0
	v_mov_b32_e32 v64, v0
	v_mov_b32_e32 v65, v0
	v_mov_b32_e32 v66, v0
	v_mov_b32_e32 v67, v0
	v_mov_b32_e32 v68, v0
	v_mov_b32_e32 v69, v0
	v_mov_b32_e32 v70, v0
	v_mov_b32_e32 v71, v0
	v_mov_b32_e32 v72, v0
	v_mov_b32_e32 v73, v0
	v_mov_b32_e32 v74, v0
	v_mov_b32_e32 v75, v0
	v_mov_b32_e32 v76, v0
	v_mov_b32_e32 v77, v0
	v_mov_b32_e32 v78, v0
	v_mov_b32_e32 v79, v0
	v_mov_b32_e32 v88, v0
	v_mov_b32_e32 v89, v0
	v_mov_b32_e32 v90, v0
	v_mov_b32_e32 v91, v0
	v_mov_b32_e32 v92, v0
	v_mov_b32_e32 v93, v0
	v_mov_b32_e32 v94, v0
	v_mov_b32_e32 v95, v0
	v_mov_b32_e32 v104, v0
	v_mov_b32_e32 v105, v0
	v_mov_b32_e32 v106, v0
	v_mov_b32_e32 v107, v0
	v_mov_b32_e32 v108, v0
	v_mov_b32_e32 v109, v0
	v_mov_b32_e32 v110, v0
	v_mov_b32_e32 v111, v0
	v_mov_b32_e32 v80, v0
	v_mov_b32_e32 v81, v0
	v_mov_b32_e32 v82, v0
	v_mov_b32_e32 v83, v0
	v_mov_b32_e32 v84, v0
	v_mov_b32_e32 v85, v0
	v_mov_b32_e32 v86, v0
	v_mov_b32_e32 v87, v0
	v_mov_b32_e32 v96, v0
	v_mov_b32_e32 v97, v0
	v_mov_b32_e32 v98, v0
	v_mov_b32_e32 v99, v0
	v_mov_b32_e32 v100, v0
	v_mov_b32_e32 v101, v0
	v_mov_b32_e32 v102, v0
	v_mov_b32_e32 v103, v0
	v_mov_b32_e32 v112, v0
	v_mov_b32_e32 v113, v0
	v_mov_b32_e32 v114, v0
	v_mov_b32_e32 v115, v0
	v_mov_b32_e32 v116, v0
	v_mov_b32_e32 v117, v0
	v_mov_b32_e32 v118, v0
	v_mov_b32_e32 v119, v0
	v_mov_b32_e32 v120, v0
	v_mov_b32_e32 v121, v0
	v_mov_b32_e32 v122, v0
	v_mov_b32_e32 v123, v0
	v_mov_b32_e32 v124, v0
	v_mov_b32_e32 v125, v0
	v_mov_b32_e32 v126, v0
	v_mov_b32_e32 v127, v0
	v_readfirstlane_b32 s48, v226
	s_nop 3
	s_bitcmp1_b32 s48, 8
	s_cbranch_scc0 .Lpr_498
	s_setprio 1
.Lpr_498:
.LBB0_498:
	s_add_u32 s48, s68, 0xfffc0080
	s_addc_u32 s49, s69, -1
	s_add_i32 s96, 0, 0x10000
	s_cmp_eq_u32 s91, 12
	s_cselect_b32 s73, s22, s49
	s_cselect_b32 s72, s37, s48
	v_add_u32_e32 v141, s96, v135
	s_cselect_b32 s71, s39, s90
	s_cselect_b32 s70, vcc_lo, vcc_hi
	s_add_i32 s48, 0, 0x14000
	ds_read_b128 v[154:157], v141
	ds_read_b128 v[158:161], v141 offset:1024
	ds_read_b128 v[162:165], v141 offset:2048
	ds_read_b128 v[166:169], v141 offset:3072
	v_add_u32_e32 v141, s48, v135
	ds_read_b128 v[170:173], v141
	ds_read_b128 v[190:193], v141 offset:1024
	ds_read_b128 v[194:197], v141 offset:2048
	ds_read_b128 v[198:201], v141 offset:3072
	v_lshl_add_u64 v[174:175], s[68:69], 0, v[152:153]
	s_add_i32 m0, s62, 0xc000
	ds_read_b128 v[202:205], v139
	ds_read_b128 v[206:209], v139 offset:1024
	ds_read_b128 v[210:213], v139 offset:2048
	ds_read_b128 v[214:217], v139 offset:3072
	ds_read_b128 v[218:221], v139 offset:4096
	ds_read_b128 v[222:225], v139 offset:5120
	ds_read_b128 v[234:237], v139 offset:6144
	ds_read_b128 v[238:241], v139 offset:7168
	global_load_lds_dwordx4 v[174:175], off
	v_lshl_add_u64 v[174:175], s[68:69], 0, v[150:151]
	s_add_i32 m0, s62, 0xe000
	s_nop 0
	global_load_lds_dwordx4 v[174:175], off
	s_waitcnt vmcnt(8)
	s_waitcnt lgkmcnt(0)
	s_barrier
	s_waitcnt lgkmcnt(0)
	v_mfma_f32_16x16x32_bf16 v[124:127], v[154:157], v[202:205], v[124:127]
	v_mfma_f32_16x16x32_bf16 v[120:123], v[162:165], v[202:205], v[120:123]
	v_mfma_f32_16x16x32_bf16 v[116:119], v[154:157], v[210:213], v[116:119]
	v_mfma_f32_16x16x32_bf16 v[112:115], v[162:165], v[210:213], v[112:115]
	v_mfma_f32_16x16x32_bf16 v[100:103], v[154:157], v[218:221], v[100:103]
	v_mfma_f32_16x16x32_bf16 v[96:99], v[162:165], v[218:221], v[96:99]
	v_mfma_f32_16x16x32_bf16 v[84:87], v[154:157], v[234:237], v[84:87]
	v_mfma_f32_16x16x32_bf16 v[80:83], v[162:165], v[234:237], v[80:83]
	v_mfma_f32_16x16x32_bf16 v[124:127], v[158:161], v[206:209], v[124:127]
	v_mfma_f32_16x16x32_bf16 v[120:123], v[166:169], v[206:209], v[120:123]
	v_mfma_f32_16x16x32_bf16 v[116:119], v[158:161], v[214:217], v[116:119]
	v_mfma_f32_16x16x32_bf16 v[112:115], v[166:169], v[214:217], v[112:115]
	v_mfma_f32_16x16x32_bf16 v[100:103], v[158:161], v[222:225], v[100:103]
	v_mfma_f32_16x16x32_bf16 v[96:99], v[166:169], v[222:225], v[96:99]
	v_mfma_f32_16x16x32_bf16 v[84:87], v[158:161], v[238:241], v[84:87]
	v_mfma_f32_16x16x32_bf16 v[80:83], v[166:169], v[238:241], v[80:83]
	v_mfma_f32_16x16x32_bf16 v[108:111], v[170:173], v[202:205], v[108:111]
	v_mfma_f32_16x16x32_bf16 v[104:107], v[194:197], v[202:205], v[104:107]
	v_mfma_f32_16x16x32_bf16 v[92:95], v[170:173], v[210:213], v[92:95]
	v_mfma_f32_16x16x32_bf16 v[88:91], v[194:197], v[210:213], v[88:91]
	v_mfma_f32_16x16x32_bf16 v[76:79], v[170:173], v[218:221], v[76:79]
	v_mfma_f32_16x16x32_bf16 v[72:75], v[194:197], v[218:221], v[72:75]
	v_mfma_f32_16x16x32_bf16 v[68:71], v[170:173], v[234:237], v[68:71]
	v_mfma_f32_16x16x32_bf16 v[64:67], v[194:197], v[234:237], v[64:67]
	v_mfma_f32_16x16x32_bf16 v[108:111], v[190:193], v[206:209], v[108:111]
	v_mfma_f32_16x16x32_bf16 v[104:107], v[198:201], v[206:209], v[104:107]
	v_mfma_f32_16x16x32_bf16 v[92:95], v[190:193], v[214:217], v[92:95]
	v_mfma_f32_16x16x32_bf16 v[88:91], v[198:201], v[214:217], v[88:91]
	v_mfma_f32_16x16x32_bf16 v[76:79], v[190:193], v[222:225], v[76:79]
	v_mfma_f32_16x16x32_bf16 v[72:75], v[198:201], v[222:225], v[72:75]
	v_mfma_f32_16x16x32_bf16 v[68:71], v[190:193], v[238:241], v[68:71]
	v_mfma_f32_16x16x32_bf16 v[64:67], v[198:201], v[238:241], v[64:67]
	s_barrier
	s_add_i32 s49, s96, s61
	v_lshl_add_u64 v[174:175], s[70:71], 0, v[176:177]
	s_mov_b32 m0, s49
	ds_read_b128 v[202:205], v139 offset:16384
	ds_read_b128 v[206:209], v139 offset:17408
	ds_read_b128 v[210:213], v139 offset:18432
	ds_read_b128 v[214:217], v139 offset:19456
	ds_read_b128 v[218:221], v139 offset:20480
	ds_read_b128 v[222:225], v139 offset:21504
	ds_read_b128 v[234:237], v139 offset:22528
	ds_read_b128 v[238:241], v139 offset:23552
	global_load_lds_dwordx4 v[174:175], off
	s_add_i32 m0, s49, 0x2000
	s_add_u32 s96, s70, 0x40000
	v_lshl_add_u64 v[186:187], s[70:71], 0, v[128:129]
	s_addc_u32 s97, s71, 0
	s_add_i32 s48, s48, s61
	global_load_lds_dwordx4 v[186:187], off
	v_lshl_add_u64 v[242:243], s[96:97], 0, v[176:177]
	s_mov_b32 m0, s48
	v_lshl_add_u64 v[244:245], s[72:73], 0, v[130:131]
	global_load_lds_dwordx4 v[242:243], off
	v_lshl_add_u64 v[242:243], s[96:97], 0, v[128:129]
	s_add_i32 m0, s48, 0x2000
	s_nop 0
	global_load_lds_dwordx4 v[242:243], off
	v_lshl_add_u64 v[242:243], s[72:73], 0, v[132:133]
	s_mov_b32 m0, s62
	s_nop 0
	global_load_lds_dwordx4 v[242:243], off
	s_mov_b32 m0, s63
	s_nop 0
	global_load_lds_dwordx4 v[244:245], off
	s_waitcnt vmcnt(8)
	s_waitcnt lgkmcnt(0)
	s_barrier
	s_waitcnt lgkmcnt(0)
	v_mfma_f32_16x16x32_bf16 v[60:63], v[154:157], v[202:205], v[60:63]
	v_mfma_f32_16x16x32_bf16 v[56:59], v[162:165], v[202:205], v[56:59]
	v_mfma_f32_16x16x32_bf16 v[52:55], v[154:157], v[210:213], v[52:55]
	v_mfma_f32_16x16x32_bf16 v[48:51], v[162:165], v[210:213], v[48:51]
	v_mfma_f32_16x16x32_bf16 v[36:39], v[154:157], v[218:221], v[36:39]
	v_mfma_f32_16x16x32_bf16 v[32:35], v[162:165], v[218:221], v[32:35]
	v_mfma_f32_16x16x32_bf16 v[20:23], v[154:157], v[234:237], v[20:23]
	v_mfma_f32_16x16x32_bf16 v[16:19], v[162:165], v[234:237], v[16:19]
	v_mfma_f32_16x16x32_bf16 v[60:63], v[158:161], v[206:209], v[60:63]
	v_mfma_f32_16x16x32_bf16 v[56:59], v[166:169], v[206:209], v[56:59]
	v_mfma_f32_16x16x32_bf16 v[52:55], v[158:161], v[214:217], v[52:55]
	v_mfma_f32_16x16x32_bf16 v[48:51], v[166:169], v[214:217], v[48:51]
	v_mfma_f32_16x16x32_bf16 v[36:39], v[158:161], v[222:225], v[36:39]
	v_mfma_f32_16x16x32_bf16 v[32:35], v[166:169], v[222:225], v[32:35]
	v_mfma_f32_16x16x32_bf16 v[20:23], v[158:161], v[238:241], v[20:23]
	v_mfma_f32_16x16x32_bf16 v[16:19], v[166:169], v[238:241], v[16:19]
	v_mfma_f32_16x16x32_bf16 v[44:47], v[170:173], v[202:205], v[44:47]
	v_mfma_f32_16x16x32_bf16 v[40:43], v[194:197], v[202:205], v[40:43]
	v_mfma_f32_16x16x32_bf16 v[28:31], v[170:173], v[210:213], v[28:31]
	v_mfma_f32_16x16x32_bf16 v[24:27], v[194:197], v[210:213], v[24:27]
	v_mfma_f32_16x16x32_bf16 v[12:15], v[170:173], v[218:221], v[12:15]
	v_mfma_f32_16x16x32_bf16 v[8:11], v[194:197], v[218:221], v[8:11]
	v_mfma_f32_16x16x32_bf16 v[4:7], v[170:173], v[234:237], v[4:7]
	v_mfma_f32_16x16x32_bf16 v[0:3], v[194:197], v[234:237], v[0:3]
	v_mfma_f32_16x16x32_bf16 v[44:47], v[190:193], v[206:209], v[44:47]
	v_mfma_f32_16x16x32_bf16 v[40:43], v[198:201], v[206:209], v[40:43]
	v_mfma_f32_16x16x32_bf16 v[28:31], v[190:193], v[214:217], v[28:31]
	v_mfma_f32_16x16x32_bf16 v[24:27], v[198:201], v[214:217], v[24:27]
	v_mfma_f32_16x16x32_bf16 v[12:15], v[190:193], v[222:225], v[12:15]
	v_mfma_f32_16x16x32_bf16 v[8:11], v[198:201], v[222:225], v[8:11]
	v_mfma_f32_16x16x32_bf16 v[4:7], v[190:193], v[238:241], v[4:7]
	v_mfma_f32_16x16x32_bf16 v[0:3], v[198:201], v[238:241], v[0:3]
	s_barrier
	s_add_i32 s48, 0, 0x18000
	v_add_u32_e32 v141, s48, v135
	s_add_i32 s49, 0, 0x1c000
	ds_read_b128 v[154:157], v141
	ds_read_b128 v[158:161], v141 offset:1024
	ds_read_b128 v[162:165], v141 offset:2048
	ds_read_b128 v[166:169], v141 offset:3072
	v_add_u32_e32 v141, s49, v135
	ds_read_b128 v[170:173], v141
	ds_read_b128 v[190:193], v141 offset:1024
	ds_read_b128 v[194:197], v141 offset:2048
	ds_read_b128 v[198:201], v141 offset:3072
	s_add_u32 s72, s72, 0x40000
	s_addc_u32 s73, s73, 0
	s_mov_b32 m0, s74
	v_lshl_add_u64 v[246:247], s[72:73], 0, v[132:133]
	ds_read_b128 v[202:205], v139 offset:32768
	ds_read_b128 v[206:209], v139 offset:33792
	ds_read_b128 v[210:213], v139 offset:34816
	ds_read_b128 v[214:217], v139 offset:35840
	ds_read_b128 v[218:221], v139 offset:36864
	ds_read_b128 v[222:225], v139 offset:37888
	ds_read_b128 v[234:237], v139 offset:38912
	ds_read_b128 v[238:241], v139 offset:39936
	global_load_lds_dwordx4 v[246:247], off
	v_lshl_add_u64 v[246:247], s[72:73], 0, v[130:131]
	s_mov_b32 m0, s75
	s_nop 0
	global_load_lds_dwordx4 v[246:247], off
	s_waitcnt vmcnt(8)
	s_waitcnt lgkmcnt(0)
	s_barrier
	s_waitcnt lgkmcnt(0)
	v_mfma_f32_16x16x32_bf16 v[124:127], v[154:157], v[202:205], v[124:127]
	v_mfma_f32_16x16x32_bf16 v[120:123], v[162:165], v[202:205], v[120:123]
	v_mfma_f32_16x16x32_bf16 v[116:119], v[154:157], v[210:213], v[116:119]
	v_mfma_f32_16x16x32_bf16 v[112:115], v[162:165], v[210:213], v[112:115]
	v_mfma_f32_16x16x32_bf16 v[100:103], v[154:157], v[218:221], v[100:103]
	v_mfma_f32_16x16x32_bf16 v[96:99], v[162:165], v[218:221], v[96:99]
	v_mfma_f32_16x16x32_bf16 v[84:87], v[154:157], v[234:237], v[84:87]
	v_mfma_f32_16x16x32_bf16 v[80:83], v[162:165], v[234:237], v[80:83]
	v_mfma_f32_16x16x32_bf16 v[124:127], v[158:161], v[206:209], v[124:127]
	v_mfma_f32_16x16x32_bf16 v[120:123], v[166:169], v[206:209], v[120:123]
	v_mfma_f32_16x16x32_bf16 v[116:119], v[158:161], v[214:217], v[116:119]
	v_mfma_f32_16x16x32_bf16 v[112:115], v[166:169], v[214:217], v[112:115]
	v_mfma_f32_16x16x32_bf16 v[100:103], v[158:161], v[222:225], v[100:103]
	v_mfma_f32_16x16x32_bf16 v[96:99], v[166:169], v[222:225], v[96:99]
	v_mfma_f32_16x16x32_bf16 v[84:87], v[158:161], v[238:241], v[84:87]
	v_mfma_f32_16x16x32_bf16 v[80:83], v[166:169], v[238:241], v[80:83]
	v_mfma_f32_16x16x32_bf16 v[108:111], v[170:173], v[202:205], v[108:111]
	v_mfma_f32_16x16x32_bf16 v[104:107], v[194:197], v[202:205], v[104:107]
	v_mfma_f32_16x16x32_bf16 v[92:95], v[170:173], v[210:213], v[92:95]
	v_mfma_f32_16x16x32_bf16 v[88:91], v[194:197], v[210:213], v[88:91]
	v_mfma_f32_16x16x32_bf16 v[76:79], v[170:173], v[218:221], v[76:79]
	v_mfma_f32_16x16x32_bf16 v[72:75], v[194:197], v[218:221], v[72:75]
	v_mfma_f32_16x16x32_bf16 v[68:71], v[170:173], v[234:237], v[68:71]
	v_mfma_f32_16x16x32_bf16 v[64:67], v[194:197], v[234:237], v[64:67]
	v_mfma_f32_16x16x32_bf16 v[108:111], v[190:193], v[206:209], v[108:111]
	v_mfma_f32_16x16x32_bf16 v[104:107], v[198:201], v[206:209], v[104:107]
	v_mfma_f32_16x16x32_bf16 v[92:95], v[190:193], v[214:217], v[92:95]
	v_mfma_f32_16x16x32_bf16 v[88:91], v[198:201], v[214:217], v[88:91]
	v_mfma_f32_16x16x32_bf16 v[76:79], v[190:193], v[222:225], v[76:79]
	v_mfma_f32_16x16x32_bf16 v[72:75], v[198:201], v[222:225], v[72:75]
	v_mfma_f32_16x16x32_bf16 v[68:71], v[190:193], v[238:241], v[68:71]
	v_mfma_f32_16x16x32_bf16 v[64:67], v[198:201], v[238:241], v[64:67]
	s_barrier
	s_add_i32 s48, s48, s61
	v_lshl_add_u64 v[174:175], v[174:175], 0, s[24:25]
	s_mov_b32 m0, s48
	ds_read_b128 v[202:205], v139 offset:49152
	ds_read_b128 v[206:209], v139 offset:50176
	ds_read_b128 v[210:213], v139 offset:51200
	ds_read_b128 v[214:217], v139 offset:52224
	ds_read_b128 v[218:221], v139 offset:53248
	ds_read_b128 v[222:225], v139 offset:54272
	ds_read_b128 v[234:237], v139 offset:55296
	ds_read_b128 v[238:241], v139 offset:56320
	global_load_lds_dwordx4 v[174:175], off
	s_add_i32 m0, s48, 0x2000
	s_add_u32 s70, s70, 0x40080
	v_lshl_add_u64 v[174:175], v[186:187], 0, s[24:25]
	s_addc_u32 s71, s71, 0
	s_add_i32 s48, s49, s61
	global_load_lds_dwordx4 v[174:175], off
	v_lshl_add_u64 v[174:175], s[70:71], 0, v[176:177]
	s_mov_b32 m0, s48
	s_nop 0
	global_load_lds_dwordx4 v[174:175], off
	v_lshl_add_u64 v[174:175], s[70:71], 0, v[128:129]
	s_add_i32 m0, s48, 0x2000
	s_nop 0
	global_load_lds_dwordx4 v[174:175], off
	v_lshl_add_u64 v[174:175], v[242:243], 0, s[24:25]
	s_mov_b32 m0, s81
	s_nop 0
	global_load_lds_dwordx4 v[174:175], off
	v_lshl_add_u64 v[174:175], v[244:245], 0, s[24:25]
	s_mov_b32 m0, s82
	s_nop 0
	global_load_lds_dwordx4 v[174:175], off
	s_waitcnt vmcnt(8)
	s_waitcnt lgkmcnt(0)
	s_barrier
	s_waitcnt lgkmcnt(0)
	v_mfma_f32_16x16x32_bf16 v[60:63], v[154:157], v[202:205], v[60:63]
	v_mfma_f32_16x16x32_bf16 v[56:59], v[162:165], v[202:205], v[56:59]
	v_mfma_f32_16x16x32_bf16 v[52:55], v[154:157], v[210:213], v[52:55]
	v_mfma_f32_16x16x32_bf16 v[48:51], v[162:165], v[210:213], v[48:51]
	v_mfma_f32_16x16x32_bf16 v[36:39], v[154:157], v[218:221], v[36:39]
	v_mfma_f32_16x16x32_bf16 v[32:35], v[162:165], v[218:221], v[32:35]
	v_mfma_f32_16x16x32_bf16 v[20:23], v[154:157], v[234:237], v[20:23]
	v_mfma_f32_16x16x32_bf16 v[16:19], v[162:165], v[234:237], v[16:19]
	v_mfma_f32_16x16x32_bf16 v[60:63], v[158:161], v[206:209], v[60:63]
	v_mfma_f32_16x16x32_bf16 v[56:59], v[166:169], v[206:209], v[56:59]
	v_mfma_f32_16x16x32_bf16 v[52:55], v[158:161], v[214:217], v[52:55]
	v_mfma_f32_16x16x32_bf16 v[48:51], v[166:169], v[214:217], v[48:51]
	v_mfma_f32_16x16x32_bf16 v[36:39], v[158:161], v[222:225], v[36:39]
	v_mfma_f32_16x16x32_bf16 v[32:35], v[166:169], v[222:225], v[32:35]
	v_mfma_f32_16x16x32_bf16 v[20:23], v[158:161], v[238:241], v[20:23]
	v_mfma_f32_16x16x32_bf16 v[16:19], v[166:169], v[238:241], v[16:19]
	v_mfma_f32_16x16x32_bf16 v[44:47], v[170:173], v[202:205], v[44:47]
	v_mfma_f32_16x16x32_bf16 v[40:43], v[194:197], v[202:205], v[40:43]
	v_mfma_f32_16x16x32_bf16 v[28:31], v[170:173], v[210:213], v[28:31]
	v_mfma_f32_16x16x32_bf16 v[24:27], v[194:197], v[210:213], v[24:27]
	v_mfma_f32_16x16x32_bf16 v[12:15], v[170:173], v[218:221], v[12:15]
	v_mfma_f32_16x16x32_bf16 v[8:11], v[194:197], v[218:221], v[8:11]
	v_mfma_f32_16x16x32_bf16 v[4:7], v[170:173], v[234:237], v[4:7]
	v_mfma_f32_16x16x32_bf16 v[0:3], v[194:197], v[234:237], v[0:3]
	v_mfma_f32_16x16x32_bf16 v[44:47], v[190:193], v[206:209], v[44:47]
	v_mfma_f32_16x16x32_bf16 v[40:43], v[198:201], v[206:209], v[40:43]
	v_mfma_f32_16x16x32_bf16 v[28:31], v[190:193], v[214:217], v[28:31]
	v_mfma_f32_16x16x32_bf16 v[24:27], v[198:201], v[214:217], v[24:27]
	v_mfma_f32_16x16x32_bf16 v[12:15], v[190:193], v[222:225], v[12:15]
	v_mfma_f32_16x16x32_bf16 v[8:11], v[198:201], v[222:225], v[8:11]
	v_mfma_f32_16x16x32_bf16 v[4:7], v[190:193], v[238:241], v[4:7]
	v_mfma_f32_16x16x32_bf16 v[0:3], v[198:201], v[238:241], v[0:3]
	s_barrier
	s_add_i32 s91, s91, 2
	s_add_u32 vcc_hi, vcc_hi, 0x100
	s_addc_u32 s90, s90, 0
	s_add_u32 s68, s68, 0x100
	s_addc_u32 s69, s69, 0
	s_cmp_gt_u32 s91, 13
	s_cbranch_scc0 .LBB0_498
	s_setprio 0
	s_and_b64 vcc, exec, s[34:35]
	s_cbranch_vccz .LBB0_501
	s_barrier

.LBB0_568:
	v_lshrrev_b32_e32 v15, 1, v140
	v_and_b32_e32 v129, 24, v15
	v_and_b32_e32 v14, 15, v140
	v_lshlrev_b32_e32 v15, 1, v129
	s_lshl_b32 s46, s46, 5
	v_lshl_or_b32 v128, s47, 6, v14
	v_lshl_or_b32 v14, v14, 6, v15
	v_lshlrev_b32_e32 v15, 2, v140
	s_and_b32 s71, s46, 0x60
	s_add_i32 m0, s61, 0x18000
	v_lshl_add_u64 v[6:7], v[6:7], 0, s[100:101]
	v_and_b32_e32 v15, 32, v15
	s_lshl_b32 s47, s47, 13
	s_lshl_b32 s46, s71, 7
	s_waitcnt vmcnt(2)
	s_barrier
	global_load_lds_dwordx4 v[6:7], off
	v_lshl_add_u64 v[4:5], v[4:5], 0, s[100:101]
	s_add_i32 m0, s61, 0x1a000
	s_add_i32 s72, s61, 0x8000
	s_add_i32 s73, s61, 0xa000
	v_bitop3_b32 v141, v14, s46, v15 bitop3:0xde
	global_load_lds_dwordx4 v[4:5], off
	v_lshl_add_u64 v[2:3], v[2:3], 0, s[100:101]
	s_mov_b32 m0, s72
	s_add_u32 s46, s40, 0x80100
	v_bitop3_b32 v16, v14, s47, v15 bitop3:0xde
	global_load_lds_dwordx4 v[2:3], off
	v_lshl_add_u64 v[0:1], v[0:1], 0, s[100:101]
	s_mov_b32 m0, s73
	s_addc_u32 s47, s41, 0
	global_load_lds_dwordx4 v[0:1], off
	s_add_i32 m0, s61, 0x1c000
	v_lshl_add_u64 v[0:1], s[46:47], 0, v[176:177]
	global_load_lds_dwordx4 v[0:1], off
	v_lshl_add_u64 v[0:1], s[46:47], 0, v[134:135]
	s_add_i32 m0, s61, 0x1e000
	s_lshl_b32 s46, s77, 21
	global_load_lds_dwordx4 v[0:1], off
	v_lshlrev_b32_e32 v0, 17, v11
	v_and_b32_e32 v0, 0xfffc0000, v0
	s_and_b32 s46, s46, 0x1c00000
	v_lshl_add_u32 v0, v12, 14, v0
	v_and_b32_e32 v1, 1, v11
	v_lshl_or_b32 v0, v1, 6, v0
	s_add_u32 s42, s42, s46
	v_lshl_add_u32 v0, v13, 1, v0
	v_mov_b32_e32 v1, v177
	s_addc_u32 s43, s43, 0
	v_lshl_add_u64 v[136:137], s[42:43], 0, v[0:1]
	v_lshlrev_b32_e32 v0, 17, v8
	v_and_b32_e32 v0, 0xfffc0000, v0
	v_lshl_add_u32 v0, v9, 14, v0
	v_and_b32_e32 v1, 1, v8
	v_lshl_or_b32 v0, v1, 6, v0
	s_waitcnt vmcnt(6)
	v_lshl_add_u32 v0, v10, 1, v0
	v_mov_b32_e32 v1, v177
	v_lshl_add_u64 v[138:139], s[42:43], 0, v[0:1]
	v_mov_b32_e32 v0, 0
	s_mov_b32 s78, -2
	s_mov_b64 s[42:43], 0x2d00100
	v_add_u32_e32 v142, 0, v16
	v_mov_b32_e32 v1, v0
	v_mov_b32_e32 v2, v0
	v_mov_b32_e32 v3, v0
	v_mov_b32_e32 v4, v0
	v_mov_b32_e32 v5, v0
	v_mov_b32_e32 v6, v0
	v_mov_b32_e32 v7, v0
	v_mov_b32_e32 v8, v0
	v_mov_b32_e32 v9, v0
	v_mov_b32_e32 v10, v0
	v_mov_b32_e32 v11, v0
	v_mov_b32_e32 v16, v0
	v_mov_b32_e32 v17, v0
	v_mov_b32_e32 v18, v0
	v_mov_b32_e32 v19, v0
	v_mov_b32_e32 v24, v0
	v_mov_b32_e32 v25, v0
	v_mov_b32_e32 v26, v0
	v_mov_b32_e32 v27, v0
	v_mov_b32_e32 v32, v0
	v_mov_b32_e32 v33, v0
	v_mov_b32_e32 v34, v0
	v_mov_b32_e32 v35, v0
	v_mov_b32_e32 v40, v0
	v_mov_b32_e32 v41, v0
	v_mov_b32_e32 v42, v0
	v_mov_b32_e32 v43, v0
	v_mov_b32_e32 v48, v0
	v_mov_b32_e32 v49, v0
	v_mov_b32_e32 v50, v0
	v_mov_b32_e32 v51, v0
	v_mov_b32_e32 v12, v0
	v_mov_b32_e32 v13, v0
	v_mov_b32_e32 v14, v0
	v_mov_b32_e32 v15, v0
	v_mov_b32_e32 v20, v0
	v_mov_b32_e32 v21, v0
	v_mov_b32_e32 v22, v0
	v_mov_b32_e32 v23, v0
	v_mov_b32_e32 v28, v0
	v_mov_b32_e32 v29, v0
	v_mov_b32_e32 v30, v0
	v_mov_b32_e32 v31, v0
	v_mov_b32_e32 v36, v0
	v_mov_b32_e32 v37, v0
	v_mov_b32_e32 v38, v0
	v_mov_b32_e32 v39, v0
	v_mov_b32_e32 v44, v0
	v_mov_b32_e32 v45, v0
	v_mov_b32_e32 v46, v0
	v_mov_b32_e32 v47, v0
	v_mov_b32_e32 v52, v0
	v_mov_b32_e32 v53, v0
	v_mov_b32_e32 v54, v0
	v_mov_b32_e32 v55, v0
	v_mov_b32_e32 v56, v0
	v_mov_b32_e32 v57, v0
	v_mov_b32_e32 v58, v0
	v_mov_b32_e32 v59, v0
	v_mov_b32_e32 v60, v0
	v_mov_b32_e32 v61, v0
	v_mov_b32_e32 v62, v0
	v_mov_b32_e32 v63, v0
	v_mov_b32_e32 v64, v0
	v_mov_b32_e32 v65, v0
	v_mov_b32_e32 v66, v0
	v_mov_b32_e32 v67, v0
	v_mov_b32_e32 v68, v0
	v_mov_b32_e32 v69, v0
	v_mov_b32_e32 v70, v0
	v_mov_b32_e32 v71, v0
	v_mov_b32_e32 v72, v0
	v_mov_b32_e32 v73, v0
	v_mov_b32_e32 v74, v0
	v_mov_b32_e32 v75, v0
	v_mov_b32_e32 v80, v0
	v_mov_b32_e32 v81, v0
	v_mov_b32_e32 v82, v0
	v_mov_b32_e32 v83, v0
	v_mov_b32_e32 v88, v0
	v_mov_b32_e32 v89, v0
	v_mov_b32_e32 v90, v0
	v_mov_b32_e32 v91, v0
	s_waitcnt vmcnt(0)
	v_mov_b32_e32 v96, v0
	v_mov_b32_e32 v97, v0
	v_mov_b32_e32 v98, v0
	v_mov_b32_e32 v99, v0
	v_mov_b32_e32 v112, v0
	v_mov_b32_e32 v113, v0
	v_mov_b32_e32 v114, v0
	v_mov_b32_e32 v115, v0
	v_mov_b32_e32 v116, v0
	v_mov_b32_e32 v117, v0
	v_mov_b32_e32 v118, v0
	v_mov_b32_e32 v119, v0
	v_mov_b32_e32 v76, v0
	v_mov_b32_e32 v77, v0
	v_mov_b32_e32 v78, v0
	v_mov_b32_e32 v79, v0
	v_mov_b32_e32 v84, v0
	v_mov_b32_e32 v85, v0
	v_mov_b32_e32 v86, v0
	v_mov_b32_e32 v87, v0
	v_mov_b32_e32 v92, v0
	v_mov_b32_e32 v93, v0
	v_mov_b32_e32 v94, v0
	v_mov_b32_e32 v95, v0
	v_mov_b32_e32 v100, v0
	v_mov_b32_e32 v101, v0
	v_mov_b32_e32 v102, v0
	v_mov_b32_e32 v103, v0
	v_mov_b32_e32 v104, v0
	v_mov_b32_e32 v105, v0
	v_mov_b32_e32 v106, v0
	v_mov_b32_e32 v107, v0
	v_mov_b32_e32 v108, v0
	v_mov_b32_e32 v109, v0
	v_mov_b32_e32 v110, v0
	v_mov_b32_e32 v111, v0
	v_mov_b32_e32 v120, v0
	v_mov_b32_e32 v121, v0
	v_mov_b32_e32 v122, v0
	v_mov_b32_e32 v123, v0
	v_mov_b32_e32 v124, v0
	v_mov_b32_e32 v125, v0
	v_mov_b32_e32 v126, v0
	v_mov_b32_e32 v127, v0
	s_barrier
	v_readfirstlane_b32 s46, v226
	s_nop 3
	s_bitcmp1_b32 s46, 8
	s_cbranch_scc0 .Lpr_569
	s_setprio 1
.Lpr_569:
.LBB0_569:
	s_add_u32 s46, s42, 0xfd300100
	s_addc_u32 s47, s43, -1
	s_andn2_b32 s48, 0x80, s42
	s_cmp_lg_u32 s78, 12
	s_cselect_b32 s46, s46, s48
	s_cselect_b32 s47, s47, 0
	s_add_u32 s68, s34, s46
	s_addc_u32 s69, s35, s47
	s_add_i32 s48, 0, 0x10000
	s_add_u32 s46, s40, s46
	v_add_u32_e32 v143, s48, v141
	s_addc_u32 s47, s41, s47
	s_add_i32 s49, 0, 0x14000
	ds_read_b128 v[144:147], v143
	ds_read_b128 v[148:151], v143 offset:1024
	ds_read_b128 v[152:155], v143 offset:2048
	ds_read_b128 v[156:159], v143 offset:3072
	v_add_u32_e32 v143, s49, v141
	ds_read_b128 v[160:163], v143
	ds_read_b128 v[164:167], v143 offset:1024
	ds_read_b128 v[168:171], v143 offset:2048
	ds_read_b128 v[172:175], v143 offset:3072
	v_lshl_add_u64 v[186:187], v[138:139], 0, s[42:43]
	s_add_i32 m0, s61, 0xc000
	ds_read_b128 v[190:193], v142
	ds_read_b128 v[194:197], v142 offset:1024
	ds_read_b128 v[198:201], v142 offset:2048
	ds_read_b128 v[202:205], v142 offset:3072
	ds_read_b128 v[206:209], v142 offset:4096
	ds_read_b128 v[210:213], v142 offset:5120
	ds_read_b128 v[214:217], v142 offset:6144
	ds_read_b128 v[218:221], v142 offset:7168
	global_load_lds_dwordx4 v[186:187], off
	v_lshl_add_u64 v[186:187], v[136:137], 0, s[42:43]
	s_add_i32 m0, s61, 0xe000
	s_nop 0
	global_load_lds_dwordx4 v[186:187], off
	s_waitcnt vmcnt(8)
	s_waitcnt lgkmcnt(0)
	s_barrier
	s_waitcnt lgkmcnt(0)
	v_mfma_f32_16x16x32_bf16 v[124:127], v[144:147], v[190:193], v[124:127]
	v_mfma_f32_16x16x32_bf16 v[120:123], v[152:155], v[190:193], v[120:123]
	v_mfma_f32_16x16x32_bf16 v[108:111], v[144:147], v[198:201], v[108:111]
	v_mfma_f32_16x16x32_bf16 v[104:107], v[152:155], v[198:201], v[104:107]
	v_mfma_f32_16x16x32_bf16 v[100:103], v[144:147], v[206:209], v[100:103]
	v_mfma_f32_16x16x32_bf16 v[92:95], v[152:155], v[206:209], v[92:95]
	v_mfma_f32_16x16x32_bf16 v[84:87], v[144:147], v[214:217], v[84:87]
	v_mfma_f32_16x16x32_bf16 v[76:79], v[152:155], v[214:217], v[76:79]
	v_mfma_f32_16x16x32_bf16 v[124:127], v[148:151], v[194:197], v[124:127]
	v_mfma_f32_16x16x32_bf16 v[120:123], v[156:159], v[194:197], v[120:123]
	v_mfma_f32_16x16x32_bf16 v[108:111], v[148:151], v[202:205], v[108:111]
	v_mfma_f32_16x16x32_bf16 v[104:107], v[156:159], v[202:205], v[104:107]
	v_mfma_f32_16x16x32_bf16 v[100:103], v[148:151], v[210:213], v[100:103]
	v_mfma_f32_16x16x32_bf16 v[92:95], v[156:159], v[210:213], v[92:95]
	v_mfma_f32_16x16x32_bf16 v[84:87], v[148:151], v[218:221], v[84:87]
	v_mfma_f32_16x16x32_bf16 v[76:79], v[156:159], v[218:221], v[76:79]
	v_mfma_f32_16x16x32_bf16 v[116:119], v[160:163], v[190:193], v[116:119]
	v_mfma_f32_16x16x32_bf16 v[112:115], v[168:171], v[190:193], v[112:115]
	v_mfma_f32_16x16x32_bf16 v[96:99], v[160:163], v[198:201], v[96:99]
	v_mfma_f32_16x16x32_bf16 v[88:91], v[168:171], v[198:201], v[88:91]
	v_mfma_f32_16x16x32_bf16 v[80:83], v[160:163], v[206:209], v[80:83]
	v_mfma_f32_16x16x32_bf16 v[72:75], v[168:171], v[206:209], v[72:75]
	v_mfma_f32_16x16x32_bf16 v[68:71], v[160:163], v[214:217], v[68:71]
	v_mfma_f32_16x16x32_bf16 v[64:67], v[168:171], v[214:217], v[64:67]
	v_mfma_f32_16x16x32_bf16 v[116:119], v[164:167], v[194:197], v[116:119]
	v_mfma_f32_16x16x32_bf16 v[112:115], v[172:175], v[194:197], v[112:115]
	v_mfma_f32_16x16x32_bf16 v[96:99], v[164:167], v[202:205], v[96:99]
	v_mfma_f32_16x16x32_bf16 v[88:91], v[172:175], v[202:205], v[88:91]
	v_mfma_f32_16x16x32_bf16 v[80:83], v[164:167], v[210:213], v[80:83]
	v_mfma_f32_16x16x32_bf16 v[72:75], v[172:175], v[210:213], v[72:75]
	v_mfma_f32_16x16x32_bf16 v[68:71], v[164:167], v[218:221], v[68:71]
	v_mfma_f32_16x16x32_bf16 v[64:67], v[172:175], v[218:221], v[64:67]
	s_barrier
	s_add_i32 s48, s48, s60
	v_lshl_add_u64 v[186:187], s[46:47], 0, v[176:177]
	s_mov_b32 m0, s48
	ds_read_b128 v[190:193], v142 offset:16384
	ds_read_b128 v[194:197], v142 offset:17408
	ds_read_b128 v[198:201], v142 offset:18432
	ds_read_b128 v[202:205], v142 offset:19456
	ds_read_b128 v[206:209], v142 offset:20480
	ds_read_b128 v[210:213], v142 offset:21504
	ds_read_b128 v[214:217], v142 offset:22528
	ds_read_b128 v[218:221], v142 offset:23552
	global_load_lds_dwordx4 v[186:187], off
	s_add_i32 m0, s48, 0x2000
	s_add_u32 s80, s46, 0x80000
	v_lshl_add_u64 v[222:223], s[46:47], 0, v[134:135]
	s_addc_u32 s81, s47, 0
	s_add_i32 s48, s49, s60
	global_load_lds_dwordx4 v[222:223], off
	v_lshl_add_u64 v[224:225], s[80:81], 0, v[176:177]
	s_mov_b32 m0, s48
	v_lshl_add_u64 v[234:235], s[68:69], 0, v[132:133]
	global_load_lds_dwordx4 v[224:225], off
	v_lshl_add_u64 v[224:225], s[80:81], 0, v[134:135]
	s_add_i32 m0, s48, 0x2000
	s_nop 0
	global_load_lds_dwordx4 v[224:225], off
	v_lshl_add_u64 v[224:225], s[68:69], 0, v[130:131]
	s_mov_b32 m0, s61
	s_nop 0
	global_load_lds_dwordx4 v[224:225], off
	s_mov_b32 m0, s62
	s_nop 0
	global_load_lds_dwordx4 v[234:235], off
	s_waitcnt vmcnt(8)
	s_waitcnt lgkmcnt(0)
	s_barrier
	s_waitcnt lgkmcnt(0)
	v_mfma_f32_16x16x32_bf16 v[60:63], v[144:147], v[190:193], v[60:63]
	v_mfma_f32_16x16x32_bf16 v[56:59], v[152:155], v[190:193], v[56:59]
	v_mfma_f32_16x16x32_bf16 v[52:55], v[144:147], v[198:201], v[52:55]
	v_mfma_f32_16x16x32_bf16 v[44:47], v[152:155], v[198:201], v[44:47]
	v_mfma_f32_16x16x32_bf16 v[36:39], v[144:147], v[206:209], v[36:39]
	v_mfma_f32_16x16x32_bf16 v[28:31], v[152:155], v[206:209], v[28:31]
	v_mfma_f32_16x16x32_bf16 v[20:23], v[144:147], v[214:217], v[20:23]
	v_mfma_f32_16x16x32_bf16 v[12:15], v[152:155], v[214:217], v[12:15]
	v_mfma_f32_16x16x32_bf16 v[60:63], v[148:151], v[194:197], v[60:63]
	v_mfma_f32_16x16x32_bf16 v[56:59], v[156:159], v[194:197], v[56:59]
	v_mfma_f32_16x16x32_bf16 v[52:55], v[148:151], v[202:205], v[52:55]
	v_mfma_f32_16x16x32_bf16 v[44:47], v[156:159], v[202:205], v[44:47]
	v_mfma_f32_16x16x32_bf16 v[36:39], v[148:151], v[210:213], v[36:39]
	v_mfma_f32_16x16x32_bf16 v[28:31], v[156:159], v[210:213], v[28:31]
	v_mfma_f32_16x16x32_bf16 v[20:23], v[148:151], v[218:221], v[20:23]
	v_mfma_f32_16x16x32_bf16 v[12:15], v[156:159], v[218:221], v[12:15]
	v_mfma_f32_16x16x32_bf16 v[48:51], v[160:163], v[190:193], v[48:51]
	v_mfma_f32_16x16x32_bf16 v[40:43], v[168:171], v[190:193], v[40:43]
	v_mfma_f32_16x16x32_bf16 v[32:35], v[160:163], v[198:201], v[32:35]
	v_mfma_f32_16x16x32_bf16 v[24:27], v[168:171], v[198:201], v[24:27]
	v_mfma_f32_16x16x32_bf16 v[16:19], v[160:163], v[206:209], v[16:19]
	v_mfma_f32_16x16x32_bf16 v[8:11], v[168:171], v[206:209], v[8:11]
	v_mfma_f32_16x16x32_bf16 v[4:7], v[160:163], v[214:217], v[4:7]
	v_mfma_f32_16x16x32_bf16 v[0:3], v[168:171], v[214:217], v[0:3]
	v_mfma_f32_16x16x32_bf16 v[48:51], v[164:167], v[194:197], v[48:51]
	v_mfma_f32_16x16x32_bf16 v[40:43], v[172:175], v[194:197], v[40:43]
	v_mfma_f32_16x16x32_bf16 v[32:35], v[164:167], v[202:205], v[32:35]
	v_mfma_f32_16x16x32_bf16 v[24:27], v[172:175], v[202:205], v[24:27]
	v_mfma_f32_16x16x32_bf16 v[16:19], v[164:167], v[210:213], v[16:19]
	v_mfma_f32_16x16x32_bf16 v[8:11], v[172:175], v[210:213], v[8:11]
	v_mfma_f32_16x16x32_bf16 v[4:7], v[164:167], v[218:221], v[4:7]
	v_mfma_f32_16x16x32_bf16 v[0:3], v[172:175], v[218:221], v[0:3]
	s_barrier
	s_add_i32 s48, 0, 0x18000
	v_add_u32_e32 v143, s48, v141
	s_add_i32 s49, 0, 0x1c000
	ds_read_b128 v[144:147], v143
	ds_read_b128 v[148:151], v143 offset:1024
	ds_read_b128 v[152:155], v143 offset:2048
	ds_read_b128 v[156:159], v143 offset:3072
	v_add_u32_e32 v143, s49, v141
	ds_read_b128 v[160:163], v143
	ds_read_b128 v[164:167], v143 offset:1024
	ds_read_b128 v[168:171], v143 offset:2048
	ds_read_b128 v[172:175], v143 offset:3072
	s_add_u32 s68, s68, 0x200000
	s_addc_u32 s69, s69, 0
	s_mov_b32 m0, s63
	v_lshl_add_u64 v[236:237], s[68:69], 0, v[130:131]
	ds_read_b128 v[190:193], v142 offset:32768
	ds_read_b128 v[194:197], v142 offset:33792
	ds_read_b128 v[198:201], v142 offset:34816
	ds_read_b128 v[202:205], v142 offset:35840
	ds_read_b128 v[206:209], v142 offset:36864
	ds_read_b128 v[210:213], v142 offset:37888
	ds_read_b128 v[214:217], v142 offset:38912
	ds_read_b128 v[218:221], v142 offset:39936
	global_load_lds_dwordx4 v[236:237], off
	v_lshl_add_u64 v[236:237], s[68:69], 0, v[132:133]
	s_mov_b32 m0, s70
	s_nop 0
	global_load_lds_dwordx4 v[236:237], off
	s_waitcnt vmcnt(8)
	s_waitcnt lgkmcnt(0)
	s_barrier
	s_waitcnt lgkmcnt(0)
	v_mfma_f32_16x16x32_bf16 v[124:127], v[144:147], v[190:193], v[124:127]
	v_mfma_f32_16x16x32_bf16 v[120:123], v[152:155], v[190:193], v[120:123]
	v_mfma_f32_16x16x32_bf16 v[108:111], v[144:147], v[198:201], v[108:111]
	v_mfma_f32_16x16x32_bf16 v[104:107], v[152:155], v[198:201], v[104:107]
	v_mfma_f32_16x16x32_bf16 v[100:103], v[144:147], v[206:209], v[100:103]
	v_mfma_f32_16x16x32_bf16 v[92:95], v[152:155], v[206:209], v[92:95]
	v_mfma_f32_16x16x32_bf16 v[84:87], v[144:147], v[214:217], v[84:87]
	v_mfma_f32_16x16x32_bf16 v[76:79], v[152:155], v[214:217], v[76:79]
	v_mfma_f32_16x16x32_bf16 v[124:127], v[148:151], v[194:197], v[124:127]
	v_mfma_f32_16x16x32_bf16 v[120:123], v[156:159], v[194:197], v[120:123]
	v_mfma_f32_16x16x32_bf16 v[108:111], v[148:151], v[202:205], v[108:111]
	v_mfma_f32_16x16x32_bf16 v[104:107], v[156:159], v[202:205], v[104:107]
	v_mfma_f32_16x16x32_bf16 v[100:103], v[148:151], v[210:213], v[100:103]
	v_mfma_f32_16x16x32_bf16 v[92:95], v[156:159], v[210:213], v[92:95]
	v_mfma_f32_16x16x32_bf16 v[84:87], v[148:151], v[218:221], v[84:87]
	v_mfma_f32_16x16x32_bf16 v[76:79], v[156:159], v[218:221], v[76:79]
	v_mfma_f32_16x16x32_bf16 v[116:119], v[160:163], v[190:193], v[116:119]
	v_mfma_f32_16x16x32_bf16 v[112:115], v[168:171], v[190:193], v[112:115]
	v_mfma_f32_16x16x32_bf16 v[96:99], v[160:163], v[198:201], v[96:99]
	v_mfma_f32_16x16x32_bf16 v[88:91], v[168:171], v[198:201], v[88:91]
	v_mfma_f32_16x16x32_bf16 v[80:83], v[160:163], v[206:209], v[80:83]
	v_mfma_f32_16x16x32_bf16 v[72:75], v[168:171], v[206:209], v[72:75]
	v_mfma_f32_16x16x32_bf16 v[68:71], v[160:163], v[214:217], v[68:71]
	v_mfma_f32_16x16x32_bf16 v[64:67], v[168:171], v[214:217], v[64:67]
	v_mfma_f32_16x16x32_bf16 v[116:119], v[164:167], v[194:197], v[116:119]
	v_mfma_f32_16x16x32_bf16 v[112:115], v[172:175], v[194:197], v[112:115]
	v_mfma_f32_16x16x32_bf16 v[96:99], v[164:167], v[202:205], v[96:99]
	v_mfma_f32_16x16x32_bf16 v[88:91], v[172:175], v[202:205], v[88:91]
	v_mfma_f32_16x16x32_bf16 v[80:83], v[164:167], v[210:213], v[80:83]
	v_mfma_f32_16x16x32_bf16 v[72:75], v[172:175], v[210:213], v[72:75]
	v_mfma_f32_16x16x32_bf16 v[68:71], v[164:167], v[218:221], v[68:71]
	v_mfma_f32_16x16x32_bf16 v[64:67], v[172:175], v[218:221], v[64:67]
	s_barrier
	s_add_i32 s48, s48, s60
	v_lshl_add_u64 v[186:187], v[186:187], 0, s[100:101]
	s_mov_b32 m0, s48
	ds_read_b128 v[190:193], v142 offset:49152
	ds_read_b128 v[194:197], v142 offset:50176
	ds_read_b128 v[198:201], v142 offset:51200
	ds_read_b128 v[202:205], v142 offset:52224
	ds_read_b128 v[206:209], v142 offset:53248
	ds_read_b128 v[210:213], v142 offset:54272
	ds_read_b128 v[214:217], v142 offset:55296
	ds_read_b128 v[218:221], v142 offset:56320
	global_load_lds_dwordx4 v[186:187], off
	s_add_i32 m0, s48, 0x2000
	s_add_u32 s46, s46, 0x80100
	v_lshl_add_u64 v[186:187], v[222:223], 0, s[100:101]
	s_addc_u32 s47, s47, 0
	s_add_i32 s48, s49, s60
	global_load_lds_dwordx4 v[186:187], off
	v_lshl_add_u64 v[186:187], s[46:47], 0, v[176:177]
	s_mov_b32 m0, s48
	s_nop 0
	global_load_lds_dwordx4 v[186:187], off
	v_lshl_add_u64 v[186:187], s[46:47], 0, v[134:135]
	s_add_i32 m0, s48, 0x2000
	s_nop 0
	global_load_lds_dwordx4 v[186:187], off
	v_lshl_add_u64 v[186:187], v[224:225], 0, s[100:101]
	s_mov_b32 m0, s72
	s_nop 0
	global_load_lds_dwordx4 v[186:187], off
	v_lshl_add_u64 v[186:187], v[234:235], 0, s[100:101]
	s_mov_b32 m0, s73
	s_nop 0
	global_load_lds_dwordx4 v[186:187], off
	s_waitcnt vmcnt(8)
	s_waitcnt lgkmcnt(0)
	s_barrier
	s_waitcnt lgkmcnt(0)
	v_mfma_f32_16x16x32_bf16 v[60:63], v[144:147], v[190:193], v[60:63]
	v_mfma_f32_16x16x32_bf16 v[56:59], v[152:155], v[190:193], v[56:59]
	v_mfma_f32_16x16x32_bf16 v[52:55], v[144:147], v[198:201], v[52:55]
	v_mfma_f32_16x16x32_bf16 v[44:47], v[152:155], v[198:201], v[44:47]
	v_mfma_f32_16x16x32_bf16 v[36:39], v[144:147], v[206:209], v[36:39]
	v_mfma_f32_16x16x32_bf16 v[28:31], v[152:155], v[206:209], v[28:31]
	v_mfma_f32_16x16x32_bf16 v[20:23], v[144:147], v[214:217], v[20:23]
	v_mfma_f32_16x16x32_bf16 v[12:15], v[152:155], v[214:217], v[12:15]
	v_mfma_f32_16x16x32_bf16 v[60:63], v[148:151], v[194:197], v[60:63]
	v_mfma_f32_16x16x32_bf16 v[56:59], v[156:159], v[194:197], v[56:59]
	v_mfma_f32_16x16x32_bf16 v[52:55], v[148:151], v[202:205], v[52:55]
	v_mfma_f32_16x16x32_bf16 v[44:47], v[156:159], v[202:205], v[44:47]
	v_mfma_f32_16x16x32_bf16 v[36:39], v[148:151], v[210:213], v[36:39]
	v_mfma_f32_16x16x32_bf16 v[28:31], v[156:159], v[210:213], v[28:31]
	v_mfma_f32_16x16x32_bf16 v[20:23], v[148:151], v[218:221], v[20:23]
	v_mfma_f32_16x16x32_bf16 v[12:15], v[156:159], v[218:221], v[12:15]
	v_mfma_f32_16x16x32_bf16 v[48:51], v[160:163], v[190:193], v[48:51]
	v_mfma_f32_16x16x32_bf16 v[40:43], v[168:171], v[190:193], v[40:43]
	v_mfma_f32_16x16x32_bf16 v[32:35], v[160:163], v[198:201], v[32:35]
	v_mfma_f32_16x16x32_bf16 v[24:27], v[168:171], v[198:201], v[24:27]
	v_mfma_f32_16x16x32_bf16 v[16:19], v[160:163], v[206:209], v[16:19]
	v_mfma_f32_16x16x32_bf16 v[8:11], v[168:171], v[206:209], v[8:11]
	v_mfma_f32_16x16x32_bf16 v[4:7], v[160:163], v[214:217], v[4:7]
	v_mfma_f32_16x16x32_bf16 v[0:3], v[168:171], v[214:217], v[0:3]
	v_mfma_f32_16x16x32_bf16 v[48:51], v[164:167], v[194:197], v[48:51]
	v_mfma_f32_16x16x32_bf16 v[40:43], v[172:175], v[194:197], v[40:43]
	v_mfma_f32_16x16x32_bf16 v[32:35], v[164:167], v[202:205], v[32:35]
	v_mfma_f32_16x16x32_bf16 v[24:27], v[172:175], v[202:205], v[24:27]
	v_mfma_f32_16x16x32_bf16 v[16:19], v[164:167], v[210:213], v[16:19]
	v_mfma_f32_16x16x32_bf16 v[8:11], v[172:175], v[210:213], v[8:11]
	v_mfma_f32_16x16x32_bf16 v[4:7], v[164:167], v[218:221], v[4:7]
	v_mfma_f32_16x16x32_bf16 v[0:3], v[172:175], v[218:221], v[0:3]
	s_barrier
	s_add_i32 s78, s78, 2
	s_add_u32 s42, s42, 0x200
	s_addc_u32 s43, s43, 0
	s_cmp_gt_u32 s78, 13
	s_cbranch_scc0 .LBB0_569
	s_setprio 0
	s_cmpk_lt_u32 s59, 0x100
	s_cbranch_scc0 .Ldfs_a
	s_barrier

.LBB0_606:
	v_lshrrev_b32_e32 v15, 1, v140
	v_and_b32_e32 v129, 24, v15
	v_and_b32_e32 v14, 15, v140
	v_lshlrev_b32_e32 v15, 1, v129
	s_lshl_b32 s46, s46, 5
	v_lshl_or_b32 v128, s47, 6, v14
	v_lshl_or_b32 v14, v14, 6, v15
	v_lshlrev_b32_e32 v15, 2, v140
	s_and_b32 s71, s46, 0x60
	s_add_i32 m0, s61, 0x18000
	v_lshl_add_u64 v[6:7], v[6:7], 0, s[100:101]
	v_and_b32_e32 v15, 32, v15
	s_lshl_b32 s47, s47, 13
	s_lshl_b32 s46, s71, 7
	s_waitcnt vmcnt(2)
	s_barrier
	global_load_lds_dwordx4 v[6:7], off
	v_lshl_add_u64 v[4:5], v[4:5], 0, s[100:101]
	s_add_i32 m0, s61, 0x1a000
	s_add_i32 s72, s61, 0x8000
	s_add_i32 s73, s61, 0xa000
	v_bitop3_b32 v141, v14, s46, v15 bitop3:0xde
	global_load_lds_dwordx4 v[4:5], off
	v_lshl_add_u64 v[2:3], v[2:3], 0, s[100:101]
	s_mov_b32 m0, s72
	s_add_u32 s46, s40, 0x100100
	v_bitop3_b32 v16, v14, s47, v15 bitop3:0xde
	global_load_lds_dwordx4 v[2:3], off
	v_lshl_add_u64 v[0:1], v[0:1], 0, s[100:101]
	s_mov_b32 m0, s73
	s_addc_u32 s47, s41, 0
	global_load_lds_dwordx4 v[0:1], off
	s_add_i32 m0, s61, 0x1c000
	v_lshl_add_u64 v[0:1], s[46:47], 0, v[176:177]
	global_load_lds_dwordx4 v[0:1], off
	v_lshl_add_u64 v[0:1], s[46:47], 0, v[134:135]
	s_add_i32 m0, s61, 0x1e000
	s_lshl_b32 s46, s77, 20
	global_load_lds_dwordx4 v[0:1], off
	v_lshlrev_b32_e32 v0, 16, v11
	v_and_b32_e32 v0, 0xfffe0000, v0
	s_and_b32 s46, s46, 0x1e00000
	v_lshl_add_u32 v0, v12, 13, v0
	v_and_b32_e32 v1, 1, v11
	v_lshl_or_b32 v0, v1, 6, v0
	s_add_u32 s42, s42, s46
	v_lshl_add_u32 v0, v13, 1, v0
	v_mov_b32_e32 v1, v177
	s_addc_u32 s43, s43, 0
	v_lshl_add_u64 v[136:137], s[42:43], 0, v[0:1]
	v_lshlrev_b32_e32 v0, 16, v8
	v_and_b32_e32 v0, 0xfffe0000, v0
	v_lshl_add_u32 v0, v9, 13, v0
	v_and_b32_e32 v1, 1, v8
	v_lshl_or_b32 v0, v1, 6, v0
	s_waitcnt vmcnt(6)
	v_lshl_add_u32 v0, v10, 1, v0
	v_mov_b32_e32 v1, v177
	v_lshl_add_u64 v[138:139], s[42:43], 0, v[0:1]
	v_mov_b32_e32 v0, 0
	s_mov_b32 s78, -2
	s_mov_b64 s[42:43], 0x2c00100
	v_add_u32_e32 v142, 0, v16
	v_mov_b32_e32 v1, v0
	v_mov_b32_e32 v2, v0
	v_mov_b32_e32 v3, v0
	v_mov_b32_e32 v4, v0
	v_mov_b32_e32 v5, v0
	v_mov_b32_e32 v6, v0
	v_mov_b32_e32 v7, v0
	v_mov_b32_e32 v8, v0
	v_mov_b32_e32 v9, v0
	v_mov_b32_e32 v10, v0
	v_mov_b32_e32 v11, v0
	v_mov_b32_e32 v16, v0
	v_mov_b32_e32 v17, v0
	v_mov_b32_e32 v18, v0
	v_mov_b32_e32 v19, v0
	v_mov_b32_e32 v24, v0
	v_mov_b32_e32 v25, v0
	v_mov_b32_e32 v26, v0
	v_mov_b32_e32 v27, v0
	v_mov_b32_e32 v32, v0
	v_mov_b32_e32 v33, v0
	v_mov_b32_e32 v34, v0
	v_mov_b32_e32 v35, v0
	v_mov_b32_e32 v40, v0
	v_mov_b32_e32 v41, v0
	v_mov_b32_e32 v42, v0
	v_mov_b32_e32 v43, v0
	v_mov_b32_e32 v48, v0
	v_mov_b32_e32 v49, v0
	v_mov_b32_e32 v50, v0
	v_mov_b32_e32 v51, v0
	v_mov_b32_e32 v12, v0
	v_mov_b32_e32 v13, v0
	v_mov_b32_e32 v14, v0
	v_mov_b32_e32 v15, v0
	v_mov_b32_e32 v20, v0
	v_mov_b32_e32 v21, v0
	v_mov_b32_e32 v22, v0
	v_mov_b32_e32 v23, v0
	v_mov_b32_e32 v28, v0
	v_mov_b32_e32 v29, v0
	v_mov_b32_e32 v30, v0
	v_mov_b32_e32 v31, v0
	v_mov_b32_e32 v36, v0
	v_mov_b32_e32 v37, v0
	v_mov_b32_e32 v38, v0
	v_mov_b32_e32 v39, v0
	v_mov_b32_e32 v44, v0
	v_mov_b32_e32 v45, v0
	v_mov_b32_e32 v46, v0
	v_mov_b32_e32 v47, v0
	v_mov_b32_e32 v52, v0
	v_mov_b32_e32 v53, v0
	v_mov_b32_e32 v54, v0
	v_mov_b32_e32 v55, v0
	v_mov_b32_e32 v56, v0
	v_mov_b32_e32 v57, v0
	v_mov_b32_e32 v58, v0
	v_mov_b32_e32 v59, v0
	v_mov_b32_e32 v60, v0
	v_mov_b32_e32 v61, v0
	v_mov_b32_e32 v62, v0
	v_mov_b32_e32 v63, v0
	v_mov_b32_e32 v64, v0
	v_mov_b32_e32 v65, v0
	v_mov_b32_e32 v66, v0
	v_mov_b32_e32 v67, v0
	v_mov_b32_e32 v68, v0
	v_mov_b32_e32 v69, v0
	v_mov_b32_e32 v70, v0
	v_mov_b32_e32 v71, v0
	v_mov_b32_e32 v72, v0
	v_mov_b32_e32 v73, v0
	v_mov_b32_e32 v74, v0
	v_mov_b32_e32 v75, v0
	v_mov_b32_e32 v80, v0
	v_mov_b32_e32 v81, v0
	v_mov_b32_e32 v82, v0
	v_mov_b32_e32 v83, v0
	v_mov_b32_e32 v88, v0
	v_mov_b32_e32 v89, v0
	v_mov_b32_e32 v90, v0
	v_mov_b32_e32 v91, v0
	s_waitcnt vmcnt(0)
	v_mov_b32_e32 v96, v0
	v_mov_b32_e32 v97, v0
	v_mov_b32_e32 v98, v0
	v_mov_b32_e32 v99, v0
	v_mov_b32_e32 v112, v0
	v_mov_b32_e32 v113, v0
	v_mov_b32_e32 v114, v0
	v_mov_b32_e32 v115, v0
	v_mov_b32_e32 v116, v0
	v_mov_b32_e32 v117, v0
	v_mov_b32_e32 v118, v0
	v_mov_b32_e32 v119, v0
	v_mov_b32_e32 v76, v0
	v_mov_b32_e32 v77, v0
	v_mov_b32_e32 v78, v0
	v_mov_b32_e32 v79, v0
	v_mov_b32_e32 v84, v0
	v_mov_b32_e32 v85, v0
	v_mov_b32_e32 v86, v0
	v_mov_b32_e32 v87, v0
	v_mov_b32_e32 v92, v0
	v_mov_b32_e32 v93, v0
	v_mov_b32_e32 v94, v0
	v_mov_b32_e32 v95, v0
	v_mov_b32_e32 v100, v0
	v_mov_b32_e32 v101, v0
	v_mov_b32_e32 v102, v0
	v_mov_b32_e32 v103, v0
	v_mov_b32_e32 v104, v0
	v_mov_b32_e32 v105, v0
	v_mov_b32_e32 v106, v0
	v_mov_b32_e32 v107, v0
	v_mov_b32_e32 v108, v0
	v_mov_b32_e32 v109, v0
	v_mov_b32_e32 v110, v0
	v_mov_b32_e32 v111, v0
	v_mov_b32_e32 v120, v0
	v_mov_b32_e32 v121, v0
	v_mov_b32_e32 v122, v0
	v_mov_b32_e32 v123, v0
	v_mov_b32_e32 v124, v0
	v_mov_b32_e32 v125, v0
	v_mov_b32_e32 v126, v0
	v_mov_b32_e32 v127, v0
	s_barrier
	v_readfirstlane_b32 s46, v226
	s_nop 3
	s_bitcmp1_b32 s46, 8
	s_cbranch_scc0 .Lpr_607
	s_setprio 1
.Lpr_607:
.LBB0_607:
	s_add_u32 s46, s42, 0xfd400100
	s_addc_u32 s47, s43, -1
	s_andn2_b32 s48, 0x80, s42
	s_cmp_lg_u32 s78, 28
	s_cselect_b32 s46, s46, s48
	s_cselect_b32 s47, s47, 0
	s_add_u32 s68, s34, s46
	s_addc_u32 s69, s35, s47
	s_add_i32 s48, 0, 0x10000
	s_add_u32 s46, s40, s46
	v_add_u32_e32 v143, s48, v141
	s_addc_u32 s47, s41, s47
	s_add_i32 s49, 0, 0x14000
	ds_read_b128 v[144:147], v143
	ds_read_b128 v[148:151], v143 offset:1024
	ds_read_b128 v[152:155], v143 offset:2048
	ds_read_b128 v[156:159], v143 offset:3072
	v_add_u32_e32 v143, s49, v141
	ds_read_b128 v[160:163], v143
	ds_read_b128 v[164:167], v143 offset:1024
	ds_read_b128 v[168:171], v143 offset:2048
	ds_read_b128 v[172:175], v143 offset:3072
	v_lshl_add_u64 v[186:187], v[138:139], 0, s[42:43]
	s_add_i32 m0, s61, 0xc000
	ds_read_b128 v[190:193], v142
	ds_read_b128 v[194:197], v142 offset:1024
	ds_read_b128 v[198:201], v142 offset:2048
	ds_read_b128 v[202:205], v142 offset:3072
	ds_read_b128 v[206:209], v142 offset:4096
	ds_read_b128 v[210:213], v142 offset:5120
	ds_read_b128 v[214:217], v142 offset:6144
	ds_read_b128 v[218:221], v142 offset:7168
	global_load_lds_dwordx4 v[186:187], off
	v_lshl_add_u64 v[186:187], v[136:137], 0, s[42:43]
	s_add_i32 m0, s61, 0xe000
	s_nop 0
	global_load_lds_dwordx4 v[186:187], off
	s_waitcnt vmcnt(8)
	s_waitcnt lgkmcnt(0)
	s_barrier
	s_waitcnt lgkmcnt(0)
	v_mfma_f32_16x16x32_bf16 v[124:127], v[144:147], v[190:193], v[124:127]
	v_mfma_f32_16x16x32_bf16 v[120:123], v[152:155], v[190:193], v[120:123]
	v_mfma_f32_16x16x32_bf16 v[108:111], v[144:147], v[198:201], v[108:111]
	v_mfma_f32_16x16x32_bf16 v[104:107], v[152:155], v[198:201], v[104:107]
	v_mfma_f32_16x16x32_bf16 v[100:103], v[144:147], v[206:209], v[100:103]
	v_mfma_f32_16x16x32_bf16 v[92:95], v[152:155], v[206:209], v[92:95]
	v_mfma_f32_16x16x32_bf16 v[84:87], v[144:147], v[214:217], v[84:87]
	v_mfma_f32_16x16x32_bf16 v[76:79], v[152:155], v[214:217], v[76:79]
	v_mfma_f32_16x16x32_bf16 v[124:127], v[148:151], v[194:197], v[124:127]
	v_mfma_f32_16x16x32_bf16 v[120:123], v[156:159], v[194:197], v[120:123]
	v_mfma_f32_16x16x32_bf16 v[108:111], v[148:151], v[202:205], v[108:111]
	v_mfma_f32_16x16x32_bf16 v[104:107], v[156:159], v[202:205], v[104:107]
	v_mfma_f32_16x16x32_bf16 v[100:103], v[148:151], v[210:213], v[100:103]
	v_mfma_f32_16x16x32_bf16 v[92:95], v[156:159], v[210:213], v[92:95]
	v_mfma_f32_16x16x32_bf16 v[84:87], v[148:151], v[218:221], v[84:87]
	v_mfma_f32_16x16x32_bf16 v[76:79], v[156:159], v[218:221], v[76:79]
	v_mfma_f32_16x16x32_bf16 v[116:119], v[160:163], v[190:193], v[116:119]
	v_mfma_f32_16x16x32_bf16 v[112:115], v[168:171], v[190:193], v[112:115]
	v_mfma_f32_16x16x32_bf16 v[96:99], v[160:163], v[198:201], v[96:99]
	v_mfma_f32_16x16x32_bf16 v[88:91], v[168:171], v[198:201], v[88:91]
	v_mfma_f32_16x16x32_bf16 v[80:83], v[160:163], v[206:209], v[80:83]
	v_mfma_f32_16x16x32_bf16 v[72:75], v[168:171], v[206:209], v[72:75]
	v_mfma_f32_16x16x32_bf16 v[68:71], v[160:163], v[214:217], v[68:71]
	v_mfma_f32_16x16x32_bf16 v[64:67], v[168:171], v[214:217], v[64:67]
	v_mfma_f32_16x16x32_bf16 v[116:119], v[164:167], v[194:197], v[116:119]
	v_mfma_f32_16x16x32_bf16 v[112:115], v[172:175], v[194:197], v[112:115]
	v_mfma_f32_16x16x32_bf16 v[96:99], v[164:167], v[202:205], v[96:99]
	v_mfma_f32_16x16x32_bf16 v[88:91], v[172:175], v[202:205], v[88:91]
	v_mfma_f32_16x16x32_bf16 v[80:83], v[164:167], v[210:213], v[80:83]
	v_mfma_f32_16x16x32_bf16 v[72:75], v[172:175], v[210:213], v[72:75]
	v_mfma_f32_16x16x32_bf16 v[68:71], v[164:167], v[218:221], v[68:71]
	v_mfma_f32_16x16x32_bf16 v[64:67], v[172:175], v[218:221], v[64:67]
	s_barrier
	s_add_i32 s48, s48, s60
	v_lshl_add_u64 v[186:187], s[46:47], 0, v[176:177]
	s_mov_b32 m0, s48
	ds_read_b128 v[190:193], v142 offset:16384
	ds_read_b128 v[194:197], v142 offset:17408
	ds_read_b128 v[198:201], v142 offset:18432
	ds_read_b128 v[202:205], v142 offset:19456
	ds_read_b128 v[206:209], v142 offset:20480
	ds_read_b128 v[210:213], v142 offset:21504
	ds_read_b128 v[214:217], v142 offset:22528
	ds_read_b128 v[218:221], v142 offset:23552
	global_load_lds_dwordx4 v[186:187], off
	s_add_i32 m0, s48, 0x2000
	s_add_u32 s80, s46, 0x100000
	v_lshl_add_u64 v[222:223], s[46:47], 0, v[134:135]
	s_addc_u32 s81, s47, 0
	s_add_i32 s48, s49, s60
	global_load_lds_dwordx4 v[222:223], off
	v_lshl_add_u64 v[224:225], s[80:81], 0, v[176:177]
	s_mov_b32 m0, s48
	v_lshl_add_u64 v[234:235], s[68:69], 0, v[132:133]
	global_load_lds_dwordx4 v[224:225], off
	v_lshl_add_u64 v[224:225], s[80:81], 0, v[134:135]
	s_add_i32 m0, s48, 0x2000
	s_nop 0
	global_load_lds_dwordx4 v[224:225], off
	v_lshl_add_u64 v[224:225], s[68:69], 0, v[130:131]
	s_mov_b32 m0, s61
	s_nop 0
	global_load_lds_dwordx4 v[224:225], off
	s_mov_b32 m0, s62
	s_nop 0
	global_load_lds_dwordx4 v[234:235], off
	s_waitcnt vmcnt(8)
	s_waitcnt lgkmcnt(0)
	s_barrier
	s_waitcnt lgkmcnt(0)
	v_mfma_f32_16x16x32_bf16 v[60:63], v[144:147], v[190:193], v[60:63]
	v_mfma_f32_16x16x32_bf16 v[56:59], v[152:155], v[190:193], v[56:59]
	v_mfma_f32_16x16x32_bf16 v[52:55], v[144:147], v[198:201], v[52:55]
	v_mfma_f32_16x16x32_bf16 v[44:47], v[152:155], v[198:201], v[44:47]
	v_mfma_f32_16x16x32_bf16 v[36:39], v[144:147], v[206:209], v[36:39]
	v_mfma_f32_16x16x32_bf16 v[28:31], v[152:155], v[206:209], v[28:31]
	v_mfma_f32_16x16x32_bf16 v[20:23], v[144:147], v[214:217], v[20:23]
	v_mfma_f32_16x16x32_bf16 v[12:15], v[152:155], v[214:217], v[12:15]
	v_mfma_f32_16x16x32_bf16 v[60:63], v[148:151], v[194:197], v[60:63]
	v_mfma_f32_16x16x32_bf16 v[56:59], v[156:159], v[194:197], v[56:59]
	v_mfma_f32_16x16x32_bf16 v[52:55], v[148:151], v[202:205], v[52:55]
	v_mfma_f32_16x16x32_bf16 v[44:47], v[156:159], v[202:205], v[44:47]
	v_mfma_f32_16x16x32_bf16 v[36:39], v[148:151], v[210:213], v[36:39]
	v_mfma_f32_16x16x32_bf16 v[28:31], v[156:159], v[210:213], v[28:31]
	v_mfma_f32_16x16x32_bf16 v[20:23], v[148:151], v[218:221], v[20:23]
	v_mfma_f32_16x16x32_bf16 v[12:15], v[156:159], v[218:221], v[12:15]
	v_mfma_f32_16x16x32_bf16 v[48:51], v[160:163], v[190:193], v[48:51]
	v_mfma_f32_16x16x32_bf16 v[40:43], v[168:171], v[190:193], v[40:43]
	v_mfma_f32_16x16x32_bf16 v[32:35], v[160:163], v[198:201], v[32:35]
	v_mfma_f32_16x16x32_bf16 v[24:27], v[168:171], v[198:201], v[24:27]
	v_mfma_f32_16x16x32_bf16 v[16:19], v[160:163], v[206:209], v[16:19]
	v_mfma_f32_16x16x32_bf16 v[8:11], v[168:171], v[206:209], v[8:11]
	v_mfma_f32_16x16x32_bf16 v[4:7], v[160:163], v[214:217], v[4:7]
	v_mfma_f32_16x16x32_bf16 v[0:3], v[168:171], v[214:217], v[0:3]
	v_mfma_f32_16x16x32_bf16 v[48:51], v[164:167], v[194:197], v[48:51]
	v_mfma_f32_16x16x32_bf16 v[40:43], v[172:175], v[194:197], v[40:43]
	v_mfma_f32_16x16x32_bf16 v[32:35], v[164:167], v[202:205], v[32:35]
	v_mfma_f32_16x16x32_bf16 v[24:27], v[172:175], v[202:205], v[24:27]
	v_mfma_f32_16x16x32_bf16 v[16:19], v[164:167], v[210:213], v[16:19]
	v_mfma_f32_16x16x32_bf16 v[8:11], v[172:175], v[210:213], v[8:11]
	v_mfma_f32_16x16x32_bf16 v[4:7], v[164:167], v[218:221], v[4:7]
	v_mfma_f32_16x16x32_bf16 v[0:3], v[172:175], v[218:221], v[0:3]
	s_barrier
	s_add_i32 s48, 0, 0x18000
	v_add_u32_e32 v143, s48, v141
	s_add_i32 s49, 0, 0x1c000
	ds_read_b128 v[144:147], v143
	ds_read_b128 v[148:151], v143 offset:1024
	ds_read_b128 v[152:155], v143 offset:2048
	ds_read_b128 v[156:159], v143 offset:3072
	v_add_u32_e32 v143, s49, v141
	ds_read_b128 v[160:163], v143
	ds_read_b128 v[164:167], v143 offset:1024
	ds_read_b128 v[168:171], v143 offset:2048
	ds_read_b128 v[172:175], v143 offset:3072
	s_add_u32 s68, s68, 0x100000
	s_addc_u32 s69, s69, 0
	s_mov_b32 m0, s63
	v_lshl_add_u64 v[236:237], s[68:69], 0, v[130:131]
	ds_read_b128 v[190:193], v142 offset:32768
	ds_read_b128 v[194:197], v142 offset:33792
	ds_read_b128 v[198:201], v142 offset:34816
	ds_read_b128 v[202:205], v142 offset:35840
	ds_read_b128 v[206:209], v142 offset:36864
	ds_read_b128 v[210:213], v142 offset:37888
	ds_read_b128 v[214:217], v142 offset:38912
	ds_read_b128 v[218:221], v142 offset:39936
	global_load_lds_dwordx4 v[236:237], off
	v_lshl_add_u64 v[236:237], s[68:69], 0, v[132:133]
	s_mov_b32 m0, s70
	s_nop 0
	global_load_lds_dwordx4 v[236:237], off
	s_waitcnt vmcnt(8)
	s_waitcnt lgkmcnt(0)
	s_barrier
	s_waitcnt lgkmcnt(0)
	v_mfma_f32_16x16x32_bf16 v[124:127], v[144:147], v[190:193], v[124:127]
	v_mfma_f32_16x16x32_bf16 v[120:123], v[152:155], v[190:193], v[120:123]
	v_mfma_f32_16x16x32_bf16 v[108:111], v[144:147], v[198:201], v[108:111]
	v_mfma_f32_16x16x32_bf16 v[104:107], v[152:155], v[198:201], v[104:107]
	v_mfma_f32_16x16x32_bf16 v[100:103], v[144:147], v[206:209], v[100:103]
	v_mfma_f32_16x16x32_bf16 v[92:95], v[152:155], v[206:209], v[92:95]
	v_mfma_f32_16x16x32_bf16 v[84:87], v[144:147], v[214:217], v[84:87]
	v_mfma_f32_16x16x32_bf16 v[76:79], v[152:155], v[214:217], v[76:79]
	v_mfma_f32_16x16x32_bf16 v[124:127], v[148:151], v[194:197], v[124:127]
	v_mfma_f32_16x16x32_bf16 v[120:123], v[156:159], v[194:197], v[120:123]
	v_mfma_f32_16x16x32_bf16 v[108:111], v[148:151], v[202:205], v[108:111]
	v_mfma_f32_16x16x32_bf16 v[104:107], v[156:159], v[202:205], v[104:107]
	v_mfma_f32_16x16x32_bf16 v[100:103], v[148:151], v[210:213], v[100:103]
	v_mfma_f32_16x16x32_bf16 v[92:95], v[156:159], v[210:213], v[92:95]
	v_mfma_f32_16x16x32_bf16 v[84:87], v[148:151], v[218:221], v[84:87]
	v_mfma_f32_16x16x32_bf16 v[76:79], v[156:159], v[218:221], v[76:79]
	v_mfma_f32_16x16x32_bf16 v[116:119], v[160:163], v[190:193], v[116:119]
	v_mfma_f32_16x16x32_bf16 v[112:115], v[168:171], v[190:193], v[112:115]
	v_mfma_f32_16x16x32_bf16 v[96:99], v[160:163], v[198:201], v[96:99]
	v_mfma_f32_16x16x32_bf16 v[88:91], v[168:171], v[198:201], v[88:91]
	v_mfma_f32_16x16x32_bf16 v[80:83], v[160:163], v[206:209], v[80:83]
	v_mfma_f32_16x16x32_bf16 v[72:75], v[168:171], v[206:209], v[72:75]
	v_mfma_f32_16x16x32_bf16 v[68:71], v[160:163], v[214:217], v[68:71]
	v_mfma_f32_16x16x32_bf16 v[64:67], v[168:171], v[214:217], v[64:67]
	v_mfma_f32_16x16x32_bf16 v[116:119], v[164:167], v[194:197], v[116:119]
	v_mfma_f32_16x16x32_bf16 v[112:115], v[172:175], v[194:197], v[112:115]
	v_mfma_f32_16x16x32_bf16 v[96:99], v[164:167], v[202:205], v[96:99]
	v_mfma_f32_16x16x32_bf16 v[88:91], v[172:175], v[202:205], v[88:91]
	v_mfma_f32_16x16x32_bf16 v[80:83], v[164:167], v[210:213], v[80:83]
	v_mfma_f32_16x16x32_bf16 v[72:75], v[172:175], v[210:213], v[72:75]
	v_mfma_f32_16x16x32_bf16 v[68:71], v[164:167], v[218:221], v[68:71]
	v_mfma_f32_16x16x32_bf16 v[64:67], v[172:175], v[218:221], v[64:67]
	s_barrier
	s_add_i32 s48, s48, s60
	v_lshl_add_u64 v[186:187], v[186:187], 0, s[100:101]
	s_mov_b32 m0, s48
	ds_read_b128 v[190:193], v142 offset:49152
	ds_read_b128 v[194:197], v142 offset:50176
	ds_read_b128 v[198:201], v142 offset:51200
	ds_read_b128 v[202:205], v142 offset:52224
	ds_read_b128 v[206:209], v142 offset:53248
	ds_read_b128 v[210:213], v142 offset:54272
	ds_read_b128 v[214:217], v142 offset:55296
	ds_read_b128 v[218:221], v142 offset:56320
	global_load_lds_dwordx4 v[186:187], off
	s_add_i32 m0, s48, 0x2000
	s_add_u32 s46, s46, 0x100100
	v_lshl_add_u64 v[186:187], v[222:223], 0, s[100:101]
	s_addc_u32 s47, s47, 0
	s_add_i32 s48, s49, s60
	global_load_lds_dwordx4 v[186:187], off
	v_lshl_add_u64 v[186:187], s[46:47], 0, v[176:177]
	s_mov_b32 m0, s48
	s_nop 0
	global_load_lds_dwordx4 v[186:187], off
	v_lshl_add_u64 v[186:187], s[46:47], 0, v[134:135]
	s_add_i32 m0, s48, 0x2000
	s_nop 0
	global_load_lds_dwordx4 v[186:187], off
	v_lshl_add_u64 v[186:187], v[224:225], 0, s[100:101]
	s_mov_b32 m0, s72
	s_nop 0
	global_load_lds_dwordx4 v[186:187], off
	v_lshl_add_u64 v[186:187], v[234:235], 0, s[100:101]
	s_mov_b32 m0, s73
	s_nop 0
	global_load_lds_dwordx4 v[186:187], off
	s_waitcnt vmcnt(8)
	s_waitcnt lgkmcnt(0)
	s_barrier
	s_waitcnt lgkmcnt(0)
	v_mfma_f32_16x16x32_bf16 v[60:63], v[144:147], v[190:193], v[60:63]
	v_mfma_f32_16x16x32_bf16 v[56:59], v[152:155], v[190:193], v[56:59]
	v_mfma_f32_16x16x32_bf16 v[52:55], v[144:147], v[198:201], v[52:55]
	v_mfma_f32_16x16x32_bf16 v[44:47], v[152:155], v[198:201], v[44:47]
	v_mfma_f32_16x16x32_bf16 v[36:39], v[144:147], v[206:209], v[36:39]
	v_mfma_f32_16x16x32_bf16 v[28:31], v[152:155], v[206:209], v[28:31]
	v_mfma_f32_16x16x32_bf16 v[20:23], v[144:147], v[214:217], v[20:23]
	v_mfma_f32_16x16x32_bf16 v[12:15], v[152:155], v[214:217], v[12:15]
	v_mfma_f32_16x16x32_bf16 v[60:63], v[148:151], v[194:197], v[60:63]
	v_mfma_f32_16x16x32_bf16 v[56:59], v[156:159], v[194:197], v[56:59]
	v_mfma_f32_16x16x32_bf16 v[52:55], v[148:151], v[202:205], v[52:55]
	v_mfma_f32_16x16x32_bf16 v[44:47], v[156:159], v[202:205], v[44:47]
	v_mfma_f32_16x16x32_bf16 v[36:39], v[148:151], v[210:213], v[36:39]
	v_mfma_f32_16x16x32_bf16 v[28:31], v[156:159], v[210:213], v[28:31]
	v_mfma_f32_16x16x32_bf16 v[20:23], v[148:151], v[218:221], v[20:23]
	v_mfma_f32_16x16x32_bf16 v[12:15], v[156:159], v[218:221], v[12:15]
	v_mfma_f32_16x16x32_bf16 v[48:51], v[160:163], v[190:193], v[48:51]
	v_mfma_f32_16x16x32_bf16 v[40:43], v[168:171], v[190:193], v[40:43]
	v_mfma_f32_16x16x32_bf16 v[32:35], v[160:163], v[198:201], v[32:35]
	v_mfma_f32_16x16x32_bf16 v[24:27], v[168:171], v[198:201], v[24:27]
	v_mfma_f32_16x16x32_bf16 v[16:19], v[160:163], v[206:209], v[16:19]
	v_mfma_f32_16x16x32_bf16 v[8:11], v[168:171], v[206:209], v[8:11]
	v_mfma_f32_16x16x32_bf16 v[4:7], v[160:163], v[214:217], v[4:7]
	v_mfma_f32_16x16x32_bf16 v[0:3], v[168:171], v[214:217], v[0:3]
	v_mfma_f32_16x16x32_bf16 v[48:51], v[164:167], v[194:197], v[48:51]
	v_mfma_f32_16x16x32_bf16 v[40:43], v[172:175], v[194:197], v[40:43]
	v_mfma_f32_16x16x32_bf16 v[32:35], v[164:167], v[202:205], v[32:35]
	v_mfma_f32_16x16x32_bf16 v[24:27], v[172:175], v[202:205], v[24:27]
	v_mfma_f32_16x16x32_bf16 v[16:19], v[164:167], v[210:213], v[16:19]
	v_mfma_f32_16x16x32_bf16 v[8:11], v[172:175], v[210:213], v[8:11]
	v_mfma_f32_16x16x32_bf16 v[4:7], v[164:167], v[218:221], v[4:7]
	v_mfma_f32_16x16x32_bf16 v[0:3], v[172:175], v[218:221], v[0:3]
	s_barrier
	s_add_i32 s78, s78, 2
	s_add_u32 s42, s42, 0x200
	s_addc_u32 s43, s43, 0
	s_cmp_gt_u32 s78, 29
	s_cbranch_scc0 .LBB0_607
	s_setprio 0
	s_cmpk_lt_u32 s59, 0x100
	s_cbranch_scc0 .Ldfl_a
	s_barrier

.LBB0_697:
	s_ashr_i32 s39, s38, 31
	s_lshl_b64 s[42:43], s[38:39], 19
	s_add_u32 s42, s3, s42
	s_addc_u32 s43, s22, s43
	s_and_b64 s[44:45], s[40:41], exec
	s_cselect_b32 s39, s43, s69
	s_cselect_b32 s82, s42, s68
	s_ashr_i32 s37, s36, 31
	s_lshl_b64 s[44:45], s[36:37], 19
	s_add_u32 s44, s58, s44
	s_addc_u32 s45, s59, s45
	s_and_b64 s[70:71], s[40:41], exec
	s_cselect_b32 s37, s45, s47
	s_cselect_b32 s83, s44, s46
	s_add_u32 s86, s46, 0x100
	s_addc_u32 s87, s47, 0
	s_add_u32 s46, s68, 0x40080
	v_mov_b32_e32 v0, 0
	s_addc_u32 s47, s69, 0
	s_mov_b32 s90, -2
	v_mov_b32_e32 v1, v0
	v_mov_b32_e32 v2, v0
	v_mov_b32_e32 v3, v0
	v_mov_b32_e32 v4, v0
	v_mov_b32_e32 v5, v0
	v_mov_b32_e32 v6, v0
	v_mov_b32_e32 v7, v0
	v_mov_b32_e32 v12, v0
	v_mov_b32_e32 v13, v0
	v_mov_b32_e32 v14, v0
	v_mov_b32_e32 v15, v0
	v_mov_b32_e32 v20, v0
	v_mov_b32_e32 v21, v0
	v_mov_b32_e32 v22, v0
	v_mov_b32_e32 v23, v0
	v_mov_b32_e32 v28, v0
	v_mov_b32_e32 v29, v0
	v_mov_b32_e32 v30, v0
	v_mov_b32_e32 v31, v0
	v_mov_b32_e32 v36, v0
	v_mov_b32_e32 v37, v0
	v_mov_b32_e32 v38, v0
	v_mov_b32_e32 v39, v0
	v_mov_b32_e32 v44, v0
	v_mov_b32_e32 v45, v0
	v_mov_b32_e32 v46, v0
	v_mov_b32_e32 v47, v0
	v_mov_b32_e32 v52, v0
	v_mov_b32_e32 v53, v0
	v_mov_b32_e32 v54, v0
	v_mov_b32_e32 v55, v0
	v_mov_b32_e32 v8, v0
	v_mov_b32_e32 v9, v0
	v_mov_b32_e32 v10, v0
	v_mov_b32_e32 v11, v0
	v_mov_b32_e32 v16, v0
	v_mov_b32_e32 v17, v0
	v_mov_b32_e32 v18, v0
	v_mov_b32_e32 v19, v0
	v_mov_b32_e32 v24, v0
	v_mov_b32_e32 v25, v0
	v_mov_b32_e32 v26, v0
	v_mov_b32_e32 v27, v0
	v_mov_b32_e32 v32, v0
	v_mov_b32_e32 v33, v0
	v_mov_b32_e32 v34, v0
	v_mov_b32_e32 v35, v0
	v_mov_b32_e32 v40, v0
	v_mov_b32_e32 v41, v0
	v_mov_b32_e32 v42, v0
	v_mov_b32_e32 v43, v0
	v_mov_b32_e32 v48, v0
	v_mov_b32_e32 v49, v0
	v_mov_b32_e32 v50, v0
	v_mov_b32_e32 v51, v0
	v_mov_b32_e32 v56, v0
	v_mov_b32_e32 v57, v0
	v_mov_b32_e32 v58, v0
	v_mov_b32_e32 v59, v0
	v_mov_b32_e32 v60, v0
	v_mov_b32_e32 v61, v0
	v_mov_b32_e32 v62, v0
	v_mov_b32_e32 v63, v0
	v_mov_b32_e32 v64, v0
	v_mov_b32_e32 v65, v0
	v_mov_b32_e32 v66, v0
	v_mov_b32_e32 v67, v0
	v_mov_b32_e32 v68, v0
	v_mov_b32_e32 v69, v0
	v_mov_b32_e32 v70, v0
	v_mov_b32_e32 v71, v0
	v_mov_b32_e32 v76, v0
	v_mov_b32_e32 v77, v0
	v_mov_b32_e32 v78, v0
	v_mov_b32_e32 v79, v0
	v_mov_b32_e32 v84, v0
	v_mov_b32_e32 v85, v0
	v_mov_b32_e32 v86, v0
	v_mov_b32_e32 v87, v0
	v_mov_b32_e32 v92, v0
	v_mov_b32_e32 v93, v0
	v_mov_b32_e32 v94, v0
	v_mov_b32_e32 v95, v0
	s_waitcnt vmcnt(0)
	v_mov_b32_e32 v100, v0
	v_mov_b32_e32 v101, v0
	v_mov_b32_e32 v102, v0
	v_mov_b32_e32 v103, v0
	v_mov_b32_e32 v128, v0
	v_mov_b32_e32 v129, v0
	v_mov_b32_e32 v130, v0
	v_mov_b32_e32 v131, v0
	v_mov_b32_e32 v132, v0
	v_mov_b32_e32 v133, v0
	v_mov_b32_e32 v134, v0
	v_mov_b32_e32 v135, v0
	v_mov_b32_e32 v72, v0
	v_mov_b32_e32 v73, v0
	v_mov_b32_e32 v74, v0
	v_mov_b32_e32 v75, v0
	v_mov_b32_e32 v80, v0
	v_mov_b32_e32 v81, v0
	v_mov_b32_e32 v82, v0
	v_mov_b32_e32 v83, v0
	v_mov_b32_e32 v88, v0
	v_mov_b32_e32 v89, v0
	v_mov_b32_e32 v90, v0
	v_mov_b32_e32 v91, v0
	v_mov_b32_e32 v96, v0
	v_mov_b32_e32 v97, v0
	v_mov_b32_e32 v98, v0
	v_mov_b32_e32 v99, v0
	v_mov_b32_e32 v112, v0
	v_mov_b32_e32 v113, v0
	v_mov_b32_e32 v114, v0
	v_mov_b32_e32 v115, v0
	v_mov_b32_e32 v124, v0
	v_mov_b32_e32 v125, v0
	v_mov_b32_e32 v126, v0
	v_mov_b32_e32 v127, v0
	v_mov_b32_e32 v136, v0
	v_mov_b32_e32 v137, v0
	v_mov_b32_e32 v138, v0
	v_mov_b32_e32 v139, v0
	v_mov_b32_e32 v140, v0
	v_mov_b32_e32 v141, v0
	v_mov_b32_e32 v142, v0
	v_mov_b32_e32 v143, v0
	v_readfirstlane_b32 s48, v226
	s_nop 3
	s_bitcmp1_b32 s48, 8
	s_cbranch_scc0 .Lpr_698
	s_setprio 1
.Lpr_698:
.LBB0_698:
	s_add_u32 s48, s46, 0xfffc0080
	s_addc_u32 s49, s47, -1
	s_add_i32 s91, 0, 0x10000
	s_cmp_eq_u32 s90, 12
	s_cselect_b32 s71, s39, s49
	s_cselect_b32 s70, s82, s48
	s_cselect_b32 s69, s37, s87
	s_cselect_b32 s68, s83, s86
	s_add_i32 s48, 0, 0x14000
	v_add_u32_e32 v120, s91, v200
	v_add_u32_e32 v156, s48, v200
	ds_read_b128 v[104:107], v120
	ds_read_b128 v[108:111], v120 offset:1024
	ds_read_b128 v[116:119], v120 offset:2048
	ds_read_b128 v[120:123], v120 offset:3072
	ds_read_b128 v[144:147], v156
	ds_read_b128 v[148:151], v156 offset:1024
	ds_read_b128 v[152:155], v156 offset:2048
	ds_read_b128 v[156:159], v156 offset:3072
	v_lshl_add_u64 v[174:175], s[46:47], 0, v[172:173]
	s_add_i32 m0, s61, 0xc000
	ds_read_b128 v[160:163], v201
	ds_read_b128 v[190:193], v201 offset:1024
	ds_read_b128 v[194:197], v201 offset:2048
	ds_read_b128 v[202:205], v201 offset:3072
	ds_read_b128 v[206:209], v201 offset:4096
	ds_read_b128 v[210:213], v201 offset:5120
	ds_read_b128 v[214:217], v201 offset:6144
	ds_read_b128 v[218:221], v201 offset:7168
	global_load_lds_dwordx4 v[174:175], off
	v_lshl_add_u64 v[174:175], s[46:47], 0, v[170:171]
	s_add_i32 m0, s61, 0xe000
	s_nop 0
	global_load_lds_dwordx4 v[174:175], off
	s_waitcnt vmcnt(8)
	s_waitcnt lgkmcnt(0)
	s_barrier
	s_waitcnt lgkmcnt(0)
	v_mfma_f32_16x16x32_bf16 v[140:143], v[104:107], v[160:163], v[140:143]
	v_mfma_f32_16x16x32_bf16 v[136:139], v[116:119], v[160:163], v[136:139]
	v_mfma_f32_16x16x32_bf16 v[124:127], v[104:107], v[194:197], v[124:127]
	v_mfma_f32_16x16x32_bf16 v[112:115], v[116:119], v[194:197], v[112:115]
	v_mfma_f32_16x16x32_bf16 v[96:99], v[104:107], v[206:209], v[96:99]
	v_mfma_f32_16x16x32_bf16 v[88:91], v[116:119], v[206:209], v[88:91]
	v_mfma_f32_16x16x32_bf16 v[80:83], v[104:107], v[214:217], v[80:83]
	v_mfma_f32_16x16x32_bf16 v[72:75], v[116:119], v[214:217], v[72:75]
	v_mfma_f32_16x16x32_bf16 v[140:143], v[108:111], v[190:193], v[140:143]
	v_mfma_f32_16x16x32_bf16 v[136:139], v[120:123], v[190:193], v[136:139]
	v_mfma_f32_16x16x32_bf16 v[124:127], v[108:111], v[202:205], v[124:127]
	v_mfma_f32_16x16x32_bf16 v[112:115], v[120:123], v[202:205], v[112:115]
	v_mfma_f32_16x16x32_bf16 v[96:99], v[108:111], v[210:213], v[96:99]
	v_mfma_f32_16x16x32_bf16 v[88:91], v[120:123], v[210:213], v[88:91]
	v_mfma_f32_16x16x32_bf16 v[80:83], v[108:111], v[218:221], v[80:83]
	v_mfma_f32_16x16x32_bf16 v[72:75], v[120:123], v[218:221], v[72:75]
	v_mfma_f32_16x16x32_bf16 v[132:135], v[144:147], v[160:163], v[132:135]
	v_mfma_f32_16x16x32_bf16 v[128:131], v[152:155], v[160:163], v[128:131]
	v_mfma_f32_16x16x32_bf16 v[100:103], v[144:147], v[194:197], v[100:103]
	v_mfma_f32_16x16x32_bf16 v[92:95], v[152:155], v[194:197], v[92:95]
	v_mfma_f32_16x16x32_bf16 v[84:87], v[144:147], v[206:209], v[84:87]
	v_mfma_f32_16x16x32_bf16 v[76:79], v[152:155], v[206:209], v[76:79]
	v_mfma_f32_16x16x32_bf16 v[68:71], v[144:147], v[214:217], v[68:71]
	v_mfma_f32_16x16x32_bf16 v[64:67], v[152:155], v[214:217], v[64:67]
	v_mfma_f32_16x16x32_bf16 v[132:135], v[148:151], v[190:193], v[132:135]
	v_mfma_f32_16x16x32_bf16 v[128:131], v[156:159], v[190:193], v[128:131]
	v_mfma_f32_16x16x32_bf16 v[100:103], v[148:151], v[202:205], v[100:103]
	v_mfma_f32_16x16x32_bf16 v[92:95], v[156:159], v[202:205], v[92:95]
	v_mfma_f32_16x16x32_bf16 v[84:87], v[148:151], v[210:213], v[84:87]
	v_mfma_f32_16x16x32_bf16 v[76:79], v[156:159], v[210:213], v[76:79]
	v_mfma_f32_16x16x32_bf16 v[68:71], v[148:151], v[218:221], v[68:71]
	v_mfma_f32_16x16x32_bf16 v[64:67], v[156:159], v[218:221], v[64:67]
	s_barrier
	s_add_i32 s49, s91, s60
	v_lshl_add_u64 v[174:175], s[68:69], 0, v[176:177]
	s_mov_b32 m0, s49
	ds_read_b128 v[160:163], v201 offset:16384
	ds_read_b128 v[190:193], v201 offset:17408
	ds_read_b128 v[194:197], v201 offset:18432
	ds_read_b128 v[202:205], v201 offset:19456
	ds_read_b128 v[206:209], v201 offset:20480
	ds_read_b128 v[210:213], v201 offset:21504
	ds_read_b128 v[214:217], v201 offset:22528
	ds_read_b128 v[218:221], v201 offset:23552
	global_load_lds_dwordx4 v[174:175], off
	s_add_i32 m0, s49, 0x2000
	s_add_u32 s96, s68, 0x40000
	v_lshl_add_u64 v[186:187], s[68:69], 0, v[164:165]
	s_addc_u32 s97, s69, 0
	s_add_i32 s48, s48, s60
	global_load_lds_dwordx4 v[186:187], off
	v_lshl_add_u64 v[222:223], s[96:97], 0, v[176:177]
	s_mov_b32 m0, s48
	v_lshl_add_u64 v[224:225], s[70:71], 0, v[166:167]
	global_load_lds_dwordx4 v[222:223], off
	v_lshl_add_u64 v[222:223], s[96:97], 0, v[164:165]
	s_add_i32 m0, s48, 0x2000
	s_nop 0
	global_load_lds_dwordx4 v[222:223], off
	v_lshl_add_u64 v[222:223], s[70:71], 0, v[168:169]
	s_mov_b32 m0, s61
	s_nop 0
	global_load_lds_dwordx4 v[222:223], off
	s_mov_b32 m0, s62
	s_nop 0
	global_load_lds_dwordx4 v[224:225], off
	s_waitcnt vmcnt(8)
	s_waitcnt lgkmcnt(0)
	s_barrier
	s_waitcnt lgkmcnt(0)
	v_mfma_f32_16x16x32_bf16 v[60:63], v[104:107], v[160:163], v[60:63]
	v_mfma_f32_16x16x32_bf16 v[56:59], v[116:119], v[160:163], v[56:59]
	v_mfma_f32_16x16x32_bf16 v[48:51], v[104:107], v[194:197], v[48:51]
	v_mfma_f32_16x16x32_bf16 v[40:43], v[116:119], v[194:197], v[40:43]
	v_mfma_f32_16x16x32_bf16 v[32:35], v[104:107], v[206:209], v[32:35]
	v_mfma_f32_16x16x32_bf16 v[24:27], v[116:119], v[206:209], v[24:27]
	v_mfma_f32_16x16x32_bf16 v[16:19], v[104:107], v[214:217], v[16:19]
	v_mfma_f32_16x16x32_bf16 v[8:11], v[116:119], v[214:217], v[8:11]
	v_mfma_f32_16x16x32_bf16 v[60:63], v[108:111], v[190:193], v[60:63]
	v_mfma_f32_16x16x32_bf16 v[56:59], v[120:123], v[190:193], v[56:59]
	v_mfma_f32_16x16x32_bf16 v[48:51], v[108:111], v[202:205], v[48:51]
	v_mfma_f32_16x16x32_bf16 v[40:43], v[120:123], v[202:205], v[40:43]
	v_mfma_f32_16x16x32_bf16 v[32:35], v[108:111], v[210:213], v[32:35]
	v_mfma_f32_16x16x32_bf16 v[24:27], v[120:123], v[210:213], v[24:27]
	v_mfma_f32_16x16x32_bf16 v[16:19], v[108:111], v[218:221], v[16:19]
	v_mfma_f32_16x16x32_bf16 v[8:11], v[120:123], v[218:221], v[8:11]
	v_mfma_f32_16x16x32_bf16 v[52:55], v[144:147], v[160:163], v[52:55]
	v_mfma_f32_16x16x32_bf16 v[44:47], v[152:155], v[160:163], v[44:47]
	v_mfma_f32_16x16x32_bf16 v[36:39], v[144:147], v[194:197], v[36:39]
	v_mfma_f32_16x16x32_bf16 v[28:31], v[152:155], v[194:197], v[28:31]
	v_mfma_f32_16x16x32_bf16 v[20:23], v[144:147], v[206:209], v[20:23]
	v_mfma_f32_16x16x32_bf16 v[12:15], v[152:155], v[206:209], v[12:15]
	v_mfma_f32_16x16x32_bf16 v[4:7], v[144:147], v[214:217], v[4:7]
	v_mfma_f32_16x16x32_bf16 v[0:3], v[152:155], v[214:217], v[0:3]
	v_mfma_f32_16x16x32_bf16 v[52:55], v[148:151], v[190:193], v[52:55]
	v_mfma_f32_16x16x32_bf16 v[44:47], v[156:159], v[190:193], v[44:47]
	v_mfma_f32_16x16x32_bf16 v[36:39], v[148:151], v[202:205], v[36:39]
	v_mfma_f32_16x16x32_bf16 v[28:31], v[156:159], v[202:205], v[28:31]
	v_mfma_f32_16x16x32_bf16 v[20:23], v[148:151], v[210:213], v[20:23]
	v_mfma_f32_16x16x32_bf16 v[12:15], v[156:159], v[210:213], v[12:15]
	v_mfma_f32_16x16x32_bf16 v[4:7], v[148:151], v[218:221], v[4:7]
	v_mfma_f32_16x16x32_bf16 v[0:3], v[156:159], v[218:221], v[0:3]
	s_barrier
	s_add_i32 s48, 0, 0x18000
	s_add_i32 s49, 0, 0x1c000
	v_add_u32_e32 v120, s48, v200
	v_add_u32_e32 v156, s49, v200
	ds_read_b128 v[104:107], v120
	ds_read_b128 v[108:111], v120 offset:1024
	ds_read_b128 v[116:119], v120 offset:2048
	ds_read_b128 v[120:123], v120 offset:3072
	ds_read_b128 v[144:147], v156
	ds_read_b128 v[148:151], v156 offset:1024
	ds_read_b128 v[152:155], v156 offset:2048
	ds_read_b128 v[156:159], v156 offset:3072
	s_add_u32 s70, s70, 0x40000
	s_addc_u32 s71, s71, 0
	s_mov_b32 m0, s63
	v_lshl_add_u64 v[234:235], s[70:71], 0, v[168:169]
	ds_read_b128 v[160:163], v201 offset:32768
	ds_read_b128 v[190:193], v201 offset:33792
	ds_read_b128 v[194:197], v201 offset:34816
	ds_read_b128 v[202:205], v201 offset:35840
	ds_read_b128 v[206:209], v201 offset:36864
	ds_read_b128 v[210:213], v201 offset:37888
	ds_read_b128 v[214:217], v201 offset:38912
	ds_read_b128 v[218:221], v201 offset:39936
	global_load_lds_dwordx4 v[234:235], off
	v_lshl_add_u64 v[234:235], s[70:71], 0, v[166:167]
	s_mov_b32 m0, s72
	s_nop 0
	global_load_lds_dwordx4 v[234:235], off
	s_waitcnt vmcnt(8)
	s_waitcnt lgkmcnt(0)
	s_barrier
	s_waitcnt lgkmcnt(0)
	v_mfma_f32_16x16x32_bf16 v[140:143], v[104:107], v[160:163], v[140:143]
	v_mfma_f32_16x16x32_bf16 v[136:139], v[116:119], v[160:163], v[136:139]
	v_mfma_f32_16x16x32_bf16 v[124:127], v[104:107], v[194:197], v[124:127]
	v_mfma_f32_16x16x32_bf16 v[112:115], v[116:119], v[194:197], v[112:115]
	v_mfma_f32_16x16x32_bf16 v[96:99], v[104:107], v[206:209], v[96:99]
	v_mfma_f32_16x16x32_bf16 v[88:91], v[116:119], v[206:209], v[88:91]
	v_mfma_f32_16x16x32_bf16 v[80:83], v[104:107], v[214:217], v[80:83]
	v_mfma_f32_16x16x32_bf16 v[72:75], v[116:119], v[214:217], v[72:75]
	v_mfma_f32_16x16x32_bf16 v[140:143], v[108:111], v[190:193], v[140:143]
	v_mfma_f32_16x16x32_bf16 v[136:139], v[120:123], v[190:193], v[136:139]
	v_mfma_f32_16x16x32_bf16 v[124:127], v[108:111], v[202:205], v[124:127]
	v_mfma_f32_16x16x32_bf16 v[112:115], v[120:123], v[202:205], v[112:115]
	v_mfma_f32_16x16x32_bf16 v[96:99], v[108:111], v[210:213], v[96:99]
	v_mfma_f32_16x16x32_bf16 v[88:91], v[120:123], v[210:213], v[88:91]
	v_mfma_f32_16x16x32_bf16 v[80:83], v[108:111], v[218:221], v[80:83]
	v_mfma_f32_16x16x32_bf16 v[72:75], v[120:123], v[218:221], v[72:75]
	v_mfma_f32_16x16x32_bf16 v[132:135], v[144:147], v[160:163], v[132:135]
	v_mfma_f32_16x16x32_bf16 v[128:131], v[152:155], v[160:163], v[128:131]
	v_mfma_f32_16x16x32_bf16 v[100:103], v[144:147], v[194:197], v[100:103]
	v_mfma_f32_16x16x32_bf16 v[92:95], v[152:155], v[194:197], v[92:95]
	v_mfma_f32_16x16x32_bf16 v[84:87], v[144:147], v[206:209], v[84:87]
	v_mfma_f32_16x16x32_bf16 v[76:79], v[152:155], v[206:209], v[76:79]
	v_mfma_f32_16x16x32_bf16 v[68:71], v[144:147], v[214:217], v[68:71]
	v_mfma_f32_16x16x32_bf16 v[64:67], v[152:155], v[214:217], v[64:67]
	v_mfma_f32_16x16x32_bf16 v[132:135], v[148:151], v[190:193], v[132:135]
	v_mfma_f32_16x16x32_bf16 v[128:131], v[156:159], v[190:193], v[128:131]
	v_mfma_f32_16x16x32_bf16 v[100:103], v[148:151], v[202:205], v[100:103]
	v_mfma_f32_16x16x32_bf16 v[92:95], v[156:159], v[202:205], v[92:95]
	v_mfma_f32_16x16x32_bf16 v[84:87], v[148:151], v[210:213], v[84:87]
	v_mfma_f32_16x16x32_bf16 v[76:79], v[156:159], v[210:213], v[76:79]
	v_mfma_f32_16x16x32_bf16 v[68:71], v[148:151], v[218:221], v[68:71]
	v_mfma_f32_16x16x32_bf16 v[64:67], v[156:159], v[218:221], v[64:67]
	s_barrier
	s_add_i32 s48, s48, s60
	v_lshl_add_u64 v[174:175], v[174:175], 0, s[24:25]
	s_mov_b32 m0, s48
	ds_read_b128 v[160:163], v201 offset:49152
	ds_read_b128 v[190:193], v201 offset:50176
	ds_read_b128 v[194:197], v201 offset:51200
	ds_read_b128 v[202:205], v201 offset:52224
	ds_read_b128 v[206:209], v201 offset:53248
	ds_read_b128 v[210:213], v201 offset:54272
	ds_read_b128 v[214:217], v201 offset:55296
	ds_read_b128 v[218:221], v201 offset:56320
	global_load_lds_dwordx4 v[174:175], off
	s_add_i32 m0, s48, 0x2000
	s_add_u32 s68, s68, 0x40080
	v_lshl_add_u64 v[174:175], v[186:187], 0, s[24:25]
	s_addc_u32 s69, s69, 0
	s_add_i32 s48, s49, s60
	global_load_lds_dwordx4 v[174:175], off
	v_lshl_add_u64 v[174:175], s[68:69], 0, v[176:177]
	s_mov_b32 m0, s48
	s_nop 0
	global_load_lds_dwordx4 v[174:175], off
	v_lshl_add_u64 v[174:175], s[68:69], 0, v[164:165]
	s_add_i32 m0, s48, 0x2000
	s_nop 0
	global_load_lds_dwordx4 v[174:175], off
	v_lshl_add_u64 v[174:175], v[222:223], 0, s[24:25]
	s_mov_b32 m0, s77
	s_nop 0
	global_load_lds_dwordx4 v[174:175], off
	v_lshl_add_u64 v[174:175], v[224:225], 0, s[24:25]
	s_mov_b32 m0, s78
	s_nop 0
	global_load_lds_dwordx4 v[174:175], off
	s_waitcnt vmcnt(8)
	s_waitcnt lgkmcnt(0)
	s_barrier
	s_waitcnt lgkmcnt(0)
	v_mfma_f32_16x16x32_bf16 v[60:63], v[104:107], v[160:163], v[60:63]
	v_mfma_f32_16x16x32_bf16 v[56:59], v[116:119], v[160:163], v[56:59]
	v_mfma_f32_16x16x32_bf16 v[48:51], v[104:107], v[194:197], v[48:51]
	v_mfma_f32_16x16x32_bf16 v[40:43], v[116:119], v[194:197], v[40:43]
	v_mfma_f32_16x16x32_bf16 v[32:35], v[104:107], v[206:209], v[32:35]
	v_mfma_f32_16x16x32_bf16 v[24:27], v[116:119], v[206:209], v[24:27]
	v_mfma_f32_16x16x32_bf16 v[16:19], v[104:107], v[214:217], v[16:19]
	v_mfma_f32_16x16x32_bf16 v[8:11], v[116:119], v[214:217], v[8:11]
	v_mfma_f32_16x16x32_bf16 v[60:63], v[108:111], v[190:193], v[60:63]
	v_mfma_f32_16x16x32_bf16 v[56:59], v[120:123], v[190:193], v[56:59]
	v_mfma_f32_16x16x32_bf16 v[48:51], v[108:111], v[202:205], v[48:51]
	v_mfma_f32_16x16x32_bf16 v[40:43], v[120:123], v[202:205], v[40:43]
	v_mfma_f32_16x16x32_bf16 v[32:35], v[108:111], v[210:213], v[32:35]
	v_mfma_f32_16x16x32_bf16 v[24:27], v[120:123], v[210:213], v[24:27]
	v_mfma_f32_16x16x32_bf16 v[16:19], v[108:111], v[218:221], v[16:19]
	v_mfma_f32_16x16x32_bf16 v[8:11], v[120:123], v[218:221], v[8:11]
	v_mfma_f32_16x16x32_bf16 v[52:55], v[144:147], v[160:163], v[52:55]
	v_mfma_f32_16x16x32_bf16 v[44:47], v[152:155], v[160:163], v[44:47]
	v_mfma_f32_16x16x32_bf16 v[36:39], v[144:147], v[194:197], v[36:39]
	v_mfma_f32_16x16x32_bf16 v[28:31], v[152:155], v[194:197], v[28:31]
	v_mfma_f32_16x16x32_bf16 v[20:23], v[144:147], v[206:209], v[20:23]
	v_mfma_f32_16x16x32_bf16 v[12:15], v[152:155], v[206:209], v[12:15]
	v_mfma_f32_16x16x32_bf16 v[4:7], v[144:147], v[214:217], v[4:7]
	v_mfma_f32_16x16x32_bf16 v[0:3], v[152:155], v[214:217], v[0:3]
	v_mfma_f32_16x16x32_bf16 v[52:55], v[148:151], v[190:193], v[52:55]
	v_mfma_f32_16x16x32_bf16 v[44:47], v[156:159], v[190:193], v[44:47]
	v_mfma_f32_16x16x32_bf16 v[36:39], v[148:151], v[202:205], v[36:39]
	v_mfma_f32_16x16x32_bf16 v[28:31], v[156:159], v[202:205], v[28:31]
	v_mfma_f32_16x16x32_bf16 v[20:23], v[148:151], v[210:213], v[20:23]
	v_mfma_f32_16x16x32_bf16 v[12:15], v[156:159], v[210:213], v[12:15]
	v_mfma_f32_16x16x32_bf16 v[4:7], v[148:151], v[218:221], v[4:7]
	v_mfma_f32_16x16x32_bf16 v[0:3], v[156:159], v[218:221], v[0:3]
	s_barrier
	s_add_i32 s90, s90, 2
	s_add_u32 s86, s86, 0x100
	s_addc_u32 s87, s87, 0
	s_add_u32 s46, s46, 0x100
	s_addc_u32 s47, s47, 0
	s_cmp_gt_u32 s90, 13
	s_cbranch_scc0 .LBB0_698
	s_setprio 0
	s_and_b64 vcc, exec, s[34:35]
	s_cbranch_vccz .LBB0_701
	s_barrier

.LBB0_843:
	s_ashr_i32 s43, s42, 31
	s_lshl_b64 s[44:45], s[42:43], 19
	s_add_u32 s44, s3, s44
	s_addc_u32 s45, s22, s45
	s_and_b64 s[46:47], s[38:39], exec
	s_cselect_b32 s43, s45, s71
	s_cselect_b32 s80, s44, s70
	s_ashr_i32 s41, s40, 31
	s_lshl_b64 s[46:47], s[40:41], 19
	s_add_u32 s46, s58, s46
	s_addc_u32 s47, s59, s47
	s_and_b64 s[72:73], s[38:39], exec
	s_cselect_b32 s41, s47, s69
	s_cselect_b32 s81, s46, s68
	s_add_u32 s82, s68, 0x100
	s_addc_u32 s83, s69, 0
	s_add_u32 s68, s70, 0x40080
	v_mov_b32_e32 v0, 0
	s_addc_u32 s69, s71, 0
	s_mov_b32 s86, -2
	v_mov_b32_e32 v1, v0
	v_mov_b32_e32 v2, v0
	v_mov_b32_e32 v3, v0
	v_mov_b32_e32 v4, v0
	v_mov_b32_e32 v5, v0
	v_mov_b32_e32 v6, v0
	v_mov_b32_e32 v7, v0
	v_mov_b32_e32 v16, v0
	v_mov_b32_e32 v17, v0
	v_mov_b32_e32 v18, v0
	v_mov_b32_e32 v19, v0
	v_mov_b32_e32 v20, v0
	v_mov_b32_e32 v21, v0
	v_mov_b32_e32 v22, v0
	v_mov_b32_e32 v23, v0
	v_mov_b32_e32 v32, v0
	v_mov_b32_e32 v33, v0
	v_mov_b32_e32 v34, v0
	v_mov_b32_e32 v35, v0
	v_mov_b32_e32 v36, v0
	v_mov_b32_e32 v37, v0
	v_mov_b32_e32 v38, v0
	v_mov_b32_e32 v39, v0
	v_mov_b32_e32 v48, v0
	v_mov_b32_e32 v49, v0
	v_mov_b32_e32 v50, v0
	v_mov_b32_e32 v51, v0
	v_mov_b32_e32 v52, v0
	v_mov_b32_e32 v53, v0
	v_mov_b32_e32 v54, v0
	v_mov_b32_e32 v55, v0
	v_mov_b32_e32 v8, v0
	v_mov_b32_e32 v9, v0
	v_mov_b32_e32 v10, v0
	v_mov_b32_e32 v11, v0
	v_mov_b32_e32 v12, v0
	v_mov_b32_e32 v13, v0
	v_mov_b32_e32 v14, v0
	v_mov_b32_e32 v15, v0
	v_mov_b32_e32 v24, v0
	v_mov_b32_e32 v25, v0
	v_mov_b32_e32 v26, v0
	v_mov_b32_e32 v27, v0
	v_mov_b32_e32 v28, v0
	v_mov_b32_e32 v29, v0
	v_mov_b32_e32 v30, v0
	v_mov_b32_e32 v31, v0
	v_mov_b32_e32 v40, v0
	v_mov_b32_e32 v41, v0
	v_mov_b32_e32 v42, v0
	v_mov_b32_e32 v43, v0
	v_mov_b32_e32 v44, v0
	v_mov_b32_e32 v45, v0
	v_mov_b32_e32 v46, v0
	v_mov_b32_e32 v47, v0
	v_mov_b32_e32 v56, v0
	v_mov_b32_e32 v57, v0
	v_mov_b32_e32 v58, v0
	v_mov_b32_e32 v59, v0
	v_mov_b32_e32 v60, v0
	v_mov_b32_e32 v61, v0
	v_mov_b32_e32 v62, v0
	v_mov_b32_e32 v63, v0
	v_mov_b32_e32 v64, v0
	v_mov_b32_e32 v65, v0
	v_mov_b32_e32 v66, v0
	v_mov_b32_e32 v67, v0
	v_mov_b32_e32 v68, v0
	v_mov_b32_e32 v69, v0
	v_mov_b32_e32 v70, v0
	v_mov_b32_e32 v71, v0
	v_mov_b32_e32 v80, v0
	v_mov_b32_e32 v81, v0
	v_mov_b32_e32 v82, v0
	v_mov_b32_e32 v83, v0
	v_mov_b32_e32 v84, v0
	v_mov_b32_e32 v85, v0
	v_mov_b32_e32 v86, v0
	v_mov_b32_e32 v87, v0
	v_mov_b32_e32 v96, v0
	v_mov_b32_e32 v97, v0
	v_mov_b32_e32 v98, v0
	v_mov_b32_e32 v99, v0
	v_mov_b32_e32 v100, v0
	v_mov_b32_e32 v101, v0
	v_mov_b32_e32 v102, v0
	v_mov_b32_e32 v103, v0
	v_mov_b32_e32 v112, v0
	v_mov_b32_e32 v113, v0
	v_mov_b32_e32 v114, v0
	v_mov_b32_e32 v115, v0
	v_mov_b32_e32 v116, v0
	v_mov_b32_e32 v117, v0
	v_mov_b32_e32 v118, v0
	v_mov_b32_e32 v119, v0
	v_mov_b32_e32 v72, v0
	v_mov_b32_e32 v73, v0
	v_mov_b32_e32 v74, v0
	v_mov_b32_e32 v75, v0
	v_mov_b32_e32 v76, v0
	v_mov_b32_e32 v77, v0
	v_mov_b32_e32 v78, v0
	v_mov_b32_e32 v79, v0
	v_mov_b32_e32 v88, v0
	v_mov_b32_e32 v89, v0
	v_mov_b32_e32 v90, v0
	v_mov_b32_e32 v91, v0
	v_mov_b32_e32 v92, v0
	v_mov_b32_e32 v93, v0
	v_mov_b32_e32 v94, v0
	v_mov_b32_e32 v95, v0
	v_mov_b32_e32 v104, v0
	v_mov_b32_e32 v105, v0
	v_mov_b32_e32 v106, v0
	v_mov_b32_e32 v107, v0
	v_mov_b32_e32 v108, v0
	v_mov_b32_e32 v109, v0
	v_mov_b32_e32 v110, v0
	v_mov_b32_e32 v111, v0
	v_mov_b32_e32 v120, v0
	v_mov_b32_e32 v121, v0
	v_mov_b32_e32 v122, v0
	v_mov_b32_e32 v123, v0
	v_mov_b32_e32 v124, v0
	v_mov_b32_e32 v125, v0
	v_mov_b32_e32 v126, v0
	v_mov_b32_e32 v127, v0
	v_readfirstlane_b32 s48, v226
	s_nop 3
	s_bitcmp1_b32 s48, 8
	s_cbranch_scc0 .Lpr_844
	s_setprio 1
.Lpr_844:
.LBB0_844:
	s_add_u32 s48, s68, 0xfffc0080
	s_addc_u32 s49, s69, -1
	s_add_i32 s87, 0, 0x10000
	s_cmp_eq_u32 s86, 12
	s_cselect_b32 s73, s43, s49
	s_cselect_b32 s72, s80, s48
	v_add_u32_e32 v138, s87, v141
	s_cselect_b32 s71, s41, s83
	s_cselect_b32 s70, s81, s82
	s_add_i32 s48, 0, 0x14000
	ds_read_b128 v[144:147], v138
	ds_read_b128 v[148:151], v138 offset:1024
	ds_read_b128 v[152:155], v138 offset:2048
	ds_read_b128 v[156:159], v138 offset:3072
	v_add_u32_e32 v138, s48, v141
	ds_read_b128 v[160:163], v138
	ds_read_b128 v[164:167], v138 offset:1024
	ds_read_b128 v[168:171], v138 offset:2048
	ds_read_b128 v[172:175], v138 offset:3072
	v_lshl_add_u64 v[138:139], s[68:69], 0, v[136:137]
	s_add_i32 m0, s61, 0xc000
	ds_read_b128 v[190:193], v143
	ds_read_b128 v[194:197], v143 offset:1024
	ds_read_b128 v[198:201], v143 offset:2048
	ds_read_b128 v[202:205], v143 offset:3072
	ds_read_b128 v[206:209], v143 offset:4096
	ds_read_b128 v[210:213], v143 offset:5120
	ds_read_b128 v[214:217], v143 offset:6144
	ds_read_b128 v[218:221], v143 offset:7168
	global_load_lds_dwordx4 v[138:139], off
	v_lshl_add_u64 v[138:139], s[68:69], 0, v[134:135]
	s_add_i32 m0, s61, 0xe000
	s_nop 0
	global_load_lds_dwordx4 v[138:139], off
	s_waitcnt vmcnt(8)
	s_waitcnt lgkmcnt(0)
	s_barrier
	s_waitcnt lgkmcnt(0)
	v_mfma_f32_16x16x32_bf16 v[124:127], v[144:147], v[190:193], v[124:127]
	v_mfma_f32_16x16x32_bf16 v[120:123], v[152:155], v[190:193], v[120:123]
	v_mfma_f32_16x16x32_bf16 v[108:111], v[144:147], v[198:201], v[108:111]
	v_mfma_f32_16x16x32_bf16 v[104:107], v[152:155], v[198:201], v[104:107]
	v_mfma_f32_16x16x32_bf16 v[92:95], v[144:147], v[206:209], v[92:95]
	v_mfma_f32_16x16x32_bf16 v[88:91], v[152:155], v[206:209], v[88:91]
	v_mfma_f32_16x16x32_bf16 v[76:79], v[144:147], v[214:217], v[76:79]
	v_mfma_f32_16x16x32_bf16 v[72:75], v[152:155], v[214:217], v[72:75]
	v_mfma_f32_16x16x32_bf16 v[124:127], v[148:151], v[194:197], v[124:127]
	v_mfma_f32_16x16x32_bf16 v[120:123], v[156:159], v[194:197], v[120:123]
	v_mfma_f32_16x16x32_bf16 v[108:111], v[148:151], v[202:205], v[108:111]
	v_mfma_f32_16x16x32_bf16 v[104:107], v[156:159], v[202:205], v[104:107]
	v_mfma_f32_16x16x32_bf16 v[92:95], v[148:151], v[210:213], v[92:95]
	v_mfma_f32_16x16x32_bf16 v[88:91], v[156:159], v[210:213], v[88:91]
	v_mfma_f32_16x16x32_bf16 v[76:79], v[148:151], v[218:221], v[76:79]
	v_mfma_f32_16x16x32_bf16 v[72:75], v[156:159], v[218:221], v[72:75]
	v_mfma_f32_16x16x32_bf16 v[116:119], v[160:163], v[190:193], v[116:119]
	v_mfma_f32_16x16x32_bf16 v[112:115], v[168:171], v[190:193], v[112:115]
	v_mfma_f32_16x16x32_bf16 v[100:103], v[160:163], v[198:201], v[100:103]
	v_mfma_f32_16x16x32_bf16 v[96:99], v[168:171], v[198:201], v[96:99]
	v_mfma_f32_16x16x32_bf16 v[84:87], v[160:163], v[206:209], v[84:87]
	v_mfma_f32_16x16x32_bf16 v[80:83], v[168:171], v[206:209], v[80:83]
	v_mfma_f32_16x16x32_bf16 v[68:71], v[160:163], v[214:217], v[68:71]
	v_mfma_f32_16x16x32_bf16 v[64:67], v[168:171], v[214:217], v[64:67]
	v_mfma_f32_16x16x32_bf16 v[116:119], v[164:167], v[194:197], v[116:119]
	v_mfma_f32_16x16x32_bf16 v[112:115], v[172:175], v[194:197], v[112:115]
	v_mfma_f32_16x16x32_bf16 v[100:103], v[164:167], v[202:205], v[100:103]
	v_mfma_f32_16x16x32_bf16 v[96:99], v[172:175], v[202:205], v[96:99]
	v_mfma_f32_16x16x32_bf16 v[84:87], v[164:167], v[210:213], v[84:87]
	v_mfma_f32_16x16x32_bf16 v[80:83], v[172:175], v[210:213], v[80:83]
	v_mfma_f32_16x16x32_bf16 v[68:71], v[164:167], v[218:221], v[68:71]
	v_mfma_f32_16x16x32_bf16 v[64:67], v[172:175], v[218:221], v[64:67]
	s_barrier
	s_add_i32 s49, s87, s60
	v_lshl_add_u64 v[138:139], s[70:71], 0, v[176:177]
	s_mov_b32 m0, s49
	ds_read_b128 v[190:193], v143 offset:16384
	ds_read_b128 v[194:197], v143 offset:17408
	ds_read_b128 v[198:201], v143 offset:18432
	ds_read_b128 v[202:205], v143 offset:19456
	ds_read_b128 v[206:209], v143 offset:20480
	ds_read_b128 v[210:213], v143 offset:21504
	ds_read_b128 v[214:217], v143 offset:22528
	ds_read_b128 v[218:221], v143 offset:23552
	global_load_lds_dwordx4 v[138:139], off
	s_add_i32 m0, s49, 0x2000
	s_add_u32 s90, s70, 0x40000
	v_lshl_add_u64 v[186:187], s[70:71], 0, v[128:129]
	s_addc_u32 s91, s71, 0
	s_add_i32 s48, s48, s60
	global_load_lds_dwordx4 v[186:187], off
	v_lshl_add_u64 v[222:223], s[90:91], 0, v[176:177]
	s_mov_b32 m0, s48
	v_lshl_add_u64 v[224:225], s[72:73], 0, v[130:131]
	global_load_lds_dwordx4 v[222:223], off
	v_lshl_add_u64 v[222:223], s[90:91], 0, v[128:129]
	s_add_i32 m0, s48, 0x2000
	s_nop 0
	global_load_lds_dwordx4 v[222:223], off
	v_lshl_add_u64 v[222:223], s[72:73], 0, v[132:133]
	s_mov_b32 m0, s61
	s_nop 0
	global_load_lds_dwordx4 v[222:223], off
	s_mov_b32 m0, s62
	s_nop 0
	global_load_lds_dwordx4 v[224:225], off
	s_waitcnt vmcnt(8)
	s_waitcnt lgkmcnt(0)
	s_barrier
	s_waitcnt lgkmcnt(0)
	v_mfma_f32_16x16x32_bf16 v[60:63], v[144:147], v[190:193], v[60:63]
	v_mfma_f32_16x16x32_bf16 v[56:59], v[152:155], v[190:193], v[56:59]
	v_mfma_f32_16x16x32_bf16 v[44:47], v[144:147], v[198:201], v[44:47]
	v_mfma_f32_16x16x32_bf16 v[40:43], v[152:155], v[198:201], v[40:43]
	v_mfma_f32_16x16x32_bf16 v[28:31], v[144:147], v[206:209], v[28:31]
	v_mfma_f32_16x16x32_bf16 v[24:27], v[152:155], v[206:209], v[24:27]
	v_mfma_f32_16x16x32_bf16 v[12:15], v[144:147], v[214:217], v[12:15]
	v_mfma_f32_16x16x32_bf16 v[8:11], v[152:155], v[214:217], v[8:11]
	v_mfma_f32_16x16x32_bf16 v[60:63], v[148:151], v[194:197], v[60:63]
	v_mfma_f32_16x16x32_bf16 v[56:59], v[156:159], v[194:197], v[56:59]
	v_mfma_f32_16x16x32_bf16 v[44:47], v[148:151], v[202:205], v[44:47]
	v_mfma_f32_16x16x32_bf16 v[40:43], v[156:159], v[202:205], v[40:43]
	v_mfma_f32_16x16x32_bf16 v[28:31], v[148:151], v[210:213], v[28:31]
	v_mfma_f32_16x16x32_bf16 v[24:27], v[156:159], v[210:213], v[24:27]
	v_mfma_f32_16x16x32_bf16 v[12:15], v[148:151], v[218:221], v[12:15]
	v_mfma_f32_16x16x32_bf16 v[8:11], v[156:159], v[218:221], v[8:11]
	v_mfma_f32_16x16x32_bf16 v[52:55], v[160:163], v[190:193], v[52:55]
	v_mfma_f32_16x16x32_bf16 v[48:51], v[168:171], v[190:193], v[48:51]
	v_mfma_f32_16x16x32_bf16 v[36:39], v[160:163], v[198:201], v[36:39]
	v_mfma_f32_16x16x32_bf16 v[32:35], v[168:171], v[198:201], v[32:35]
	v_mfma_f32_16x16x32_bf16 v[20:23], v[160:163], v[206:209], v[20:23]
	v_mfma_f32_16x16x32_bf16 v[16:19], v[168:171], v[206:209], v[16:19]
	v_mfma_f32_16x16x32_bf16 v[4:7], v[160:163], v[214:217], v[4:7]
	v_mfma_f32_16x16x32_bf16 v[0:3], v[168:171], v[214:217], v[0:3]
	v_mfma_f32_16x16x32_bf16 v[52:55], v[164:167], v[194:197], v[52:55]
	v_mfma_f32_16x16x32_bf16 v[48:51], v[172:175], v[194:197], v[48:51]
	v_mfma_f32_16x16x32_bf16 v[36:39], v[164:167], v[202:205], v[36:39]
	v_mfma_f32_16x16x32_bf16 v[32:35], v[172:175], v[202:205], v[32:35]
	v_mfma_f32_16x16x32_bf16 v[20:23], v[164:167], v[210:213], v[20:23]
	v_mfma_f32_16x16x32_bf16 v[16:19], v[172:175], v[210:213], v[16:19]
	v_mfma_f32_16x16x32_bf16 v[4:7], v[164:167], v[218:221], v[4:7]
	v_mfma_f32_16x16x32_bf16 v[0:3], v[172:175], v[218:221], v[0:3]
	s_barrier
	s_add_i32 s48, 0, 0x18000
	s_add_i32 s49, 0, 0x1c000
	v_add_u32_e32 v156, s48, v141
	v_add_u32_e32 v172, s49, v141
	ds_read_b128 v[144:147], v156
	ds_read_b128 v[148:151], v156 offset:1024
	ds_read_b128 v[152:155], v156 offset:2048
	ds_read_b128 v[156:159], v156 offset:3072
	ds_read_b128 v[160:163], v172
	ds_read_b128 v[164:167], v172 offset:1024
	ds_read_b128 v[168:171], v172 offset:2048
	ds_read_b128 v[172:175], v172 offset:3072
	s_add_u32 s72, s72, 0x40000
	s_addc_u32 s73, s73, 0
	s_mov_b32 m0, s63
	v_lshl_add_u64 v[234:235], s[72:73], 0, v[132:133]
	ds_read_b128 v[190:193], v143 offset:32768
	ds_read_b128 v[194:197], v143 offset:33792
	ds_read_b128 v[198:201], v143 offset:34816
	ds_read_b128 v[202:205], v143 offset:35840
	ds_read_b128 v[206:209], v143 offset:36864
	ds_read_b128 v[210:213], v143 offset:37888
	ds_read_b128 v[214:217], v143 offset:38912
	ds_read_b128 v[218:221], v143 offset:39936
	global_load_lds_dwordx4 v[234:235], off
	v_lshl_add_u64 v[234:235], s[72:73], 0, v[130:131]
	s_mov_b32 m0, s74
	s_nop 0
	global_load_lds_dwordx4 v[234:235], off
	s_waitcnt vmcnt(8)
	s_waitcnt lgkmcnt(0)
	s_barrier
	s_waitcnt lgkmcnt(0)
	v_mfma_f32_16x16x32_bf16 v[124:127], v[144:147], v[190:193], v[124:127]
	v_mfma_f32_16x16x32_bf16 v[120:123], v[152:155], v[190:193], v[120:123]
	v_mfma_f32_16x16x32_bf16 v[108:111], v[144:147], v[198:201], v[108:111]
	v_mfma_f32_16x16x32_bf16 v[104:107], v[152:155], v[198:201], v[104:107]
	v_mfma_f32_16x16x32_bf16 v[92:95], v[144:147], v[206:209], v[92:95]
	v_mfma_f32_16x16x32_bf16 v[88:91], v[152:155], v[206:209], v[88:91]
	v_mfma_f32_16x16x32_bf16 v[76:79], v[144:147], v[214:217], v[76:79]
	v_mfma_f32_16x16x32_bf16 v[72:75], v[152:155], v[214:217], v[72:75]
	v_mfma_f32_16x16x32_bf16 v[124:127], v[148:151], v[194:197], v[124:127]
	v_mfma_f32_16x16x32_bf16 v[120:123], v[156:159], v[194:197], v[120:123]
	v_mfma_f32_16x16x32_bf16 v[108:111], v[148:151], v[202:205], v[108:111]
	v_mfma_f32_16x16x32_bf16 v[104:107], v[156:159], v[202:205], v[104:107]
	v_mfma_f32_16x16x32_bf16 v[92:95], v[148:151], v[210:213], v[92:95]
	v_mfma_f32_16x16x32_bf16 v[88:91], v[156:159], v[210:213], v[88:91]
	v_mfma_f32_16x16x32_bf16 v[76:79], v[148:151], v[218:221], v[76:79]
	v_mfma_f32_16x16x32_bf16 v[72:75], v[156:159], v[218:221], v[72:75]
	v_mfma_f32_16x16x32_bf16 v[116:119], v[160:163], v[190:193], v[116:119]
	v_mfma_f32_16x16x32_bf16 v[112:115], v[168:171], v[190:193], v[112:115]
	v_mfma_f32_16x16x32_bf16 v[100:103], v[160:163], v[198:201], v[100:103]
	v_mfma_f32_16x16x32_bf16 v[96:99], v[168:171], v[198:201], v[96:99]
	v_mfma_f32_16x16x32_bf16 v[84:87], v[160:163], v[206:209], v[84:87]
	v_mfma_f32_16x16x32_bf16 v[80:83], v[168:171], v[206:209], v[80:83]
	v_mfma_f32_16x16x32_bf16 v[68:71], v[160:163], v[214:217], v[68:71]
	v_mfma_f32_16x16x32_bf16 v[64:67], v[168:171], v[214:217], v[64:67]
	v_mfma_f32_16x16x32_bf16 v[116:119], v[164:167], v[194:197], v[116:119]
	v_mfma_f32_16x16x32_bf16 v[112:115], v[172:175], v[194:197], v[112:115]
	v_mfma_f32_16x16x32_bf16 v[100:103], v[164:167], v[202:205], v[100:103]
	v_mfma_f32_16x16x32_bf16 v[96:99], v[172:175], v[202:205], v[96:99]
	v_mfma_f32_16x16x32_bf16 v[84:87], v[164:167], v[210:213], v[84:87]
	v_mfma_f32_16x16x32_bf16 v[80:83], v[172:175], v[210:213], v[80:83]
	v_mfma_f32_16x16x32_bf16 v[68:71], v[164:167], v[218:221], v[68:71]
	v_mfma_f32_16x16x32_bf16 v[64:67], v[172:175], v[218:221], v[64:67]
	s_barrier
	s_add_i32 s48, s48, s60
	v_lshl_add_u64 v[138:139], v[138:139], 0, s[24:25]
	s_mov_b32 m0, s48
	ds_read_b128 v[190:193], v143 offset:49152
	ds_read_b128 v[194:197], v143 offset:50176
	ds_read_b128 v[198:201], v143 offset:51200
	ds_read_b128 v[202:205], v143 offset:52224
	ds_read_b128 v[206:209], v143 offset:53248
	ds_read_b128 v[210:213], v143 offset:54272
	ds_read_b128 v[214:217], v143 offset:55296
	ds_read_b128 v[218:221], v143 offset:56320
	global_load_lds_dwordx4 v[138:139], off
	s_add_i32 m0, s48, 0x2000
	s_add_u32 s70, s70, 0x40080
	v_lshl_add_u64 v[138:139], v[186:187], 0, s[24:25]
	s_addc_u32 s71, s71, 0
	s_add_i32 s48, s49, s60
	global_load_lds_dwordx4 v[138:139], off
	v_lshl_add_u64 v[138:139], s[70:71], 0, v[176:177]
	s_mov_b32 m0, s48
	s_nop 0
	global_load_lds_dwordx4 v[138:139], off
	v_lshl_add_u64 v[138:139], s[70:71], 0, v[128:129]
	s_add_i32 m0, s48, 0x2000
	s_nop 0
	global_load_lds_dwordx4 v[138:139], off
	v_lshl_add_u64 v[138:139], v[222:223], 0, s[24:25]
	s_mov_b32 m0, s75
	s_nop 0
	global_load_lds_dwordx4 v[138:139], off
	v_lshl_add_u64 v[138:139], v[224:225], 0, s[24:25]
	s_mov_b32 m0, s76
	s_nop 0
	global_load_lds_dwordx4 v[138:139], off
	s_waitcnt vmcnt(8)
	s_waitcnt lgkmcnt(0)
	s_barrier
	s_waitcnt lgkmcnt(0)
	v_mfma_f32_16x16x32_bf16 v[60:63], v[144:147], v[190:193], v[60:63]
	v_mfma_f32_16x16x32_bf16 v[56:59], v[152:155], v[190:193], v[56:59]
	v_mfma_f32_16x16x32_bf16 v[44:47], v[144:147], v[198:201], v[44:47]
	v_mfma_f32_16x16x32_bf16 v[40:43], v[152:155], v[198:201], v[40:43]
	v_mfma_f32_16x16x32_bf16 v[28:31], v[144:147], v[206:209], v[28:31]
	v_mfma_f32_16x16x32_bf16 v[24:27], v[152:155], v[206:209], v[24:27]
	v_mfma_f32_16x16x32_bf16 v[12:15], v[144:147], v[214:217], v[12:15]
	v_mfma_f32_16x16x32_bf16 v[8:11], v[152:155], v[214:217], v[8:11]
	v_mfma_f32_16x16x32_bf16 v[60:63], v[148:151], v[194:197], v[60:63]
	v_mfma_f32_16x16x32_bf16 v[56:59], v[156:159], v[194:197], v[56:59]
	v_mfma_f32_16x16x32_bf16 v[44:47], v[148:151], v[202:205], v[44:47]
	v_mfma_f32_16x16x32_bf16 v[40:43], v[156:159], v[202:205], v[40:43]
	v_mfma_f32_16x16x32_bf16 v[28:31], v[148:151], v[210:213], v[28:31]
	v_mfma_f32_16x16x32_bf16 v[24:27], v[156:159], v[210:213], v[24:27]
	v_mfma_f32_16x16x32_bf16 v[12:15], v[148:151], v[218:221], v[12:15]
	v_mfma_f32_16x16x32_bf16 v[8:11], v[156:159], v[218:221], v[8:11]
	v_mfma_f32_16x16x32_bf16 v[52:55], v[160:163], v[190:193], v[52:55]
	v_mfma_f32_16x16x32_bf16 v[48:51], v[168:171], v[190:193], v[48:51]
	v_mfma_f32_16x16x32_bf16 v[36:39], v[160:163], v[198:201], v[36:39]
	v_mfma_f32_16x16x32_bf16 v[32:35], v[168:171], v[198:201], v[32:35]
	v_mfma_f32_16x16x32_bf16 v[20:23], v[160:163], v[206:209], v[20:23]
	v_mfma_f32_16x16x32_bf16 v[16:19], v[168:171], v[206:209], v[16:19]
	v_mfma_f32_16x16x32_bf16 v[4:7], v[160:163], v[214:217], v[4:7]
	v_mfma_f32_16x16x32_bf16 v[0:3], v[168:171], v[214:217], v[0:3]
	v_mfma_f32_16x16x32_bf16 v[52:55], v[164:167], v[194:197], v[52:55]
	v_mfma_f32_16x16x32_bf16 v[48:51], v[172:175], v[194:197], v[48:51]
	v_mfma_f32_16x16x32_bf16 v[36:39], v[164:167], v[202:205], v[36:39]
	v_mfma_f32_16x16x32_bf16 v[32:35], v[172:175], v[202:205], v[32:35]
	v_mfma_f32_16x16x32_bf16 v[20:23], v[164:167], v[210:213], v[20:23]
	v_mfma_f32_16x16x32_bf16 v[16:19], v[172:175], v[210:213], v[16:19]
	v_mfma_f32_16x16x32_bf16 v[4:7], v[164:167], v[218:221], v[4:7]
	v_mfma_f32_16x16x32_bf16 v[0:3], v[172:175], v[218:221], v[0:3]
	s_barrier
	s_add_i32 s86, s86, 2
	s_add_u32 s82, s82, 0x100
	s_addc_u32 s83, s83, 0
	s_add_u32 s68, s68, 0x100
	s_addc_u32 s69, s69, 0
	s_cmp_gt_u32 s86, 13
	s_cbranch_scc0 .LBB0_844
	s_setprio 0
	s_and_b64 vcc, exec, s[36:37]
	s_cbranch_vccz .LBB0_847
	s_barrier

.LBB0_912:
	s_add_u32 s90, s68, 0x100
	v_mov_b32_e32 v0, 0
	s_addc_u32 s91, s69, 0
	s_mov_b32 vcc_lo, -2
	v_mov_b32_e32 v1, v0
	v_mov_b32_e32 v2, v0
	v_mov_b32_e32 v3, v0
	v_mov_b32_e32 v4, v0
	v_mov_b32_e32 v5, v0
	v_mov_b32_e32 v6, v0
	v_mov_b32_e32 v7, v0
	v_mov_b32_e32 v12, v0
	v_mov_b32_e32 v13, v0
	v_mov_b32_e32 v14, v0
	v_mov_b32_e32 v15, v0
	v_mov_b32_e32 v20, v0
	v_mov_b32_e32 v21, v0
	v_mov_b32_e32 v22, v0
	v_mov_b32_e32 v23, v0
	v_mov_b32_e32 v28, v0
	v_mov_b32_e32 v29, v0
	v_mov_b32_e32 v30, v0
	v_mov_b32_e32 v31, v0
	v_mov_b32_e32 v36, v0
	v_mov_b32_e32 v37, v0
	v_mov_b32_e32 v38, v0
	v_mov_b32_e32 v39, v0
	v_mov_b32_e32 v44, v0
	v_mov_b32_e32 v45, v0
	v_mov_b32_e32 v46, v0
	v_mov_b32_e32 v47, v0
	v_mov_b32_e32 v52, v0
	v_mov_b32_e32 v53, v0
	v_mov_b32_e32 v54, v0
	v_mov_b32_e32 v55, v0
	v_mov_b32_e32 v8, v0
	v_mov_b32_e32 v9, v0
	v_mov_b32_e32 v10, v0
	v_mov_b32_e32 v11, v0
	v_mov_b32_e32 v16, v0
	v_mov_b32_e32 v17, v0
	v_mov_b32_e32 v18, v0
	v_mov_b32_e32 v19, v0
	v_mov_b32_e32 v24, v0
	v_mov_b32_e32 v25, v0
	v_mov_b32_e32 v26, v0
	v_mov_b32_e32 v27, v0
	v_mov_b32_e32 v32, v0
	v_mov_b32_e32 v33, v0
	v_mov_b32_e32 v34, v0
	v_mov_b32_e32 v35, v0
	v_mov_b32_e32 v40, v0
	v_mov_b32_e32 v41, v0
	v_mov_b32_e32 v42, v0
	v_mov_b32_e32 v43, v0
	v_mov_b32_e32 v48, v0
	v_mov_b32_e32 v49, v0
	v_mov_b32_e32 v50, v0
	v_mov_b32_e32 v51, v0
	v_mov_b32_e32 v56, v0
	v_mov_b32_e32 v57, v0
	v_mov_b32_e32 v58, v0
	v_mov_b32_e32 v59, v0
	v_mov_b32_e32 v60, v0
	v_mov_b32_e32 v61, v0
	v_mov_b32_e32 v62, v0
	v_mov_b32_e32 v63, v0
	v_mov_b32_e32 v64, v0
	v_mov_b32_e32 v65, v0
	v_mov_b32_e32 v66, v0
	v_mov_b32_e32 v67, v0
	v_mov_b32_e32 v68, v0
	v_mov_b32_e32 v69, v0
	v_mov_b32_e32 v70, v0
	v_mov_b32_e32 v71, v0
	v_mov_b32_e32 v76, v0
	v_mov_b32_e32 v77, v0
	v_mov_b32_e32 v78, v0
	v_mov_b32_e32 v79, v0
	v_mov_b32_e32 v84, v0
	v_mov_b32_e32 v85, v0
	v_mov_b32_e32 v86, v0
	v_mov_b32_e32 v87, v0
	v_mov_b32_e32 v92, v0
	v_mov_b32_e32 v93, v0
	v_mov_b32_e32 v94, v0
	v_mov_b32_e32 v95, v0
	v_mov_b32_e32 v100, v0
	v_mov_b32_e32 v101, v0
	v_mov_b32_e32 v102, v0
	v_mov_b32_e32 v103, v0
	v_mov_b32_e32 v112, v0
	v_mov_b32_e32 v113, v0
	v_mov_b32_e32 v114, v0
	v_mov_b32_e32 v115, v0
	v_mov_b32_e32 v116, v0
	v_mov_b32_e32 v117, v0
	v_mov_b32_e32 v118, v0
	v_mov_b32_e32 v119, v0
	v_mov_b32_e32 v72, v0
	v_mov_b32_e32 v73, v0
	v_mov_b32_e32 v74, v0
	v_mov_b32_e32 v75, v0
	v_mov_b32_e32 v80, v0
	v_mov_b32_e32 v81, v0
	v_mov_b32_e32 v82, v0
	v_mov_b32_e32 v83, v0
	v_mov_b32_e32 v88, v0
	v_mov_b32_e32 v89, v0
	v_mov_b32_e32 v90, v0
	v_mov_b32_e32 v91, v0
	v_mov_b32_e32 v96, v0
	v_mov_b32_e32 v97, v0
	v_mov_b32_e32 v98, v0
	v_mov_b32_e32 v99, v0
	v_mov_b32_e32 v104, v0
	v_mov_b32_e32 v105, v0
	v_mov_b32_e32 v106, v0
	v_mov_b32_e32 v107, v0
	v_mov_b32_e32 v108, v0
	v_mov_b32_e32 v109, v0
	v_mov_b32_e32 v110, v0
	v_mov_b32_e32 v111, v0
	v_mov_b32_e32 v120, v0
	v_mov_b32_e32 v121, v0
	v_mov_b32_e32 v122, v0
	v_mov_b32_e32 v123, v0
	v_mov_b32_e32 v124, v0
	v_mov_b32_e32 v125, v0
	v_mov_b32_e32 v126, v0
	v_mov_b32_e32 v127, v0
	v_readfirstlane_b32 s68, v226
	s_nop 3
	s_bitcmp1_b32 s68, 8
	s_cbranch_scc0 .Lpr_913
	s_setprio 1
.Lpr_913:
.LBB0_913:
	s_add_u32 s68, s46, 0x100
	s_addc_u32 s69, s47, 0
	s_add_i32 s48, 0, 0x10000
	s_cmp_eq_u32 vcc_lo, 40
	s_cselect_b32 s73, s1, s69
	s_cselect_b32 s72, s0, s68
	s_cselect_b32 s71, s45, s91
	s_cselect_b32 s70, s44, s90
	s_add_i32 s49, 0, 0x14000
	v_add_u32_e32 v140, s48, v204
	v_add_u32_e32 v166, s49, v204
	ds_read_b128 v[128:131], v140
	ds_read_b128 v[132:135], v140 offset:1024
	ds_read_b128 v[136:139], v140 offset:2048
	ds_read_b128 v[140:143], v140 offset:3072
	ds_read_b128 v[144:147], v166
	ds_read_b128 v[148:151], v166 offset:1024
	ds_read_b128 v[162:165], v166 offset:2048
	ds_read_b128 v[166:169], v166 offset:3072
	v_lshl_add_u64 v[174:175], s[46:47], 0, v[160:161]
	s_add_i32 m0, s58, 0xc000
	ds_read_b128 v[170:173], v205
	ds_read_b128 v[190:193], v205 offset:1024
	ds_read_b128 v[194:197], v205 offset:2048
	ds_read_b128 v[198:201], v205 offset:3072
	ds_read_b128 v[206:209], v205 offset:4096
	ds_read_b128 v[210:213], v205 offset:5120
	ds_read_b128 v[214:217], v205 offset:6144
	ds_read_b128 v[218:221], v205 offset:7168
	global_load_lds_dwordx4 v[174:175], off
	v_lshl_add_u64 v[174:175], s[46:47], 0, v[158:159]
	s_add_i32 m0, s58, 0xe000
	s_nop 0
	global_load_lds_dwordx4 v[174:175], off
	s_waitcnt vmcnt(8)
	s_waitcnt lgkmcnt(0)
	s_barrier
	s_waitcnt lgkmcnt(0)
	v_mfma_f32_16x16x32_bf16 v[124:127], v[128:131], v[170:173], v[124:127]
	v_mfma_f32_16x16x32_bf16 v[120:123], v[136:139], v[170:173], v[120:123]
	v_mfma_f32_16x16x32_bf16 v[108:111], v[128:131], v[194:197], v[108:111]
	v_mfma_f32_16x16x32_bf16 v[104:107], v[136:139], v[194:197], v[104:107]
	v_mfma_f32_16x16x32_bf16 v[96:99], v[128:131], v[206:209], v[96:99]
	v_mfma_f32_16x16x32_bf16 v[88:91], v[136:139], v[206:209], v[88:91]
	v_mfma_f32_16x16x32_bf16 v[80:83], v[128:131], v[214:217], v[80:83]
	v_mfma_f32_16x16x32_bf16 v[72:75], v[136:139], v[214:217], v[72:75]
	v_mfma_f32_16x16x32_bf16 v[124:127], v[132:135], v[190:193], v[124:127]
	v_mfma_f32_16x16x32_bf16 v[120:123], v[140:143], v[190:193], v[120:123]
	v_mfma_f32_16x16x32_bf16 v[108:111], v[132:135], v[198:201], v[108:111]
	v_mfma_f32_16x16x32_bf16 v[104:107], v[140:143], v[198:201], v[104:107]
	v_mfma_f32_16x16x32_bf16 v[96:99], v[132:135], v[210:213], v[96:99]
	v_mfma_f32_16x16x32_bf16 v[88:91], v[140:143], v[210:213], v[88:91]
	v_mfma_f32_16x16x32_bf16 v[80:83], v[132:135], v[218:221], v[80:83]
	v_mfma_f32_16x16x32_bf16 v[72:75], v[140:143], v[218:221], v[72:75]
	v_mfma_f32_16x16x32_bf16 v[116:119], v[144:147], v[170:173], v[116:119]
	v_mfma_f32_16x16x32_bf16 v[112:115], v[162:165], v[170:173], v[112:115]
	v_mfma_f32_16x16x32_bf16 v[100:103], v[144:147], v[194:197], v[100:103]
	v_mfma_f32_16x16x32_bf16 v[92:95], v[162:165], v[194:197], v[92:95]
	v_mfma_f32_16x16x32_bf16 v[84:87], v[144:147], v[206:209], v[84:87]
	v_mfma_f32_16x16x32_bf16 v[76:79], v[162:165], v[206:209], v[76:79]
	v_mfma_f32_16x16x32_bf16 v[68:71], v[144:147], v[214:217], v[68:71]
	v_mfma_f32_16x16x32_bf16 v[64:67], v[162:165], v[214:217], v[64:67]
	v_mfma_f32_16x16x32_bf16 v[116:119], v[148:151], v[190:193], v[116:119]
	v_mfma_f32_16x16x32_bf16 v[112:115], v[166:169], v[190:193], v[112:115]
	v_mfma_f32_16x16x32_bf16 v[100:103], v[148:151], v[198:201], v[100:103]
	v_mfma_f32_16x16x32_bf16 v[92:95], v[166:169], v[198:201], v[92:95]
	v_mfma_f32_16x16x32_bf16 v[84:87], v[148:151], v[210:213], v[84:87]
	v_mfma_f32_16x16x32_bf16 v[76:79], v[166:169], v[210:213], v[76:79]
	v_mfma_f32_16x16x32_bf16 v[68:71], v[148:151], v[218:221], v[68:71]
	v_mfma_f32_16x16x32_bf16 v[64:67], v[166:169], v[218:221], v[64:67]
	s_barrier
	s_add_i32 s46, s48, s3
	v_lshl_add_u64 v[174:175], s[70:71], 0, v[176:177]
	s_mov_b32 m0, s46
	ds_read_b128 v[170:173], v205 offset:16384
	ds_read_b128 v[190:193], v205 offset:17408
	ds_read_b128 v[194:197], v205 offset:18432
	ds_read_b128 v[198:201], v205 offset:19456
	ds_read_b128 v[206:209], v205 offset:20480
	ds_read_b128 v[210:213], v205 offset:21504
	ds_read_b128 v[214:217], v205 offset:22528
	ds_read_b128 v[218:221], v205 offset:23552
	global_load_lds_dwordx4 v[174:175], off
	s_add_i32 m0, s46, 0x2000
	s_add_u32 s46, s70, 0xb0000
	v_lshl_add_u64 v[186:187], s[70:71], 0, v[152:153]
	s_addc_u32 s47, s71, 0
	s_add_i32 s48, s49, s3
	global_load_lds_dwordx4 v[186:187], off
	v_lshl_add_u64 v[222:223], s[46:47], 0, v[176:177]
	s_mov_b32 m0, s48
	v_lshl_add_u64 v[224:225], s[72:73], 0, v[154:155]
	global_load_lds_dwordx4 v[222:223], off
	v_lshl_add_u64 v[222:223], s[46:47], 0, v[152:153]
	s_add_i32 m0, s48, 0x2000
	s_nop 0
	global_load_lds_dwordx4 v[222:223], off
	v_lshl_add_u64 v[222:223], s[72:73], 0, v[156:157]
	s_mov_b32 m0, s58
	s_nop 0
	global_load_lds_dwordx4 v[222:223], off
	s_mov_b32 m0, s59
	s_nop 0
	global_load_lds_dwordx4 v[224:225], off
	s_waitcnt vmcnt(8)
	s_waitcnt lgkmcnt(0)
	s_barrier
	s_waitcnt lgkmcnt(0)
	v_mfma_f32_16x16x32_bf16 v[60:63], v[128:131], v[170:173], v[60:63]
	v_mfma_f32_16x16x32_bf16 v[56:59], v[136:139], v[170:173], v[56:59]
	v_mfma_f32_16x16x32_bf16 v[48:51], v[128:131], v[194:197], v[48:51]
	v_mfma_f32_16x16x32_bf16 v[40:43], v[136:139], v[194:197], v[40:43]
	v_mfma_f32_16x16x32_bf16 v[32:35], v[128:131], v[206:209], v[32:35]
	v_mfma_f32_16x16x32_bf16 v[24:27], v[136:139], v[206:209], v[24:27]
	v_mfma_f32_16x16x32_bf16 v[16:19], v[128:131], v[214:217], v[16:19]
	v_mfma_f32_16x16x32_bf16 v[8:11], v[136:139], v[214:217], v[8:11]
	v_mfma_f32_16x16x32_bf16 v[60:63], v[132:135], v[190:193], v[60:63]
	v_mfma_f32_16x16x32_bf16 v[56:59], v[140:143], v[190:193], v[56:59]
	v_mfma_f32_16x16x32_bf16 v[48:51], v[132:135], v[198:201], v[48:51]
	v_mfma_f32_16x16x32_bf16 v[40:43], v[140:143], v[198:201], v[40:43]
	v_mfma_f32_16x16x32_bf16 v[32:35], v[132:135], v[210:213], v[32:35]
	v_mfma_f32_16x16x32_bf16 v[24:27], v[140:143], v[210:213], v[24:27]
	v_mfma_f32_16x16x32_bf16 v[16:19], v[132:135], v[218:221], v[16:19]
	v_mfma_f32_16x16x32_bf16 v[8:11], v[140:143], v[218:221], v[8:11]
	v_mfma_f32_16x16x32_bf16 v[52:55], v[144:147], v[170:173], v[52:55]
	v_mfma_f32_16x16x32_bf16 v[44:47], v[162:165], v[170:173], v[44:47]
	v_mfma_f32_16x16x32_bf16 v[36:39], v[144:147], v[194:197], v[36:39]
	v_mfma_f32_16x16x32_bf16 v[28:31], v[162:165], v[194:197], v[28:31]
	v_mfma_f32_16x16x32_bf16 v[20:23], v[144:147], v[206:209], v[20:23]
	v_mfma_f32_16x16x32_bf16 v[12:15], v[162:165], v[206:209], v[12:15]
	v_mfma_f32_16x16x32_bf16 v[4:7], v[144:147], v[214:217], v[4:7]
	v_mfma_f32_16x16x32_bf16 v[0:3], v[162:165], v[214:217], v[0:3]
	v_mfma_f32_16x16x32_bf16 v[52:55], v[148:151], v[190:193], v[52:55]
	v_mfma_f32_16x16x32_bf16 v[44:47], v[166:169], v[190:193], v[44:47]
	v_mfma_f32_16x16x32_bf16 v[36:39], v[148:151], v[198:201], v[36:39]
	v_mfma_f32_16x16x32_bf16 v[28:31], v[166:169], v[198:201], v[28:31]
	v_mfma_f32_16x16x32_bf16 v[20:23], v[148:151], v[210:213], v[20:23]
	v_mfma_f32_16x16x32_bf16 v[12:15], v[166:169], v[210:213], v[12:15]
	v_mfma_f32_16x16x32_bf16 v[4:7], v[148:151], v[218:221], v[4:7]
	v_mfma_f32_16x16x32_bf16 v[0:3], v[166:169], v[218:221], v[0:3]
	s_barrier
	s_add_i32 s48, 0, 0x18000
	s_add_i32 s49, 0, 0x1c000
	v_add_u32_e32 v140, s48, v204
	v_add_u32_e32 v166, s49, v204
	ds_read_b128 v[128:131], v140
	ds_read_b128 v[132:135], v140 offset:1024
	ds_read_b128 v[136:139], v140 offset:2048
	ds_read_b128 v[140:143], v140 offset:3072
	ds_read_b128 v[144:147], v166
	ds_read_b128 v[148:151], v166 offset:1024
	ds_read_b128 v[162:165], v166 offset:2048
	ds_read_b128 v[166:169], v166 offset:3072
	s_add_u32 s46, s72, 0xb0000
	s_addc_u32 s47, s73, 0
	s_mov_b32 m0, s60
	v_lshl_add_u64 v[234:235], s[46:47], 0, v[156:157]
	ds_read_b128 v[170:173], v205 offset:32768
	ds_read_b128 v[190:193], v205 offset:33792
	ds_read_b128 v[194:197], v205 offset:34816
	ds_read_b128 v[198:201], v205 offset:35840
	ds_read_b128 v[206:209], v205 offset:36864
	ds_read_b128 v[210:213], v205 offset:37888
	ds_read_b128 v[214:217], v205 offset:38912
	ds_read_b128 v[218:221], v205 offset:39936
	global_load_lds_dwordx4 v[234:235], off
	v_lshl_add_u64 v[234:235], s[46:47], 0, v[154:155]
	s_mov_b32 m0, s61
	s_nop 0
	global_load_lds_dwordx4 v[234:235], off
	s_waitcnt vmcnt(8)
	s_waitcnt lgkmcnt(0)
	s_barrier
	s_waitcnt lgkmcnt(0)
	v_mfma_f32_16x16x32_bf16 v[124:127], v[128:131], v[170:173], v[124:127]
	v_mfma_f32_16x16x32_bf16 v[120:123], v[136:139], v[170:173], v[120:123]
	v_mfma_f32_16x16x32_bf16 v[108:111], v[128:131], v[194:197], v[108:111]
	v_mfma_f32_16x16x32_bf16 v[104:107], v[136:139], v[194:197], v[104:107]
	v_mfma_f32_16x16x32_bf16 v[96:99], v[128:131], v[206:209], v[96:99]
	v_mfma_f32_16x16x32_bf16 v[88:91], v[136:139], v[206:209], v[88:91]
	v_mfma_f32_16x16x32_bf16 v[80:83], v[128:131], v[214:217], v[80:83]
	v_mfma_f32_16x16x32_bf16 v[72:75], v[136:139], v[214:217], v[72:75]
	v_mfma_f32_16x16x32_bf16 v[124:127], v[132:135], v[190:193], v[124:127]
	v_mfma_f32_16x16x32_bf16 v[120:123], v[140:143], v[190:193], v[120:123]
	v_mfma_f32_16x16x32_bf16 v[108:111], v[132:135], v[198:201], v[108:111]
	v_mfma_f32_16x16x32_bf16 v[104:107], v[140:143], v[198:201], v[104:107]
	v_mfma_f32_16x16x32_bf16 v[96:99], v[132:135], v[210:213], v[96:99]
	v_mfma_f32_16x16x32_bf16 v[88:91], v[140:143], v[210:213], v[88:91]
	v_mfma_f32_16x16x32_bf16 v[80:83], v[132:135], v[218:221], v[80:83]
	v_mfma_f32_16x16x32_bf16 v[72:75], v[140:143], v[218:221], v[72:75]
	v_mfma_f32_16x16x32_bf16 v[116:119], v[144:147], v[170:173], v[116:119]
	v_mfma_f32_16x16x32_bf16 v[112:115], v[162:165], v[170:173], v[112:115]
	v_mfma_f32_16x16x32_bf16 v[100:103], v[144:147], v[194:197], v[100:103]
	v_mfma_f32_16x16x32_bf16 v[92:95], v[162:165], v[194:197], v[92:95]
	v_mfma_f32_16x16x32_bf16 v[84:87], v[144:147], v[206:209], v[84:87]
	v_mfma_f32_16x16x32_bf16 v[76:79], v[162:165], v[206:209], v[76:79]
	v_mfma_f32_16x16x32_bf16 v[68:71], v[144:147], v[214:217], v[68:71]
	v_mfma_f32_16x16x32_bf16 v[64:67], v[162:165], v[214:217], v[64:67]
	v_mfma_f32_16x16x32_bf16 v[116:119], v[148:151], v[190:193], v[116:119]
	v_mfma_f32_16x16x32_bf16 v[112:115], v[166:169], v[190:193], v[112:115]
	v_mfma_f32_16x16x32_bf16 v[100:103], v[148:151], v[198:201], v[100:103]
	v_mfma_f32_16x16x32_bf16 v[92:95], v[166:169], v[198:201], v[92:95]
	v_mfma_f32_16x16x32_bf16 v[84:87], v[148:151], v[210:213], v[84:87]
	v_mfma_f32_16x16x32_bf16 v[76:79], v[166:169], v[210:213], v[76:79]
	v_mfma_f32_16x16x32_bf16 v[68:71], v[148:151], v[218:221], v[68:71]
	v_mfma_f32_16x16x32_bf16 v[64:67], v[166:169], v[218:221], v[64:67]
	s_barrier
	s_add_i32 s46, s48, s3
	v_lshl_add_u64 v[174:175], v[174:175], 0, s[24:25]
	s_mov_b32 m0, s46
	ds_read_b128 v[170:173], v205 offset:49152
	ds_read_b128 v[190:193], v205 offset:50176
	ds_read_b128 v[194:197], v205 offset:51200
	ds_read_b128 v[198:201], v205 offset:52224
	ds_read_b128 v[206:209], v205 offset:53248
	ds_read_b128 v[210:213], v205 offset:54272
	ds_read_b128 v[214:217], v205 offset:55296
	ds_read_b128 v[218:221], v205 offset:56320
	global_load_lds_dwordx4 v[174:175], off
	s_add_i32 m0, s46, 0x2000
	s_add_u32 s46, s70, 0xb0080
	v_lshl_add_u64 v[174:175], v[186:187], 0, s[24:25]
	s_addc_u32 s47, s71, 0
	s_add_i32 s48, s49, s3
	global_load_lds_dwordx4 v[174:175], off
	v_lshl_add_u64 v[174:175], s[46:47], 0, v[176:177]
	s_mov_b32 m0, s48
	s_nop 0
	global_load_lds_dwordx4 v[174:175], off
	v_lshl_add_u64 v[174:175], s[46:47], 0, v[152:153]
	s_add_i32 m0, s48, 0x2000
	s_nop 0
	global_load_lds_dwordx4 v[174:175], off
	v_lshl_add_u64 v[174:175], v[222:223], 0, s[24:25]
	s_mov_b32 m0, s81
	s_nop 0
	global_load_lds_dwordx4 v[174:175], off
	v_lshl_add_u64 v[174:175], v[224:225], 0, s[24:25]
	s_mov_b32 m0, s82
	s_nop 0
	global_load_lds_dwordx4 v[174:175], off
	s_waitcnt vmcnt(8)
	s_waitcnt lgkmcnt(0)
	s_barrier
	s_waitcnt lgkmcnt(0)
	v_mfma_f32_16x16x32_bf16 v[60:63], v[128:131], v[170:173], v[60:63]
	v_mfma_f32_16x16x32_bf16 v[56:59], v[136:139], v[170:173], v[56:59]
	v_mfma_f32_16x16x32_bf16 v[48:51], v[128:131], v[194:197], v[48:51]
	v_mfma_f32_16x16x32_bf16 v[40:43], v[136:139], v[194:197], v[40:43]
	v_mfma_f32_16x16x32_bf16 v[32:35], v[128:131], v[206:209], v[32:35]
	v_mfma_f32_16x16x32_bf16 v[24:27], v[136:139], v[206:209], v[24:27]
	v_mfma_f32_16x16x32_bf16 v[16:19], v[128:131], v[214:217], v[16:19]
	v_mfma_f32_16x16x32_bf16 v[8:11], v[136:139], v[214:217], v[8:11]
	v_mfma_f32_16x16x32_bf16 v[60:63], v[132:135], v[190:193], v[60:63]
	v_mfma_f32_16x16x32_bf16 v[56:59], v[140:143], v[190:193], v[56:59]
	v_mfma_f32_16x16x32_bf16 v[48:51], v[132:135], v[198:201], v[48:51]
	v_mfma_f32_16x16x32_bf16 v[40:43], v[140:143], v[198:201], v[40:43]
	v_mfma_f32_16x16x32_bf16 v[32:35], v[132:135], v[210:213], v[32:35]
	v_mfma_f32_16x16x32_bf16 v[24:27], v[140:143], v[210:213], v[24:27]
	v_mfma_f32_16x16x32_bf16 v[16:19], v[132:135], v[218:221], v[16:19]
	v_mfma_f32_16x16x32_bf16 v[8:11], v[140:143], v[218:221], v[8:11]
	v_mfma_f32_16x16x32_bf16 v[52:55], v[144:147], v[170:173], v[52:55]
	v_mfma_f32_16x16x32_bf16 v[44:47], v[162:165], v[170:173], v[44:47]
	v_mfma_f32_16x16x32_bf16 v[36:39], v[144:147], v[194:197], v[36:39]
	v_mfma_f32_16x16x32_bf16 v[28:31], v[162:165], v[194:197], v[28:31]
	v_mfma_f32_16x16x32_bf16 v[20:23], v[144:147], v[206:209], v[20:23]
	v_mfma_f32_16x16x32_bf16 v[12:15], v[162:165], v[206:209], v[12:15]
	v_mfma_f32_16x16x32_bf16 v[4:7], v[144:147], v[214:217], v[4:7]
	v_mfma_f32_16x16x32_bf16 v[0:3], v[162:165], v[214:217], v[0:3]
	v_mfma_f32_16x16x32_bf16 v[52:55], v[148:151], v[190:193], v[52:55]
	v_mfma_f32_16x16x32_bf16 v[44:47], v[166:169], v[190:193], v[44:47]
	v_mfma_f32_16x16x32_bf16 v[36:39], v[148:151], v[198:201], v[36:39]
	v_mfma_f32_16x16x32_bf16 v[28:31], v[166:169], v[198:201], v[28:31]
	v_mfma_f32_16x16x32_bf16 v[20:23], v[148:151], v[210:213], v[20:23]
	v_mfma_f32_16x16x32_bf16 v[12:15], v[166:169], v[210:213], v[12:15]
	v_mfma_f32_16x16x32_bf16 v[4:7], v[148:151], v[218:221], v[4:7]
	v_mfma_f32_16x16x32_bf16 v[0:3], v[166:169], v[218:221], v[0:3]
	s_barrier
	s_add_i32 vcc_lo, vcc_lo, 2
	s_add_u32 s90, s90, 0x100
	s_addc_u32 s91, s91, 0
	s_cmp_gt_u32 vcc_lo, 41
	s_mov_b64 s[46:47], s[68:69]
	s_cbranch_scc0 .LBB0_913
	s_setprio 0
	s_and_b64 vcc, exec, s[42:43]
	s_cbranch_vccz .LBB0_916
	s_barrier

.Lpr_943:
.LBB0_943:
	s_add_u32 s44, s42, 0x100
	s_addc_u32 s45, s43, 0
	s_add_i32 s48, 0, 0x10000
	s_cmp_eq_u32 s86, 40
	s_cselect_b32 s69, s1, s45
	s_cselect_b32 s68, s0, s44
	s_cselect_b32 s47, s41, s83
	s_cselect_b32 s46, s40, s82
	s_add_i32 s49, 0, 0x14000
	v_add_u32_e32 v140, s48, v204
	v_add_u32_e32 v166, s49, v204
	ds_read_b128 v[128:131], v140
	ds_read_b128 v[132:135], v140 offset:1024
	ds_read_b128 v[136:139], v140 offset:2048
	ds_read_b128 v[140:143], v140 offset:3072
	ds_read_b128 v[144:147], v166
	ds_read_b128 v[148:151], v166 offset:1024
	ds_read_b128 v[162:165], v166 offset:2048
	ds_read_b128 v[166:169], v166 offset:3072
	v_lshl_add_u64 v[174:175], s[42:43], 0, v[160:161]
	s_add_i32 m0, s58, 0xc000
	ds_read_b128 v[170:173], v205
	ds_read_b128 v[190:193], v205 offset:1024
	ds_read_b128 v[194:197], v205 offset:2048
	ds_read_b128 v[198:201], v205 offset:3072
	ds_read_b128 v[206:209], v205 offset:4096
	ds_read_b128 v[210:213], v205 offset:5120
	ds_read_b128 v[214:217], v205 offset:6144
	ds_read_b128 v[218:221], v205 offset:7168
	global_load_lds_dwordx4 v[174:175], off
	v_lshl_add_u64 v[174:175], s[42:43], 0, v[158:159]
	s_add_i32 m0, s58, 0xe000
	s_nop 0
	global_load_lds_dwordx4 v[174:175], off
	s_waitcnt vmcnt(8)
	s_waitcnt lgkmcnt(0)
	s_barrier
	s_waitcnt lgkmcnt(0)
	v_mfma_f32_16x16x32_bf16 v[124:127], v[128:131], v[170:173], v[124:127]
	v_mfma_f32_16x16x32_bf16 v[120:123], v[136:139], v[170:173], v[120:123]
	v_mfma_f32_16x16x32_bf16 v[108:111], v[128:131], v[194:197], v[108:111]
	v_mfma_f32_16x16x32_bf16 v[104:107], v[136:139], v[194:197], v[104:107]
	v_mfma_f32_16x16x32_bf16 v[96:99], v[128:131], v[206:209], v[96:99]
	v_mfma_f32_16x16x32_bf16 v[88:91], v[136:139], v[206:209], v[88:91]
	v_mfma_f32_16x16x32_bf16 v[80:83], v[128:131], v[214:217], v[80:83]
	v_mfma_f32_16x16x32_bf16 v[72:75], v[136:139], v[214:217], v[72:75]
	v_mfma_f32_16x16x32_bf16 v[124:127], v[132:135], v[190:193], v[124:127]
	v_mfma_f32_16x16x32_bf16 v[120:123], v[140:143], v[190:193], v[120:123]
	v_mfma_f32_16x16x32_bf16 v[108:111], v[132:135], v[198:201], v[108:111]
	v_mfma_f32_16x16x32_bf16 v[104:107], v[140:143], v[198:201], v[104:107]
	v_mfma_f32_16x16x32_bf16 v[96:99], v[132:135], v[210:213], v[96:99]
	v_mfma_f32_16x16x32_bf16 v[88:91], v[140:143], v[210:213], v[88:91]
	v_mfma_f32_16x16x32_bf16 v[80:83], v[132:135], v[218:221], v[80:83]
	v_mfma_f32_16x16x32_bf16 v[72:75], v[140:143], v[218:221], v[72:75]
	v_mfma_f32_16x16x32_bf16 v[116:119], v[144:147], v[170:173], v[116:119]
	v_mfma_f32_16x16x32_bf16 v[112:115], v[162:165], v[170:173], v[112:115]
	v_mfma_f32_16x16x32_bf16 v[100:103], v[144:147], v[194:197], v[100:103]
	v_mfma_f32_16x16x32_bf16 v[92:95], v[162:165], v[194:197], v[92:95]
	v_mfma_f32_16x16x32_bf16 v[84:87], v[144:147], v[206:209], v[84:87]
	v_mfma_f32_16x16x32_bf16 v[76:79], v[162:165], v[206:209], v[76:79]
	v_mfma_f32_16x16x32_bf16 v[68:71], v[144:147], v[214:217], v[68:71]
	v_mfma_f32_16x16x32_bf16 v[64:67], v[162:165], v[214:217], v[64:67]
	v_mfma_f32_16x16x32_bf16 v[116:119], v[148:151], v[190:193], v[116:119]
	v_mfma_f32_16x16x32_bf16 v[112:115], v[166:169], v[190:193], v[112:115]
	v_mfma_f32_16x16x32_bf16 v[100:103], v[148:151], v[198:201], v[100:103]
	v_mfma_f32_16x16x32_bf16 v[92:95], v[166:169], v[198:201], v[92:95]
	v_mfma_f32_16x16x32_bf16 v[84:87], v[148:151], v[210:213], v[84:87]
	v_mfma_f32_16x16x32_bf16 v[76:79], v[166:169], v[210:213], v[76:79]
	v_mfma_f32_16x16x32_bf16 v[68:71], v[148:151], v[218:221], v[68:71]
	v_mfma_f32_16x16x32_bf16 v[64:67], v[166:169], v[218:221], v[64:67]
	s_barrier
	s_add_i32 s42, s48, s3
	v_lshl_add_u64 v[174:175], s[46:47], 0, v[176:177]
	s_mov_b32 m0, s42
	ds_read_b128 v[170:173], v205 offset:16384
	ds_read_b128 v[190:193], v205 offset:17408
	ds_read_b128 v[194:197], v205 offset:18432
	ds_read_b128 v[198:201], v205 offset:19456
	ds_read_b128 v[206:209], v205 offset:20480
	ds_read_b128 v[210:213], v205 offset:21504
	ds_read_b128 v[214:217], v205 offset:22528
	ds_read_b128 v[218:221], v205 offset:23552
	global_load_lds_dwordx4 v[174:175], off
	s_add_i32 m0, s42, 0x2000
	s_add_u32 s42, s46, 0xb0000
	v_lshl_add_u64 v[186:187], s[46:47], 0, v[152:153]
	s_addc_u32 s43, s47, 0
	s_add_i32 s48, s49, s3
	global_load_lds_dwordx4 v[186:187], off
	v_lshl_add_u64 v[222:223], s[42:43], 0, v[176:177]
	s_mov_b32 m0, s48
	v_lshl_add_u64 v[224:225], s[68:69], 0, v[154:155]
	global_load_lds_dwordx4 v[222:223], off
	v_lshl_add_u64 v[222:223], s[42:43], 0, v[152:153]
	s_add_i32 m0, s48, 0x2000
	s_nop 0
	global_load_lds_dwordx4 v[222:223], off
	v_lshl_add_u64 v[222:223], s[68:69], 0, v[156:157]
	s_mov_b32 m0, s58
	s_nop 0
	global_load_lds_dwordx4 v[222:223], off
	s_mov_b32 m0, s59
	s_nop 0
	global_load_lds_dwordx4 v[224:225], off
	s_waitcnt vmcnt(8)
	s_waitcnt lgkmcnt(0)
	s_barrier
	s_waitcnt lgkmcnt(0)
	v_mfma_f32_16x16x32_bf16 v[60:63], v[128:131], v[170:173], v[60:63]
	v_mfma_f32_16x16x32_bf16 v[56:59], v[136:139], v[170:173], v[56:59]
	v_mfma_f32_16x16x32_bf16 v[48:51], v[128:131], v[194:197], v[48:51]
	v_mfma_f32_16x16x32_bf16 v[40:43], v[136:139], v[194:197], v[40:43]
	v_mfma_f32_16x16x32_bf16 v[32:35], v[128:131], v[206:209], v[32:35]
	v_mfma_f32_16x16x32_bf16 v[24:27], v[136:139], v[206:209], v[24:27]
	v_mfma_f32_16x16x32_bf16 v[16:19], v[128:131], v[214:217], v[16:19]
	v_mfma_f32_16x16x32_bf16 v[8:11], v[136:139], v[214:217], v[8:11]
	v_mfma_f32_16x16x32_bf16 v[60:63], v[132:135], v[190:193], v[60:63]
	v_mfma_f32_16x16x32_bf16 v[56:59], v[140:143], v[190:193], v[56:59]
	v_mfma_f32_16x16x32_bf16 v[48:51], v[132:135], v[198:201], v[48:51]
	v_mfma_f32_16x16x32_bf16 v[40:43], v[140:143], v[198:201], v[40:43]
	v_mfma_f32_16x16x32_bf16 v[32:35], v[132:135], v[210:213], v[32:35]
	v_mfma_f32_16x16x32_bf16 v[24:27], v[140:143], v[210:213], v[24:27]
	v_mfma_f32_16x16x32_bf16 v[16:19], v[132:135], v[218:221], v[16:19]
	v_mfma_f32_16x16x32_bf16 v[8:11], v[140:143], v[218:221], v[8:11]
	v_mfma_f32_16x16x32_bf16 v[52:55], v[144:147], v[170:173], v[52:55]
	v_mfma_f32_16x16x32_bf16 v[44:47], v[162:165], v[170:173], v[44:47]
	v_mfma_f32_16x16x32_bf16 v[36:39], v[144:147], v[194:197], v[36:39]
	v_mfma_f32_16x16x32_bf16 v[28:31], v[162:165], v[194:197], v[28:31]
	v_mfma_f32_16x16x32_bf16 v[20:23], v[144:147], v[206:209], v[20:23]
	v_mfma_f32_16x16x32_bf16 v[12:15], v[162:165], v[206:209], v[12:15]
	v_mfma_f32_16x16x32_bf16 v[4:7], v[144:147], v[214:217], v[4:7]
	v_mfma_f32_16x16x32_bf16 v[0:3], v[162:165], v[214:217], v[0:3]
	v_mfma_f32_16x16x32_bf16 v[52:55], v[148:151], v[190:193], v[52:55]
	v_mfma_f32_16x16x32_bf16 v[44:47], v[166:169], v[190:193], v[44:47]
	v_mfma_f32_16x16x32_bf16 v[36:39], v[148:151], v[198:201], v[36:39]
	v_mfma_f32_16x16x32_bf16 v[28:31], v[166:169], v[198:201], v[28:31]
	v_mfma_f32_16x16x32_bf16 v[20:23], v[148:151], v[210:213], v[20:23]
	v_mfma_f32_16x16x32_bf16 v[12:15], v[166:169], v[210:213], v[12:15]
	v_mfma_f32_16x16x32_bf16 v[4:7], v[148:151], v[218:221], v[4:7]
	v_mfma_f32_16x16x32_bf16 v[0:3], v[166:169], v[218:221], v[0:3]
	s_barrier
	s_add_i32 s48, 0, 0x18000
	s_add_i32 s49, 0, 0x1c000
	v_add_u32_e32 v140, s48, v204
	v_add_u32_e32 v166, s49, v204
	ds_read_b128 v[128:131], v140
	ds_read_b128 v[132:135], v140 offset:1024
	ds_read_b128 v[136:139], v140 offset:2048
	ds_read_b128 v[140:143], v140 offset:3072
	ds_read_b128 v[144:147], v166
	ds_read_b128 v[148:151], v166 offset:1024
	ds_read_b128 v[162:165], v166 offset:2048
	ds_read_b128 v[166:169], v166 offset:3072
	s_add_u32 s42, s68, 0xb0000
	s_addc_u32 s43, s69, 0
	s_mov_b32 m0, s60
	v_lshl_add_u64 v[234:235], s[42:43], 0, v[156:157]
	ds_read_b128 v[170:173], v205 offset:32768
	ds_read_b128 v[190:193], v205 offset:33792
	ds_read_b128 v[194:197], v205 offset:34816
	ds_read_b128 v[198:201], v205 offset:35840
	ds_read_b128 v[206:209], v205 offset:36864
	ds_read_b128 v[210:213], v205 offset:37888
	ds_read_b128 v[214:217], v205 offset:38912
	ds_read_b128 v[218:221], v205 offset:39936
	global_load_lds_dwordx4 v[234:235], off
	v_lshl_add_u64 v[234:235], s[42:43], 0, v[154:155]
	s_mov_b32 m0, s61
	s_nop 0
	global_load_lds_dwordx4 v[234:235], off
	s_waitcnt vmcnt(8)
	s_waitcnt lgkmcnt(0)
	s_barrier
	s_waitcnt lgkmcnt(0)
	v_mfma_f32_16x16x32_bf16 v[124:127], v[128:131], v[170:173], v[124:127]
	v_mfma_f32_16x16x32_bf16 v[120:123], v[136:139], v[170:173], v[120:123]
	v_mfma_f32_16x16x32_bf16 v[108:111], v[128:131], v[194:197], v[108:111]
	v_mfma_f32_16x16x32_bf16 v[104:107], v[136:139], v[194:197], v[104:107]
	v_mfma_f32_16x16x32_bf16 v[96:99], v[128:131], v[206:209], v[96:99]
	v_mfma_f32_16x16x32_bf16 v[88:91], v[136:139], v[206:209], v[88:91]
	v_mfma_f32_16x16x32_bf16 v[80:83], v[128:131], v[214:217], v[80:83]
	v_mfma_f32_16x16x32_bf16 v[72:75], v[136:139], v[214:217], v[72:75]
	v_mfma_f32_16x16x32_bf16 v[124:127], v[132:135], v[190:193], v[124:127]
	v_mfma_f32_16x16x32_bf16 v[120:123], v[140:143], v[190:193], v[120:123]
	v_mfma_f32_16x16x32_bf16 v[108:111], v[132:135], v[198:201], v[108:111]
	v_mfma_f32_16x16x32_bf16 v[104:107], v[140:143], v[198:201], v[104:107]
	v_mfma_f32_16x16x32_bf16 v[96:99], v[132:135], v[210:213], v[96:99]
	v_mfma_f32_16x16x32_bf16 v[88:91], v[140:143], v[210:213], v[88:91]
	v_mfma_f32_16x16x32_bf16 v[80:83], v[132:135], v[218:221], v[80:83]
	v_mfma_f32_16x16x32_bf16 v[72:75], v[140:143], v[218:221], v[72:75]
	v_mfma_f32_16x16x32_bf16 v[116:119], v[144:147], v[170:173], v[116:119]
	v_mfma_f32_16x16x32_bf16 v[112:115], v[162:165], v[170:173], v[112:115]
	v_mfma_f32_16x16x32_bf16 v[100:103], v[144:147], v[194:197], v[100:103]
	v_mfma_f32_16x16x32_bf16 v[92:95], v[162:165], v[194:197], v[92:95]
	v_mfma_f32_16x16x32_bf16 v[84:87], v[144:147], v[206:209], v[84:87]
	v_mfma_f32_16x16x32_bf16 v[76:79], v[162:165], v[206:209], v[76:79]
	v_mfma_f32_16x16x32_bf16 v[68:71], v[144:147], v[214:217], v[68:71]
	v_mfma_f32_16x16x32_bf16 v[64:67], v[162:165], v[214:217], v[64:67]
	v_mfma_f32_16x16x32_bf16 v[116:119], v[148:151], v[190:193], v[116:119]
	v_mfma_f32_16x16x32_bf16 v[112:115], v[166:169], v[190:193], v[112:115]
	v_mfma_f32_16x16x32_bf16 v[100:103], v[148:151], v[198:201], v[100:103]
	v_mfma_f32_16x16x32_bf16 v[92:95], v[166:169], v[198:201], v[92:95]
	v_mfma_f32_16x16x32_bf16 v[84:87], v[148:151], v[210:213], v[84:87]
	v_mfma_f32_16x16x32_bf16 v[76:79], v[166:169], v[210:213], v[76:79]
	v_mfma_f32_16x16x32_bf16 v[68:71], v[148:151], v[218:221], v[68:71]
	v_mfma_f32_16x16x32_bf16 v[64:67], v[166:169], v[218:221], v[64:67]
	s_barrier
	s_add_i32 s42, s48, s3
	v_lshl_add_u64 v[174:175], v[174:175], 0, s[24:25]
	s_mov_b32 m0, s42
	ds_read_b128 v[170:173], v205 offset:49152
	ds_read_b128 v[190:193], v205 offset:50176
	ds_read_b128 v[194:197], v205 offset:51200
	ds_read_b128 v[198:201], v205 offset:52224
	ds_read_b128 v[206:209], v205 offset:53248
	ds_read_b128 v[210:213], v205 offset:54272
	ds_read_b128 v[214:217], v205 offset:55296
	ds_read_b128 v[218:221], v205 offset:56320
	global_load_lds_dwordx4 v[174:175], off
	s_add_i32 m0, s42, 0x2000
	s_add_u32 s42, s46, 0xb0080
	v_lshl_add_u64 v[174:175], v[186:187], 0, s[24:25]
	s_addc_u32 s43, s47, 0
	s_add_i32 s46, s49, s3
	global_load_lds_dwordx4 v[174:175], off
	v_lshl_add_u64 v[174:175], s[42:43], 0, v[176:177]
	s_mov_b32 m0, s46
	s_nop 0
	global_load_lds_dwordx4 v[174:175], off
	v_lshl_add_u64 v[174:175], s[42:43], 0, v[152:153]
	s_add_i32 m0, s46, 0x2000
	s_nop 0
	global_load_lds_dwordx4 v[174:175], off
	v_lshl_add_u64 v[174:175], v[222:223], 0, s[24:25]
	s_mov_b32 m0, s62
	s_nop 0
	global_load_lds_dwordx4 v[174:175], off
	v_lshl_add_u64 v[174:175], v[224:225], 0, s[24:25]
	s_mov_b32 m0, s63
	s_nop 0
	global_load_lds_dwordx4 v[174:175], off
	s_waitcnt vmcnt(8)
	s_waitcnt lgkmcnt(0)
	s_barrier
	s_waitcnt lgkmcnt(0)
	v_mfma_f32_16x16x32_bf16 v[60:63], v[128:131], v[170:173], v[60:63]
	v_mfma_f32_16x16x32_bf16 v[56:59], v[136:139], v[170:173], v[56:59]
	v_mfma_f32_16x16x32_bf16 v[48:51], v[128:131], v[194:197], v[48:51]
	v_mfma_f32_16x16x32_bf16 v[40:43], v[136:139], v[194:197], v[40:43]
	v_mfma_f32_16x16x32_bf16 v[32:35], v[128:131], v[206:209], v[32:35]
	v_mfma_f32_16x16x32_bf16 v[24:27], v[136:139], v[206:209], v[24:27]
	v_mfma_f32_16x16x32_bf16 v[16:19], v[128:131], v[214:217], v[16:19]
	v_mfma_f32_16x16x32_bf16 v[8:11], v[136:139], v[214:217], v[8:11]
	v_mfma_f32_16x16x32_bf16 v[60:63], v[132:135], v[190:193], v[60:63]
	v_mfma_f32_16x16x32_bf16 v[56:59], v[140:143], v[190:193], v[56:59]
	v_mfma_f32_16x16x32_bf16 v[48:51], v[132:135], v[198:201], v[48:51]
	v_mfma_f32_16x16x32_bf16 v[40:43], v[140:143], v[198:201], v[40:43]
	v_mfma_f32_16x16x32_bf16 v[32:35], v[132:135], v[210:213], v[32:35]
	v_mfma_f32_16x16x32_bf16 v[24:27], v[140:143], v[210:213], v[24:27]
	v_mfma_f32_16x16x32_bf16 v[16:19], v[132:135], v[218:221], v[16:19]
	v_mfma_f32_16x16x32_bf16 v[8:11], v[140:143], v[218:221], v[8:11]
	v_mfma_f32_16x16x32_bf16 v[52:55], v[144:147], v[170:173], v[52:55]
	v_mfma_f32_16x16x32_bf16 v[44:47], v[162:165], v[170:173], v[44:47]
	v_mfma_f32_16x16x32_bf16 v[36:39], v[144:147], v[194:197], v[36:39]
	v_mfma_f32_16x16x32_bf16 v[28:31], v[162:165], v[194:197], v[28:31]
	v_mfma_f32_16x16x32_bf16 v[20:23], v[144:147], v[206:209], v[20:23]
	v_mfma_f32_16x16x32_bf16 v[12:15], v[162:165], v[206:209], v[12:15]
	v_mfma_f32_16x16x32_bf16 v[4:7], v[144:147], v[214:217], v[4:7]
	v_mfma_f32_16x16x32_bf16 v[0:3], v[162:165], v[214:217], v[0:3]
	v_mfma_f32_16x16x32_bf16 v[52:55], v[148:151], v[190:193], v[52:55]
	v_mfma_f32_16x16x32_bf16 v[44:47], v[166:169], v[190:193], v[44:47]
	v_mfma_f32_16x16x32_bf16 v[36:39], v[148:151], v[198:201], v[36:39]
	v_mfma_f32_16x16x32_bf16 v[28:31], v[166:169], v[198:201], v[28:31]
	v_mfma_f32_16x16x32_bf16 v[20:23], v[148:151], v[210:213], v[20:23]
	v_mfma_f32_16x16x32_bf16 v[12:15], v[166:169], v[210:213], v[12:15]
	v_mfma_f32_16x16x32_bf16 v[4:7], v[148:151], v[218:221], v[4:7]
	v_mfma_f32_16x16x32_bf16 v[0:3], v[166:169], v[218:221], v[0:3]
	s_barrier
	s_add_i32 s86, s86, 2
	s_add_u32 s82, s82, 0x100
	s_addc_u32 s83, s83, 0
	s_cmp_gt_u32 s86, 41
	s_mov_b64 s[42:43], s[44:45]
	s_cbranch_scc0 .LBB0_943
	s_setprio 0
	s_and_b64 vcc, exec, s[38:39]
	s_cbranch_vccz .LBB0_946
	s_barrier
